# main-loop LDS-DMA landing waits relaxed: vmcnt(10) before the pre-cluster barriers of phases 8,1,2,4,5,6 instead of vmcnt(6) twice per iteration (loads of the last 5 phases may stay in flight)
# baseline (speedup 1.0000x reference)
.LBB0_403:
	s_add_u32 s14, s4, 0x100
	s_addc_u32 s15, s5, 0
	s_add_i32 s38, 0, 0x10000
	v_add_u32_e32 v12, s38, v193
	ds_read_b128 v[0:3], v12
	ds_read_b128 v[8:11], v12 offset:2048
	ds_read_b128 v[4:7], v12 offset:1024
	ds_read_b128 v[12:15], v12 offset:3072
	s_cmp_eq_u32 s37, 12
	s_cselect_b32 s19, s9, s15
	s_cselect_b32 s18, s8, s14
	s_cselect_b32 s17, s11, s36
	s_cselect_b32 s16, s10, s7
	v_lshl_add_u64 v[190:191], s[4:5], 0, v[186:187]
	s_add_i32 m0, s23, 0xc000
	ds_read_b128 v[16:19], v206
	ds_read_b128 v[24:27], v206 offset:2048
	ds_read_b128 v[162:165], v206 offset:4096
	ds_read_b128 v[170:173], v206 offset:6144
	ds_read_b128 v[20:23], v206 offset:1024
	ds_read_b128 v[28:31], v206 offset:3072
	ds_read_b128 v[166:169], v206 offset:5120
	ds_read_b128 v[174:177], v206 offset:7168
	global_load_lds_dwordx4 v[190:191], off
	v_lshl_add_u64 v[190:191], s[4:5], 0, v[188:189]
	s_add_i32 m0, s23, 0xe000
	s_nop 0
	global_load_lds_dwordx4 v[190:191], off
	s_waitcnt lgkmcnt(8)
	s_waitcnt vmcnt(10)
	s_barrier
	s_waitcnt lgkmcnt(7)
	s_setprio 1
	v_mfma_f32_16x16x32_f16 v[158:161], v[0:3], v[16:19], v[158:161]
	v_mfma_f32_16x16x32_f16 v[142:145], v[8:11], v[16:19], v[142:145]
	s_waitcnt lgkmcnt(6)
	v_mfma_f32_16x16x32_f16 v[150:153], v[0:3], v[24:27], v[150:153]
	v_mfma_f32_16x16x32_f16 v[134:137], v[8:11], v[24:27], v[134:137]
	s_waitcnt lgkmcnt(5)
	v_mfma_f32_16x16x32_f16 v[154:157], v[0:3], v[162:165], v[154:157]
	v_mfma_f32_16x16x32_f16 v[138:141], v[8:11], v[162:165], v[138:141]
	s_waitcnt lgkmcnt(4)
	v_mfma_f32_16x16x32_f16 v[146:149], v[0:3], v[170:173], v[146:149]
	v_mfma_f32_16x16x32_f16 v[130:133], v[8:11], v[170:173], v[130:133]
	s_waitcnt lgkmcnt(3)
	v_mfma_f32_16x16x32_f16 v[158:161], v[4:7], v[20:23], v[158:161]
	v_mfma_f32_16x16x32_f16 v[142:145], v[12:15], v[20:23], v[142:145]
	s_waitcnt lgkmcnt(2)
	v_mfma_f32_16x16x32_f16 v[150:153], v[4:7], v[28:31], v[150:153]
	v_mfma_f32_16x16x32_f16 v[134:137], v[12:15], v[28:31], v[134:137]
	s_waitcnt lgkmcnt(1)
	v_mfma_f32_16x16x32_f16 v[154:157], v[4:7], v[166:169], v[154:157]
	v_mfma_f32_16x16x32_f16 v[138:141], v[12:15], v[166:169], v[138:141]
	s_waitcnt lgkmcnt(0)
	v_mfma_f32_16x16x32_f16 v[146:149], v[4:7], v[174:177], v[146:149]
	v_mfma_f32_16x16x32_f16 v[130:133], v[12:15], v[174:177], v[130:133]
	s_setprio 0
	s_barrier
	s_add_i32 s39, 0, 0x14000
	s_add_i32 s4, s38, s22
	v_add_u32_e32 v32, s39, v193
	v_lshl_add_u64 v[190:191], s[16:17], 0, v[178:179]
	s_mov_b32 m0, s4
	ds_read_b128 v[208:211], v32
	ds_read_b128 v[216:219], v32 offset:2048
	ds_read_b128 v[212:215], v32 offset:1024
	ds_read_b128 v[230:233], v32 offset:3072
	global_load_lds_dwordx4 v[190:191], off
	v_lshl_add_u64 v[238:239], s[16:17], 0, v[180:181]
	s_add_i32 m0, s4, 0x2000
	s_nop 0
	global_load_lds_dwordx4 v[238:239], off
	s_waitcnt vmcnt(10)
	s_barrier
	s_waitcnt lgkmcnt(2)
	s_setprio 1
	v_mfma_f32_16x16x32_f16 v[94:97], v[208:211], v[16:19], v[94:97]
	v_mfma_f32_16x16x32_f16 v[16:19], v[216:219], v[16:19], v[78:81]
	s_waitcnt lgkmcnt(0)
	v_mfma_f32_16x16x32_f16 v[94:97], v[212:215], v[20:23], v[94:97]
	v_mfma_f32_16x16x32_f16 v[16:19], v[230:233], v[20:23], v[16:19]
	v_mfma_f32_16x16x32_f16 v[20:23], v[208:211], v[24:27], v[86:89]
	v_mfma_f32_16x16x32_f16 v[24:27], v[216:219], v[24:27], v[70:73]
	v_mfma_f32_16x16x32_f16 v[70:73], v[216:219], v[162:165], v[74:77]
	v_mfma_f32_16x16x32_f16 v[74:77], v[230:233], v[166:169], v[70:73]
	v_mfma_f32_16x16x32_f16 v[70:73], v[208:211], v[170:173], v[82:85]
	v_mfma_f32_16x16x32_f16 v[66:69], v[216:219], v[170:173], v[66:69]
	v_mfma_f32_16x16x32_f16 v[20:23], v[212:215], v[28:31], v[20:23]
	v_mfma_f32_16x16x32_f16 v[24:27], v[230:233], v[28:31], v[24:27]
	v_mfma_f32_16x16x32_f16 v[28:31], v[208:211], v[162:165], v[90:93]
	v_mfma_f32_16x16x32_f16 v[82:85], v[212:215], v[174:177], v[70:73]
	v_mfma_f32_16x16x32_f16 v[66:69], v[230:233], v[174:177], v[66:69]
	v_mfma_f32_16x16x32_f16 v[28:31], v[212:215], v[166:169], v[28:31]
	s_setprio 0
	s_mov_b32 m0, s23
	v_lshl_add_u64 v[240:241], s[18:19], 0, v[178:179]
	s_barrier
	ds_read_b128 v[70:73], v206 offset:16384
	ds_read_b128 v[86:89], v206 offset:18432
	ds_read_b128 v[162:165], v206 offset:20480
	ds_read_b128 v[170:173], v206 offset:22528
	ds_read_b128 v[78:81], v206 offset:17408
	ds_read_b128 v[90:93], v206 offset:19456
	ds_read_b128 v[166:169], v206 offset:21504
	ds_read_b128 v[174:177], v206 offset:23552
	global_load_lds_dwordx4 v[240:241], off
	v_lshl_add_u64 v[242:243], s[18:19], 0, v[180:181]
	s_mov_b32 m0, s24
	s_nop 0
	global_load_lds_dwordx4 v[242:243], off
	s_barrier
	s_waitcnt lgkmcnt(7)
	s_setprio 1
	v_mfma_f32_16x16x32_f16 v[126:129], v[0:3], v[70:73], v[126:129]
	v_mfma_f32_16x16x32_f16 v[110:113], v[8:11], v[70:73], v[110:113]
	s_waitcnt lgkmcnt(6)
	v_mfma_f32_16x16x32_f16 v[118:121], v[0:3], v[86:89], v[118:121]
	v_mfma_f32_16x16x32_f16 v[102:105], v[8:11], v[86:89], v[102:105]
	s_waitcnt lgkmcnt(5)
	v_mfma_f32_16x16x32_f16 v[122:125], v[0:3], v[162:165], v[122:125]
	v_mfma_f32_16x16x32_f16 v[106:109], v[8:11], v[162:165], v[106:109]
	s_waitcnt lgkmcnt(3)
	v_mfma_f32_16x16x32_f16 v[0:3], v[0:3], v[170:173], v[114:117]
	v_mfma_f32_16x16x32_f16 v[126:129], v[4:7], v[78:81], v[126:129]
	s_waitcnt lgkmcnt(2)
	v_mfma_f32_16x16x32_f16 v[110:113], v[12:15], v[78:81], v[110:113]
	v_mfma_f32_16x16x32_f16 v[118:121], v[4:7], v[90:93], v[118:121]
	s_waitcnt lgkmcnt(1)
	v_mfma_f32_16x16x32_f16 v[102:105], v[12:15], v[90:93], v[102:105]
	v_mfma_f32_16x16x32_f16 v[122:125], v[4:7], v[166:169], v[122:125]
	s_waitcnt lgkmcnt(0)
	v_mfma_f32_16x16x32_f16 v[106:109], v[12:15], v[166:169], v[106:109]
	v_mfma_f32_16x16x32_f16 v[0:3], v[4:7], v[174:177], v[0:3]
	v_mfma_f32_16x16x32_f16 v[4:7], v[8:11], v[170:173], v[98:101]
	v_mfma_f32_16x16x32_f16 v[4:7], v[12:15], v[174:177], v[4:7]
	s_setprio 0
	s_barrier
	s_add_u32 s4, s16, 0x40000
	s_addc_u32 s5, s17, 0
	s_add_i32 s38, s39, s22
	v_lshl_add_u64 v[8:9], s[4:5], 0, v[178:179]
	s_mov_b32 m0, s38
	s_nop 0
	global_load_lds_dwordx4 v[8:9], off
	v_lshl_add_u64 v[8:9], s[4:5], 0, v[180:181]
	s_add_i32 m0, s38, 0x2000
	s_nop 0
	global_load_lds_dwordx4 v[8:9], off
	s_waitcnt vmcnt(10)
	s_barrier
	s_setprio 1
	v_mfma_f32_16x16x32_f16 v[12:15], v[216:219], v[70:73], v[46:49]
	v_mfma_f32_16x16x32_f16 v[46:49], v[208:211], v[86:89], v[54:57]
	v_mfma_f32_16x16x32_f16 v[54:57], v[212:215], v[90:93], v[46:49]
	v_mfma_f32_16x16x32_f16 v[46:49], v[208:211], v[162:165], v[58:61]
	v_mfma_f32_16x16x32_f16 v[38:41], v[216:219], v[86:89], v[38:41]
	v_mfma_f32_16x16x32_f16 v[58:61], v[212:215], v[166:169], v[46:49]
	v_mfma_f32_16x16x32_f16 v[42:45], v[216:219], v[162:165], v[42:45]
	v_mfma_f32_16x16x32_f16 v[46:49], v[208:211], v[170:173], v[50:53]
	v_mfma_f32_16x16x32_f16 v[34:37], v[216:219], v[170:173], v[34:37]
	v_mfma_f32_16x16x32_f16 v[8:11], v[208:211], v[70:73], v[62:65]
	v_mfma_f32_16x16x32_f16 v[38:41], v[230:233], v[90:93], v[38:41]
	v_mfma_f32_16x16x32_f16 v[42:45], v[230:233], v[166:169], v[42:45]
	v_mfma_f32_16x16x32_f16 v[50:53], v[212:215], v[174:177], v[46:49]
	v_mfma_f32_16x16x32_f16 v[34:37], v[230:233], v[174:177], v[34:37]
	v_mfma_f32_16x16x32_f16 v[8:11], v[212:215], v[78:81], v[8:11]
	v_mfma_f32_16x16x32_f16 v[12:15], v[230:233], v[78:81], v[12:15]
	s_setprio 0
	s_add_i32 s38, 0, 0x18000
	v_add_u32_e32 v32, s38, v193
	s_barrier
	ds_read_b128 v[46:49], v32
	ds_read_b128 v[62:65], v32 offset:1024
	ds_read_b128 v[98:101], v32 offset:2048
	ds_read_b128 v[162:165], v32 offset:3072
	s_add_u32 s4, s18, 0x40000
	s_addc_u32 s5, s19, 0
	s_mov_b32 m0, s25
	v_lshl_add_u64 v[86:87], s[4:5], 0, v[178:179]
	ds_read_b128 v[70:73], v206 offset:32768
	ds_read_b128 v[78:81], v206 offset:33792
	ds_read_b128 v[90:93], v206 offset:34816
	ds_read_b128 v[114:117], v206 offset:35840
	ds_read_b128 v[166:169], v206 offset:36864
	ds_read_b128 v[170:173], v206 offset:37888
	ds_read_b128 v[174:177], v206 offset:38912
	ds_read_b128 v[208:211], v206 offset:39936
	global_load_lds_dwordx4 v[86:87], off
	v_lshl_add_u64 v[86:87], s[4:5], 0, v[180:181]
	s_mov_b32 m0, s26
	s_nop 0
	global_load_lds_dwordx4 v[86:87], off
	s_waitcnt lgkmcnt(8)
	s_waitcnt vmcnt(10)
	s_barrier
	s_waitcnt lgkmcnt(6)
	s_setprio 1
	v_mfma_f32_16x16x32_f16 v[86:89], v[46:49], v[70:73], v[158:161]
	v_mfma_f32_16x16x32_f16 v[158:161], v[62:65], v[78:81], v[86:89]
	v_mfma_f32_16x16x32_f16 v[86:89], v[98:101], v[70:73], v[142:145]
	v_mfma_f32_16x16x32_f16 v[142:145], v[162:165], v[78:81], v[86:89]
	s_waitcnt lgkmcnt(4)
	v_mfma_f32_16x16x32_f16 v[86:89], v[46:49], v[90:93], v[150:153]
	v_mfma_f32_16x16x32_f16 v[150:153], v[62:65], v[114:117], v[86:89]
	v_mfma_f32_16x16x32_f16 v[86:89], v[98:101], v[90:93], v[134:137]
	v_mfma_f32_16x16x32_f16 v[134:137], v[162:165], v[114:117], v[86:89]
	s_waitcnt lgkmcnt(2)
	v_mfma_f32_16x16x32_f16 v[86:89], v[46:49], v[166:169], v[154:157]
	v_mfma_f32_16x16x32_f16 v[154:157], v[62:65], v[170:173], v[86:89]
	v_mfma_f32_16x16x32_f16 v[86:89], v[98:101], v[166:169], v[138:141]
	v_mfma_f32_16x16x32_f16 v[138:141], v[162:165], v[170:173], v[86:89]
	s_waitcnt lgkmcnt(0)
	v_mfma_f32_16x16x32_f16 v[86:89], v[46:49], v[174:177], v[146:149]
	v_mfma_f32_16x16x32_f16 v[146:149], v[62:65], v[208:211], v[86:89]
	v_mfma_f32_16x16x32_f16 v[86:89], v[98:101], v[174:177], v[130:133]
	v_mfma_f32_16x16x32_f16 v[130:133], v[162:165], v[208:211], v[86:89]
	s_setprio 0
	s_barrier
	s_add_i32 s18, 0, 0x1c000
	s_add_i32 s4, s38, s22
	v_add_u32_e32 v32, s18, v193
	s_nop 1
	v_lshl_add_u64 v[86:87], v[190:191], 0, s[84:85]
	s_mov_b32 m0, s4
	ds_read_b128 v[212:215], v32
	ds_read_b128 v[230:233], v32 offset:2048
	ds_read_b128 v[216:219], v32 offset:1024
	ds_read_b128 v[234:237], v32 offset:3072
	global_load_lds_dwordx4 v[86:87], off
	v_lshl_add_u64 v[86:87], v[238:239], 0, s[84:85]
	s_add_i32 m0, s4, 0x2000
	s_nop 0
	global_load_lds_dwordx4 v[86:87], off
	s_waitcnt vmcnt(10)
	s_barrier
	s_waitcnt lgkmcnt(2)
	s_setprio 1
	v_mfma_f32_16x16x32_f16 v[86:89], v[212:215], v[70:73], v[94:97]
	v_mfma_f32_16x16x32_f16 v[16:19], v[230:233], v[70:73], v[16:19]
	s_waitcnt lgkmcnt(0)
	v_mfma_f32_16x16x32_f16 v[94:97], v[216:219], v[78:81], v[86:89]
	v_mfma_f32_16x16x32_f16 v[78:81], v[234:237], v[78:81], v[16:19]
	v_mfma_f32_16x16x32_f16 v[16:19], v[212:215], v[90:93], v[20:23]
	v_mfma_f32_16x16x32_f16 v[86:89], v[216:219], v[114:117], v[16:19]
	v_mfma_f32_16x16x32_f16 v[16:19], v[230:233], v[90:93], v[24:27]
	v_mfma_f32_16x16x32_f16 v[70:73], v[234:237], v[114:117], v[16:19]
	v_mfma_f32_16x16x32_f16 v[16:19], v[212:215], v[166:169], v[28:31]
	v_mfma_f32_16x16x32_f16 v[90:93], v[216:219], v[170:173], v[16:19]
	v_mfma_f32_16x16x32_f16 v[16:19], v[230:233], v[166:169], v[74:77]
	v_mfma_f32_16x16x32_f16 v[74:77], v[234:237], v[170:173], v[16:19]
	v_mfma_f32_16x16x32_f16 v[16:19], v[212:215], v[174:177], v[82:85]
	v_mfma_f32_16x16x32_f16 v[82:85], v[216:219], v[208:211], v[16:19]
	v_mfma_f32_16x16x32_f16 v[16:19], v[230:233], v[174:177], v[66:69]
	v_mfma_f32_16x16x32_f16 v[66:69], v[234:237], v[208:211], v[16:19]
	s_setprio 0
	s_mov_b32 m0, s28
	v_lshl_add_u64 v[114:115], v[240:241], 0, s[84:85]
	s_barrier
	s_nop 2
	ds_read_b128 v[16:19], v206 offset:49152
	ds_read_b128 v[20:23], v206 offset:50176
	ds_read_b128 v[24:27], v206 offset:51200
	ds_read_b128 v[28:31], v206 offset:52224
	ds_read_b128 v[166:169], v206 offset:53248
	ds_read_b128 v[174:177], v206 offset:55296
	ds_read_b128 v[170:173], v206 offset:54272
	ds_read_b128 v[208:211], v206 offset:56320
	global_load_lds_dwordx4 v[114:115], off
	v_lshl_add_u64 v[114:115], v[242:243], 0, s[84:85]
	s_mov_b32 m0, s29
	s_nop 0
	global_load_lds_dwordx4 v[114:115], off
	s_barrier
	s_waitcnt lgkmcnt(6)
	s_setprio 1
	v_mfma_f32_16x16x32_f16 v[114:117], v[46:49], v[16:19], v[126:129]
	v_mfma_f32_16x16x32_f16 v[126:129], v[62:65], v[20:23], v[114:117]
	s_waitcnt lgkmcnt(4)
	v_mfma_f32_16x16x32_f16 v[114:117], v[46:49], v[24:27], v[118:121]
	v_mfma_f32_16x16x32_f16 v[118:121], v[62:65], v[28:31], v[114:117]
	s_waitcnt lgkmcnt(2)
	v_mfma_f32_16x16x32_f16 v[114:117], v[46:49], v[166:169], v[122:125]
	v_mfma_f32_16x16x32_f16 v[0:3], v[46:49], v[174:177], v[0:3]
	v_mfma_f32_16x16x32_f16 v[110:113], v[98:101], v[16:19], v[110:113]
	v_mfma_f32_16x16x32_f16 v[102:105], v[98:101], v[24:27], v[102:105]
	s_waitcnt lgkmcnt(1)
	v_mfma_f32_16x16x32_f16 v[122:125], v[62:65], v[170:173], v[114:117]
	v_mfma_f32_16x16x32_f16 v[106:109], v[98:101], v[166:169], v[106:109]
	s_waitcnt lgkmcnt(0)
	v_mfma_f32_16x16x32_f16 v[114:117], v[62:65], v[208:211], v[0:3]
	v_mfma_f32_16x16x32_f16 v[0:3], v[98:101], v[174:177], v[4:7]
	v_mfma_f32_16x16x32_f16 v[110:113], v[162:165], v[20:23], v[110:113]
	v_mfma_f32_16x16x32_f16 v[102:105], v[162:165], v[28:31], v[102:105]
	v_mfma_f32_16x16x32_f16 v[106:109], v[162:165], v[170:173], v[106:109]
	v_mfma_f32_16x16x32_f16 v[98:101], v[162:165], v[208:211], v[0:3]
	s_setprio 0
	s_barrier
	s_add_u32 s4, s16, 0x40080
	s_addc_u32 s5, s17, 0
	s_add_i32 s16, s18, s22
	v_lshl_add_u64 v[0:1], s[4:5], 0, v[178:179]
	s_mov_b32 m0, s16
	s_nop 0
	global_load_lds_dwordx4 v[0:1], off
	v_lshl_add_u64 v[0:1], s[4:5], 0, v[180:181]
	s_add_i32 m0, s16, 0x2000
	s_nop 0
	global_load_lds_dwordx4 v[0:1], off
	s_waitcnt vmcnt(10)
	s_barrier
	s_setprio 1
	v_mfma_f32_16x16x32_f16 v[0:3], v[212:215], v[16:19], v[8:11]
	v_mfma_f32_16x16x32_f16 v[62:65], v[216:219], v[20:23], v[0:3]
	v_mfma_f32_16x16x32_f16 v[0:3], v[230:233], v[16:19], v[12:15]
	v_mfma_f32_16x16x32_f16 v[46:49], v[234:237], v[20:23], v[0:3]
	v_mfma_f32_16x16x32_f16 v[0:3], v[212:215], v[24:27], v[54:57]
	v_mfma_f32_16x16x32_f16 v[54:57], v[216:219], v[28:31], v[0:3]
	v_mfma_f32_16x16x32_f16 v[0:3], v[230:233], v[24:27], v[38:41]
	v_mfma_f32_16x16x32_f16 v[38:41], v[234:237], v[28:31], v[0:3]
	v_mfma_f32_16x16x32_f16 v[0:3], v[212:215], v[166:169], v[58:61]
	v_mfma_f32_16x16x32_f16 v[58:61], v[216:219], v[170:173], v[0:3]
	v_mfma_f32_16x16x32_f16 v[0:3], v[230:233], v[166:169], v[42:45]
	v_mfma_f32_16x16x32_f16 v[42:45], v[234:237], v[170:173], v[0:3]
	v_mfma_f32_16x16x32_f16 v[0:3], v[212:215], v[174:177], v[50:53]
	v_mfma_f32_16x16x32_f16 v[50:53], v[216:219], v[208:211], v[0:3]
	v_mfma_f32_16x16x32_f16 v[0:3], v[230:233], v[174:177], v[34:37]
	v_mfma_f32_16x16x32_f16 v[34:37], v[234:237], v[208:211], v[0:3]
	s_setprio 0
	s_add_i32 s37, s37, 2
	s_add_u32 s7, s7, 0x100
	s_addc_u32 s36, s36, 0
	s_cmp_gt_u32 s37, 13
	s_mov_b64 s[4:5], s[14:15]
	s_barrier
	s_cbranch_scc0 .LBB0_403
	s_lshl_b32 s7, s34, 8
	s_cmp_lt_i32 s35, 28
	s_mov_b64 s[4:5], -1
	s_cbranch_scc0 .LBB0_431
	s_add_i32 s16, s7, s27
	v_or_b32_e32 v207, s16, v192
	s_cmp_gt_i32 s35, 3
	s_cbranch_scc0 .LBB0_411
	s_add_i32 s4, s35, -12
	s_cmp_gt_u32 s4, 7
	s_mov_b64 s[4:5], -1
	s_cbranch_scc0 .LBB0_408
	s_lshl_b32 s4, s35, 8
	s_add_i32 s5, s4, 0xfffffc00
	s_cmp_lt_u32 s35, 12
	s_cselect_b32 s4, s4, s5
	v_and_b32_e32 v10, 7, v220
	v_and_b32_e32 v11, 8, v220
	v_cmp_ne_u32_e32 vcc, 0, v11
	v_and_b32_e32 v12, 0x60, v194
	v_lshlrev_b32_e32 v12, 1, v12
	v_lshl_or_b32 v12, v11, 2, v12
	v_and_b32_e32 v13, 0x18, v194
	v_or_b32_e32 v12, v12, v13
	v_or_b32_e32 v32, s4, v12
	v_or_b32_e32 v14, s16, v10
	v_mov_b64_e32 v[4:5], s[70:71]
	v_mad_i64_i32 v[0:1], s[4:5], v14, s33, v[4:5]
	v_lshlrev_b64 v[6:7], 1, v[32:33]
	v_lshl_add_u64 v[16:17], v[0:1], 0, v[6:7]
	v_mov_b32_e32 v32, 0x30000
	v_lshl_add_u64 v[18:19], v[16:17], 0, v[32:33]
	v_lshl_add_u64 v[20:21], v[18:19], 0, v[32:33]
	v_lshl_add_u64 v[22:23], v[20:21], 0, v[32:33]
	v_mov_b32_e32 v8, 0x180000
	v_mov_b32_e32 v9, 0
	v_lshl_add_u64 v[24:25], v[16:17], 0, v[8:9]
	v_lshl_add_u64 v[26:27], v[24:25], 0, v[32:33]
	v_lshl_add_u64 v[28:29], v[26:27], 0, v[32:33]
	v_lshl_add_u64 v[30:31], v[28:29], 0, v[32:33]
	v_mov_b32_e32 v8, 0x18000
	v_cvt_pk_f16_f32 v158, v158, v159
	v_cvt_pk_f16_f32 v159, v160, v161
	v_cvt_pk_f16_f32 v160, v142, v143
	v_cvt_pk_f16_f32 v161, v144, v145
	v_cvt_pk_f16_f32 v94, v94, v95
	v_cvt_pk_f16_f32 v95, v96, v97
	v_cvt_pk_f16_f32 v96, v78, v79
	v_cvt_pk_f16_f32 v97, v80, v81
	v_mov_b32_dpp v0, v158 row_ror:8 row_mask:0xf bank_mask:0xf
	v_mov_b32_dpp v1, v159 row_ror:8 row_mask:0xf bank_mask:0xf
	v_mov_b32_dpp v2, v160 row_ror:8 row_mask:0xf bank_mask:0xf
	v_mov_b32_dpp v3, v161 row_ror:8 row_mask:0xf bank_mask:0xf
	v_mov_b32_dpp v4, v94 row_ror:8 row_mask:0xf bank_mask:0xf
	v_mov_b32_dpp v5, v95 row_ror:8 row_mask:0xf bank_mask:0xf
	v_mov_b32_dpp v6, v96 row_ror:8 row_mask:0xf bank_mask:0xf
	v_mov_b32_dpp v7, v97 row_ror:8 row_mask:0xf bank_mask:0xf
	v_cndmask_b32_e32 v158, v158, v4, vcc
	v_cndmask_b32_e32 v159, v159, v5, vcc
	v_cndmask_b32_e32 v160, v160, v6, vcc
	v_cndmask_b32_e32 v161, v161, v7, vcc
	v_cndmask_b32_e32 v94, v0, v94, vcc
	v_cndmask_b32_e32 v95, v1, v95, vcc
	v_cndmask_b32_e32 v96, v2, v96, vcc
	v_cndmask_b32_e32 v97, v3, v97, vcc
	v_lshl_add_u64 v[10:11], v[16:17], 0, v[8:9]
	global_store_dwordx4 v[16:17], v[158:161], off
	global_store_dwordx4 v[10:11], v[94:97], off
	v_cvt_pk_f16_f32 v150, v150, v151
	v_cvt_pk_f16_f32 v151, v152, v153
	v_cvt_pk_f16_f32 v152, v134, v135
	v_cvt_pk_f16_f32 v153, v136, v137
	v_cvt_pk_f16_f32 v86, v86, v87
	v_cvt_pk_f16_f32 v87, v88, v89
	v_cvt_pk_f16_f32 v88, v70, v71
	v_cvt_pk_f16_f32 v89, v72, v73
	v_mov_b32_dpp v0, v150 row_ror:8 row_mask:0xf bank_mask:0xf
	v_mov_b32_dpp v1, v151 row_ror:8 row_mask:0xf bank_mask:0xf
	v_mov_b32_dpp v2, v152 row_ror:8 row_mask:0xf bank_mask:0xf
	v_mov_b32_dpp v3, v153 row_ror:8 row_mask:0xf bank_mask:0xf
	v_mov_b32_dpp v4, v86 row_ror:8 row_mask:0xf bank_mask:0xf
	v_mov_b32_dpp v5, v87 row_ror:8 row_mask:0xf bank_mask:0xf
	v_mov_b32_dpp v6, v88 row_ror:8 row_mask:0xf bank_mask:0xf
	v_mov_b32_dpp v7, v89 row_ror:8 row_mask:0xf bank_mask:0xf
	v_cndmask_b32_e32 v150, v150, v4, vcc
	v_cndmask_b32_e32 v151, v151, v5, vcc
	v_cndmask_b32_e32 v152, v152, v6, vcc
	v_cndmask_b32_e32 v153, v153, v7, vcc
	v_cndmask_b32_e32 v86, v0, v86, vcc
	v_cndmask_b32_e32 v87, v1, v87, vcc
	v_cndmask_b32_e32 v88, v2, v88, vcc
	v_cndmask_b32_e32 v89, v3, v89, vcc
	v_lshl_add_u64 v[10:11], v[18:19], 0, v[8:9]
	global_store_dwordx4 v[18:19], v[150:153], off
	global_store_dwordx4 v[10:11], v[86:89], off
	v_cvt_pk_f16_f32 v154, v154, v155
	v_cvt_pk_f16_f32 v155, v156, v157
	v_cvt_pk_f16_f32 v156, v138, v139
	v_cvt_pk_f16_f32 v157, v140, v141
	v_cvt_pk_f16_f32 v90, v90, v91
	v_cvt_pk_f16_f32 v91, v92, v93
	v_cvt_pk_f16_f32 v92, v74, v75
	v_cvt_pk_f16_f32 v93, v76, v77
	v_mov_b32_dpp v0, v154 row_ror:8 row_mask:0xf bank_mask:0xf
	v_mov_b32_dpp v1, v155 row_ror:8 row_mask:0xf bank_mask:0xf
	v_mov_b32_dpp v2, v156 row_ror:8 row_mask:0xf bank_mask:0xf
	v_mov_b32_dpp v3, v157 row_ror:8 row_mask:0xf bank_mask:0xf
	v_mov_b32_dpp v4, v90 row_ror:8 row_mask:0xf bank_mask:0xf
	v_mov_b32_dpp v5, v91 row_ror:8 row_mask:0xf bank_mask:0xf
	v_mov_b32_dpp v6, v92 row_ror:8 row_mask:0xf bank_mask:0xf
	v_mov_b32_dpp v7, v93 row_ror:8 row_mask:0xf bank_mask:0xf
	v_cndmask_b32_e32 v154, v154, v4, vcc
	v_cndmask_b32_e32 v155, v155, v5, vcc
	v_cndmask_b32_e32 v156, v156, v6, vcc
	v_cndmask_b32_e32 v157, v157, v7, vcc
	v_cndmask_b32_e32 v90, v0, v90, vcc
	v_cndmask_b32_e32 v91, v1, v91, vcc
	v_cndmask_b32_e32 v92, v2, v92, vcc
	v_cndmask_b32_e32 v93, v3, v93, vcc
	v_lshl_add_u64 v[10:11], v[20:21], 0, v[8:9]
	global_store_dwordx4 v[20:21], v[154:157], off
	global_store_dwordx4 v[10:11], v[90:93], off
	v_cvt_pk_f16_f32 v146, v146, v147
	v_cvt_pk_f16_f32 v147, v148, v149
	v_cvt_pk_f16_f32 v148, v130, v131
	v_cvt_pk_f16_f32 v149, v132, v133
	v_cvt_pk_f16_f32 v82, v82, v83
	v_cvt_pk_f16_f32 v83, v84, v85
	v_cvt_pk_f16_f32 v84, v66, v67
	v_cvt_pk_f16_f32 v85, v68, v69
	v_mov_b32_dpp v0, v146 row_ror:8 row_mask:0xf bank_mask:0xf
	v_mov_b32_dpp v1, v147 row_ror:8 row_mask:0xf bank_mask:0xf
	v_mov_b32_dpp v2, v148 row_ror:8 row_mask:0xf bank_mask:0xf
	v_mov_b32_dpp v3, v149 row_ror:8 row_mask:0xf bank_mask:0xf
	v_mov_b32_dpp v4, v82 row_ror:8 row_mask:0xf bank_mask:0xf
	v_mov_b32_dpp v5, v83 row_ror:8 row_mask:0xf bank_mask:0xf
	v_mov_b32_dpp v6, v84 row_ror:8 row_mask:0xf bank_mask:0xf
	v_mov_b32_dpp v7, v85 row_ror:8 row_mask:0xf bank_mask:0xf
	v_cndmask_b32_e32 v146, v146, v4, vcc
	v_cndmask_b32_e32 v147, v147, v5, vcc
	v_cndmask_b32_e32 v148, v148, v6, vcc
	v_cndmask_b32_e32 v149, v149, v7, vcc
	v_cndmask_b32_e32 v82, v0, v82, vcc
	v_cndmask_b32_e32 v83, v1, v83, vcc
	v_cndmask_b32_e32 v84, v2, v84, vcc
	v_cndmask_b32_e32 v85, v3, v85, vcc
	v_lshl_add_u64 v[10:11], v[22:23], 0, v[8:9]
	global_store_dwordx4 v[22:23], v[146:149], off
	global_store_dwordx4 v[10:11], v[82:85], off
	v_cvt_pk_f16_f32 v126, v126, v127
	v_cvt_pk_f16_f32 v127, v128, v129
	v_cvt_pk_f16_f32 v128, v110, v111
	v_cvt_pk_f16_f32 v129, v112, v113
	v_cvt_pk_f16_f32 v62, v62, v63
	v_cvt_pk_f16_f32 v63, v64, v65
	v_cvt_pk_f16_f32 v64, v46, v47
	v_cvt_pk_f16_f32 v65, v48, v49
	v_mov_b32_dpp v0, v126 row_ror:8 row_mask:0xf bank_mask:0xf
	v_mov_b32_dpp v1, v127 row_ror:8 row_mask:0xf bank_mask:0xf
	v_mov_b32_dpp v2, v128 row_ror:8 row_mask:0xf bank_mask:0xf
	v_mov_b32_dpp v3, v129 row_ror:8 row_mask:0xf bank_mask:0xf
	v_mov_b32_dpp v4, v62 row_ror:8 row_mask:0xf bank_mask:0xf
	v_mov_b32_dpp v5, v63 row_ror:8 row_mask:0xf bank_mask:0xf
	v_mov_b32_dpp v6, v64 row_ror:8 row_mask:0xf bank_mask:0xf
	v_mov_b32_dpp v7, v65 row_ror:8 row_mask:0xf bank_mask:0xf
	v_cndmask_b32_e32 v126, v126, v4, vcc
	v_cndmask_b32_e32 v127, v127, v5, vcc
	v_cndmask_b32_e32 v128, v128, v6, vcc
	v_cndmask_b32_e32 v129, v129, v7, vcc
	v_cndmask_b32_e32 v62, v0, v62, vcc
	v_cndmask_b32_e32 v63, v1, v63, vcc
	v_cndmask_b32_e32 v64, v2, v64, vcc
	v_cndmask_b32_e32 v65, v3, v65, vcc
	v_lshl_add_u64 v[10:11], v[24:25], 0, v[8:9]
	global_store_dwordx4 v[24:25], v[126:129], off
	global_store_dwordx4 v[10:11], v[62:65], off
	v_cvt_pk_f16_f32 v118, v118, v119
	v_cvt_pk_f16_f32 v119, v120, v121
	v_cvt_pk_f16_f32 v120, v102, v103
	v_cvt_pk_f16_f32 v121, v104, v105
	v_cvt_pk_f16_f32 v54, v54, v55
	v_cvt_pk_f16_f32 v55, v56, v57
	v_cvt_pk_f16_f32 v56, v38, v39
	v_cvt_pk_f16_f32 v57, v40, v41
	v_mov_b32_dpp v0, v118 row_ror:8 row_mask:0xf bank_mask:0xf
	v_mov_b32_dpp v1, v119 row_ror:8 row_mask:0xf bank_mask:0xf
	v_mov_b32_dpp v2, v120 row_ror:8 row_mask:0xf bank_mask:0xf
	v_mov_b32_dpp v3, v121 row_ror:8 row_mask:0xf bank_mask:0xf
	v_mov_b32_dpp v4, v54 row_ror:8 row_mask:0xf bank_mask:0xf
	v_mov_b32_dpp v5, v55 row_ror:8 row_mask:0xf bank_mask:0xf
	v_mov_b32_dpp v6, v56 row_ror:8 row_mask:0xf bank_mask:0xf
	v_mov_b32_dpp v7, v57 row_ror:8 row_mask:0xf bank_mask:0xf
	v_cndmask_b32_e32 v118, v118, v4, vcc
	v_cndmask_b32_e32 v119, v119, v5, vcc
	v_cndmask_b32_e32 v120, v120, v6, vcc
	v_cndmask_b32_e32 v121, v121, v7, vcc
	v_cndmask_b32_e32 v54, v0, v54, vcc
	v_cndmask_b32_e32 v55, v1, v55, vcc
	v_cndmask_b32_e32 v56, v2, v56, vcc
	v_cndmask_b32_e32 v57, v3, v57, vcc
	v_lshl_add_u64 v[10:11], v[26:27], 0, v[8:9]
	global_store_dwordx4 v[26:27], v[118:121], off
	global_store_dwordx4 v[10:11], v[54:57], off
	v_cvt_pk_f16_f32 v122, v122, v123
	v_cvt_pk_f16_f32 v123, v124, v125
	v_cvt_pk_f16_f32 v124, v106, v107
	v_cvt_pk_f16_f32 v125, v108, v109
	v_cvt_pk_f16_f32 v58, v58, v59
	v_cvt_pk_f16_f32 v59, v60, v61
	v_cvt_pk_f16_f32 v60, v42, v43
	v_cvt_pk_f16_f32 v61, v44, v45
	v_mov_b32_dpp v0, v122 row_ror:8 row_mask:0xf bank_mask:0xf
	v_mov_b32_dpp v1, v123 row_ror:8 row_mask:0xf bank_mask:0xf
	v_mov_b32_dpp v2, v124 row_ror:8 row_mask:0xf bank_mask:0xf
	v_mov_b32_dpp v3, v125 row_ror:8 row_mask:0xf bank_mask:0xf
	v_mov_b32_dpp v4, v58 row_ror:8 row_mask:0xf bank_mask:0xf
	v_mov_b32_dpp v5, v59 row_ror:8 row_mask:0xf bank_mask:0xf
	v_mov_b32_dpp v6, v60 row_ror:8 row_mask:0xf bank_mask:0xf
	v_mov_b32_dpp v7, v61 row_ror:8 row_mask:0xf bank_mask:0xf
	v_cndmask_b32_e32 v122, v122, v4, vcc
	v_cndmask_b32_e32 v123, v123, v5, vcc
	v_cndmask_b32_e32 v124, v124, v6, vcc
	v_cndmask_b32_e32 v125, v125, v7, vcc
	v_cndmask_b32_e32 v58, v0, v58, vcc
	v_cndmask_b32_e32 v59, v1, v59, vcc
	v_cndmask_b32_e32 v60, v2, v60, vcc
	v_cndmask_b32_e32 v61, v3, v61, vcc
	v_lshl_add_u64 v[10:11], v[28:29], 0, v[8:9]
	global_store_dwordx4 v[28:29], v[122:125], off
	global_store_dwordx4 v[10:11], v[58:61], off
	v_cvt_pk_f16_f32 v114, v114, v115
	v_cvt_pk_f16_f32 v115, v116, v117
	v_cvt_pk_f16_f32 v116, v98, v99
	v_cvt_pk_f16_f32 v117, v100, v101
	v_cvt_pk_f16_f32 v50, v50, v51
	v_cvt_pk_f16_f32 v51, v52, v53
	v_cvt_pk_f16_f32 v52, v34, v35
	v_cvt_pk_f16_f32 v53, v36, v37
	v_mov_b32_dpp v0, v114 row_ror:8 row_mask:0xf bank_mask:0xf
	v_mov_b32_dpp v1, v115 row_ror:8 row_mask:0xf bank_mask:0xf
	v_mov_b32_dpp v2, v116 row_ror:8 row_mask:0xf bank_mask:0xf
	v_mov_b32_dpp v3, v117 row_ror:8 row_mask:0xf bank_mask:0xf
	v_mov_b32_dpp v4, v50 row_ror:8 row_mask:0xf bank_mask:0xf
	v_mov_b32_dpp v5, v51 row_ror:8 row_mask:0xf bank_mask:0xf
	v_mov_b32_dpp v6, v52 row_ror:8 row_mask:0xf bank_mask:0xf
	v_mov_b32_dpp v7, v53 row_ror:8 row_mask:0xf bank_mask:0xf
	v_cndmask_b32_e32 v114, v114, v4, vcc
	v_cndmask_b32_e32 v115, v115, v5, vcc
	v_cndmask_b32_e32 v116, v116, v6, vcc
	v_cndmask_b32_e32 v117, v117, v7, vcc
	v_cndmask_b32_e32 v50, v0, v50, vcc
	v_cndmask_b32_e32 v51, v1, v51, vcc
	v_cndmask_b32_e32 v52, v2, v52, vcc
	v_cndmask_b32_e32 v53, v3, v53, vcc
	v_lshl_add_u64 v[10:11], v[30:31], 0, v[8:9]
	global_store_dwordx4 v[30:31], v[114:117], off
	global_store_dwordx4 v[10:11], v[50:53], off
	s_mov_b64 s[4:5], 0

.LBB0_940:
	s_add_u32 s20, s14, 0x100
	s_addc_u32 s21, s15, 0
	s_add_i32 s40, 0, 0x10000
	v_add_u32_e32 v32, s40, v209
	ds_read_b128 v[132:135], v32
	ds_read_b128 v[140:143], v32 offset:2048
	ds_read_b128 v[136:139], v32 offset:1024
	ds_read_b128 v[144:147], v32 offset:3072
	s_cmp_eq_u32 s11, 12
	s_cselect_b32 s25, s17, s21
	s_cselect_b32 s24, s16, s20
	s_cselect_b32 s23, s19, s3
	s_cselect_b32 s22, s18, s1
	v_lshl_add_u64 v[34:35], s[14:15], 0, v[200:201]
	s_add_i32 m0, s30, 0xc000
	ds_read_b128 v[148:151], v211
	ds_read_b128 v[156:159], v211 offset:2048
	ds_read_b128 v[164:167], v211 offset:4096
	ds_read_b128 v[172:175], v211 offset:6144
	ds_read_b128 v[152:155], v211 offset:1024
	ds_read_b128 v[160:163], v211 offset:3072
	ds_read_b128 v[168:171], v211 offset:5120
	ds_read_b128 v[176:179], v211 offset:7168
	global_load_lds_dwordx4 v[34:35], off
	v_lshl_add_u64 v[34:35], s[14:15], 0, v[202:203]
	s_add_i32 m0, s30, 0xe000
	s_nop 0
	global_load_lds_dwordx4 v[34:35], off
	s_waitcnt lgkmcnt(8)
	s_waitcnt vmcnt(10)
	s_barrier
	s_waitcnt lgkmcnt(7)
	s_setprio 1
	v_mfma_f32_16x16x32_f16 v[128:131], v[132:135], v[148:151], v[128:131]
	v_mfma_f32_16x16x32_f16 v[124:127], v[140:143], v[148:151], v[124:127]
	s_waitcnt lgkmcnt(6)
	v_mfma_f32_16x16x32_f16 v[120:123], v[132:135], v[156:159], v[120:123]
	v_mfma_f32_16x16x32_f16 v[116:119], v[140:143], v[156:159], v[116:119]
	s_waitcnt lgkmcnt(5)
	v_mfma_f32_16x16x32_f16 v[112:115], v[132:135], v[164:167], v[112:115]
	v_mfma_f32_16x16x32_f16 v[108:111], v[140:143], v[164:167], v[108:111]
	s_waitcnt lgkmcnt(4)
	v_mfma_f32_16x16x32_f16 v[104:107], v[132:135], v[172:175], v[104:107]
	v_mfma_f32_16x16x32_f16 v[100:103], v[140:143], v[172:175], v[100:103]
	s_waitcnt lgkmcnt(3)
	v_mfma_f32_16x16x32_f16 v[128:131], v[136:139], v[152:155], v[128:131]
	v_mfma_f32_16x16x32_f16 v[124:127], v[144:147], v[152:155], v[124:127]
	s_waitcnt lgkmcnt(2)
	v_mfma_f32_16x16x32_f16 v[120:123], v[136:139], v[160:163], v[120:123]
	v_mfma_f32_16x16x32_f16 v[116:119], v[144:147], v[160:163], v[116:119]
	s_waitcnt lgkmcnt(1)
	v_mfma_f32_16x16x32_f16 v[112:115], v[136:139], v[168:171], v[112:115]
	v_mfma_f32_16x16x32_f16 v[108:111], v[144:147], v[168:171], v[108:111]
	s_waitcnt lgkmcnt(0)
	v_mfma_f32_16x16x32_f16 v[104:107], v[136:139], v[176:179], v[104:107]
	v_mfma_f32_16x16x32_f16 v[100:103], v[144:147], v[176:179], v[100:103]
	s_setprio 0
	s_barrier
	s_add_i32 s41, 0, 0x14000
	s_add_i32 s14, s40, s29
	v_add_u32_e32 v32, s41, v209
	v_lshl_add_u64 v[204:205], s[22:23], 0, v[196:197]
	s_mov_b32 m0, s14
	ds_read_b128 v[180:183], v32
	ds_read_b128 v[188:191], v32 offset:2048
	ds_read_b128 v[184:187], v32 offset:1024
	ds_read_b128 v[192:195], v32 offset:3072
	global_load_lds_dwordx4 v[204:205], off
	v_lshl_add_u64 v[206:207], s[22:23], 0, v[198:199]
	s_add_i32 m0, s14, 0x2000
	s_nop 0
	global_load_lds_dwordx4 v[206:207], off
	s_waitcnt vmcnt(10)
	s_barrier
	s_waitcnt lgkmcnt(2)
	s_setprio 1
	v_mfma_f32_16x16x32_f16 v[96:99], v[180:183], v[148:151], v[96:99]
	v_mfma_f32_16x16x32_f16 v[92:95], v[188:191], v[148:151], v[92:95]
	v_mfma_f32_16x16x32_f16 v[88:91], v[180:183], v[156:159], v[88:91]
	v_mfma_f32_16x16x32_f16 v[84:87], v[188:191], v[156:159], v[84:87]
	v_mfma_f32_16x16x32_f16 v[80:83], v[180:183], v[164:167], v[80:83]
	v_mfma_f32_16x16x32_f16 v[76:79], v[188:191], v[164:167], v[76:79]
	v_mfma_f32_16x16x32_f16 v[72:75], v[180:183], v[172:175], v[72:75]
	v_mfma_f32_16x16x32_f16 v[68:71], v[188:191], v[172:175], v[68:71]
	s_waitcnt lgkmcnt(0)
	v_mfma_f32_16x16x32_f16 v[96:99], v[184:187], v[152:155], v[96:99]
	v_mfma_f32_16x16x32_f16 v[92:95], v[192:195], v[152:155], v[92:95]
	v_mfma_f32_16x16x32_f16 v[88:91], v[184:187], v[160:163], v[88:91]
	v_mfma_f32_16x16x32_f16 v[84:87], v[192:195], v[160:163], v[84:87]
	v_mfma_f32_16x16x32_f16 v[80:83], v[184:187], v[168:171], v[80:83]
	v_mfma_f32_16x16x32_f16 v[76:79], v[192:195], v[168:171], v[76:79]
	v_mfma_f32_16x16x32_f16 v[72:75], v[184:187], v[176:179], v[72:75]
	v_mfma_f32_16x16x32_f16 v[68:71], v[192:195], v[176:179], v[68:71]
	s_setprio 0
	s_mov_b32 m0, s30
	v_lshl_add_u64 v[212:213], s[24:25], 0, v[196:197]
	s_barrier
	ds_read_b128 v[148:151], v211 offset:16384
	ds_read_b128 v[156:159], v211 offset:18432
	ds_read_b128 v[164:167], v211 offset:20480
	ds_read_b128 v[172:175], v211 offset:22528
	ds_read_b128 v[152:155], v211 offset:17408
	ds_read_b128 v[160:163], v211 offset:19456
	ds_read_b128 v[168:171], v211 offset:21504
	ds_read_b128 v[176:179], v211 offset:23552
	global_load_lds_dwordx4 v[212:213], off
	v_lshl_add_u64 v[214:215], s[24:25], 0, v[198:199]
	s_mov_b32 m0, s31
	s_nop 0
	global_load_lds_dwordx4 v[214:215], off
	s_barrier
	s_waitcnt lgkmcnt(7)
	s_setprio 1
	v_mfma_f32_16x16x32_f16 v[64:67], v[132:135], v[148:151], v[64:67]
	v_mfma_f32_16x16x32_f16 v[60:63], v[140:143], v[148:151], v[60:63]
	s_waitcnt lgkmcnt(6)
	v_mfma_f32_16x16x32_f16 v[56:59], v[132:135], v[156:159], v[56:59]
	v_mfma_f32_16x16x32_f16 v[52:55], v[140:143], v[156:159], v[52:55]
	s_waitcnt lgkmcnt(5)
	v_mfma_f32_16x16x32_f16 v[48:51], v[132:135], v[164:167], v[48:51]
	v_mfma_f32_16x16x32_f16 v[44:47], v[140:143], v[164:167], v[44:47]
	s_waitcnt lgkmcnt(4)
	v_mfma_f32_16x16x32_f16 v[40:43], v[132:135], v[172:175], v[40:43]
	v_mfma_f32_16x16x32_f16 v[34:37], v[140:143], v[172:175], v[36:39]
	s_waitcnt lgkmcnt(3)
	v_mfma_f32_16x16x32_f16 v[64:67], v[136:139], v[152:155], v[64:67]
	v_mfma_f32_16x16x32_f16 v[60:63], v[144:147], v[152:155], v[60:63]
	s_waitcnt lgkmcnt(2)
	v_mfma_f32_16x16x32_f16 v[56:59], v[136:139], v[160:163], v[56:59]
	v_mfma_f32_16x16x32_f16 v[52:55], v[144:147], v[160:163], v[52:55]
	s_waitcnt lgkmcnt(1)
	v_mfma_f32_16x16x32_f16 v[48:51], v[136:139], v[168:171], v[48:51]
	v_mfma_f32_16x16x32_f16 v[44:47], v[144:147], v[168:171], v[44:47]
	s_waitcnt lgkmcnt(0)
	v_mfma_f32_16x16x32_f16 v[40:43], v[136:139], v[176:179], v[40:43]
	v_mfma_f32_16x16x32_f16 v[34:37], v[144:147], v[176:179], v[34:37]
	s_setprio 0
	s_barrier
	s_add_u32 s14, s22, 0x40000
	s_addc_u32 s15, s23, 0
	s_add_i32 s40, s41, s29
	v_lshl_add_u64 v[38:39], s[14:15], 0, v[196:197]
	s_mov_b32 m0, s40
	s_nop 0
	global_load_lds_dwordx4 v[38:39], off
	v_lshl_add_u64 v[38:39], s[14:15], 0, v[198:199]
	s_add_i32 m0, s40, 0x2000
	s_nop 0
	global_load_lds_dwordx4 v[38:39], off
	s_waitcnt vmcnt(10)
	s_barrier
	s_setprio 1
	v_mfma_f32_16x16x32_f16 v[28:31], v[180:183], v[148:151], v[28:31]
	v_mfma_f32_16x16x32_f16 v[24:27], v[188:191], v[148:151], v[24:27]
	v_mfma_f32_16x16x32_f16 v[20:23], v[180:183], v[156:159], v[20:23]
	v_mfma_f32_16x16x32_f16 v[16:19], v[188:191], v[156:159], v[16:19]
	v_mfma_f32_16x16x32_f16 v[12:15], v[180:183], v[164:167], v[12:15]
	v_mfma_f32_16x16x32_f16 v[8:11], v[188:191], v[164:167], v[8:11]
	v_mfma_f32_16x16x32_f16 v[4:7], v[180:183], v[172:175], v[4:7]
	v_mfma_f32_16x16x32_f16 v[0:3], v[188:191], v[172:175], v[0:3]
	v_mfma_f32_16x16x32_f16 v[28:31], v[184:187], v[152:155], v[28:31]
	v_mfma_f32_16x16x32_f16 v[24:27], v[192:195], v[152:155], v[24:27]
	v_mfma_f32_16x16x32_f16 v[20:23], v[184:187], v[160:163], v[20:23]
	v_mfma_f32_16x16x32_f16 v[16:19], v[192:195], v[160:163], v[16:19]
	v_mfma_f32_16x16x32_f16 v[12:15], v[184:187], v[168:171], v[12:15]
	v_mfma_f32_16x16x32_f16 v[8:11], v[192:195], v[168:171], v[8:11]
	v_mfma_f32_16x16x32_f16 v[4:7], v[184:187], v[176:179], v[4:7]
	v_mfma_f32_16x16x32_f16 v[0:3], v[192:195], v[176:179], v[0:3]
	s_setprio 0
	s_add_i32 s40, 0, 0x18000
	v_add_u32_e32 v32, s40, v209
	s_barrier
	ds_read_b128 v[132:135], v32
	ds_read_b128 v[140:143], v32 offset:2048
	ds_read_b128 v[136:139], v32 offset:1024
	ds_read_b128 v[144:147], v32 offset:3072
	s_add_u32 s14, s24, 0x40000
	s_addc_u32 s15, s25, 0
	s_mov_b32 m0, s34
	v_lshl_add_u64 v[38:39], s[14:15], 0, v[196:197]
	ds_read_b128 v[148:151], v211 offset:32768
	ds_read_b128 v[156:159], v211 offset:34816
	ds_read_b128 v[164:167], v211 offset:36864
	ds_read_b128 v[172:175], v211 offset:38912
	ds_read_b128 v[152:155], v211 offset:33792
	ds_read_b128 v[160:163], v211 offset:35840
	ds_read_b128 v[168:171], v211 offset:37888
	ds_read_b128 v[176:179], v211 offset:39936
	global_load_lds_dwordx4 v[38:39], off
	v_lshl_add_u64 v[38:39], s[14:15], 0, v[198:199]
	s_mov_b32 m0, s35
	s_nop 0
	global_load_lds_dwordx4 v[38:39], off
	s_waitcnt lgkmcnt(8)
	s_waitcnt vmcnt(10)
	s_barrier
	s_waitcnt lgkmcnt(7)
	s_setprio 1
	v_mfma_f32_16x16x32_f16 v[128:131], v[132:135], v[148:151], v[128:131]
	v_mfma_f32_16x16x32_f16 v[124:127], v[140:143], v[148:151], v[124:127]
	s_waitcnt lgkmcnt(6)
	v_mfma_f32_16x16x32_f16 v[120:123], v[132:135], v[156:159], v[120:123]
	v_mfma_f32_16x16x32_f16 v[116:119], v[140:143], v[156:159], v[116:119]
	s_waitcnt lgkmcnt(5)
	v_mfma_f32_16x16x32_f16 v[112:115], v[132:135], v[164:167], v[112:115]
	v_mfma_f32_16x16x32_f16 v[108:111], v[140:143], v[164:167], v[108:111]
	s_waitcnt lgkmcnt(4)
	v_mfma_f32_16x16x32_f16 v[104:107], v[132:135], v[172:175], v[104:107]
	v_mfma_f32_16x16x32_f16 v[100:103], v[140:143], v[172:175], v[100:103]
	s_waitcnt lgkmcnt(3)
	v_mfma_f32_16x16x32_f16 v[128:131], v[136:139], v[152:155], v[128:131]
	v_mfma_f32_16x16x32_f16 v[124:127], v[144:147], v[152:155], v[124:127]
	s_waitcnt lgkmcnt(2)
	v_mfma_f32_16x16x32_f16 v[120:123], v[136:139], v[160:163], v[120:123]
	v_mfma_f32_16x16x32_f16 v[116:119], v[144:147], v[160:163], v[116:119]
	s_waitcnt lgkmcnt(1)
	v_mfma_f32_16x16x32_f16 v[112:115], v[136:139], v[168:171], v[112:115]
	v_mfma_f32_16x16x32_f16 v[108:111], v[144:147], v[168:171], v[108:111]
	s_waitcnt lgkmcnt(0)
	v_mfma_f32_16x16x32_f16 v[104:107], v[136:139], v[176:179], v[104:107]
	v_mfma_f32_16x16x32_f16 v[100:103], v[144:147], v[176:179], v[100:103]
	s_setprio 0
	s_barrier
	s_add_i32 s24, 0, 0x1c000
	s_add_i32 s14, s40, s29
	v_add_u32_e32 v32, s24, v209
	v_lshl_add_u64 v[38:39], v[204:205], 0, s[84:85]
	s_mov_b32 m0, s14
	ds_read_b128 v[180:183], v32
	ds_read_b128 v[188:191], v32 offset:2048
	ds_read_b128 v[184:187], v32 offset:1024
	ds_read_b128 v[192:195], v32 offset:3072
	global_load_lds_dwordx4 v[38:39], off
	v_lshl_add_u64 v[38:39], v[206:207], 0, s[84:85]
	s_add_i32 m0, s14, 0x2000
	s_nop 0
	global_load_lds_dwordx4 v[38:39], off
	s_waitcnt vmcnt(10)
	s_barrier
	s_waitcnt lgkmcnt(2)
	s_setprio 1
	v_mfma_f32_16x16x32_f16 v[96:99], v[180:183], v[148:151], v[96:99]
	v_mfma_f32_16x16x32_f16 v[92:95], v[188:191], v[148:151], v[92:95]
	v_mfma_f32_16x16x32_f16 v[88:91], v[180:183], v[156:159], v[88:91]
	v_mfma_f32_16x16x32_f16 v[84:87], v[188:191], v[156:159], v[84:87]
	v_mfma_f32_16x16x32_f16 v[80:83], v[180:183], v[164:167], v[80:83]
	v_mfma_f32_16x16x32_f16 v[76:79], v[188:191], v[164:167], v[76:79]
	v_mfma_f32_16x16x32_f16 v[72:75], v[180:183], v[172:175], v[72:75]
	v_mfma_f32_16x16x32_f16 v[68:71], v[188:191], v[172:175], v[68:71]
	s_waitcnt lgkmcnt(0)
	v_mfma_f32_16x16x32_f16 v[96:99], v[184:187], v[152:155], v[96:99]
	v_mfma_f32_16x16x32_f16 v[92:95], v[192:195], v[152:155], v[92:95]
	v_mfma_f32_16x16x32_f16 v[88:91], v[184:187], v[160:163], v[88:91]
	v_mfma_f32_16x16x32_f16 v[84:87], v[192:195], v[160:163], v[84:87]
	v_mfma_f32_16x16x32_f16 v[80:83], v[184:187], v[168:171], v[80:83]
	v_mfma_f32_16x16x32_f16 v[76:79], v[192:195], v[168:171], v[76:79]
	v_mfma_f32_16x16x32_f16 v[72:75], v[184:187], v[176:179], v[72:75]
	v_mfma_f32_16x16x32_f16 v[68:71], v[192:195], v[176:179], v[68:71]
	s_setprio 0
	s_mov_b32 m0, s36
	v_lshl_add_u64 v[38:39], v[212:213], 0, s[84:85]
	s_barrier
	ds_read_b128 v[148:151], v211 offset:49152
	ds_read_b128 v[156:159], v211 offset:51200
	ds_read_b128 v[164:167], v211 offset:53248
	ds_read_b128 v[172:175], v211 offset:55296
	ds_read_b128 v[152:155], v211 offset:50176
	ds_read_b128 v[160:163], v211 offset:52224
	ds_read_b128 v[168:171], v211 offset:54272
	ds_read_b128 v[176:179], v211 offset:56320
	global_load_lds_dwordx4 v[38:39], off
	v_lshl_add_u64 v[38:39], v[214:215], 0, s[84:85]
	s_mov_b32 m0, s37
	s_nop 0
	global_load_lds_dwordx4 v[38:39], off
	s_barrier
	s_waitcnt lgkmcnt(7)
	s_setprio 1
	v_mfma_f32_16x16x32_f16 v[64:67], v[132:135], v[148:151], v[64:67]
	v_mfma_f32_16x16x32_f16 v[60:63], v[140:143], v[148:151], v[60:63]
	s_waitcnt lgkmcnt(6)
	v_mfma_f32_16x16x32_f16 v[56:59], v[132:135], v[156:159], v[56:59]
	v_mfma_f32_16x16x32_f16 v[52:55], v[140:143], v[156:159], v[52:55]
	s_waitcnt lgkmcnt(5)
	v_mfma_f32_16x16x32_f16 v[48:51], v[132:135], v[164:167], v[48:51]
	v_mfma_f32_16x16x32_f16 v[44:47], v[140:143], v[164:167], v[44:47]
	s_waitcnt lgkmcnt(4)
	v_mfma_f32_16x16x32_f16 v[38:41], v[132:135], v[172:175], v[40:43]
	v_mfma_f32_16x16x32_f16 v[34:37], v[140:143], v[172:175], v[34:37]
	s_waitcnt lgkmcnt(3)
	v_mfma_f32_16x16x32_f16 v[64:67], v[136:139], v[152:155], v[64:67]
	v_mfma_f32_16x16x32_f16 v[60:63], v[144:147], v[152:155], v[60:63]
	s_waitcnt lgkmcnt(2)
	v_mfma_f32_16x16x32_f16 v[56:59], v[136:139], v[160:163], v[56:59]
	v_mfma_f32_16x16x32_f16 v[52:55], v[144:147], v[160:163], v[52:55]
	s_waitcnt lgkmcnt(1)
	v_mfma_f32_16x16x32_f16 v[48:51], v[136:139], v[168:171], v[48:51]
	v_mfma_f32_16x16x32_f16 v[44:47], v[144:147], v[168:171], v[44:47]
	s_waitcnt lgkmcnt(0)
	v_mfma_f32_16x16x32_f16 v[40:43], v[136:139], v[176:179], v[38:41]
	v_mfma_f32_16x16x32_f16 v[36:39], v[144:147], v[176:179], v[34:37]
	s_setprio 0
	s_barrier
	s_add_u32 s14, s22, 0x40080
	s_addc_u32 s15, s23, 0
	s_add_i32 s22, s24, s29
	v_lshl_add_u64 v[34:35], s[14:15], 0, v[196:197]
	s_mov_b32 m0, s22
	s_nop 0
	global_load_lds_dwordx4 v[34:35], off
	v_lshl_add_u64 v[34:35], s[14:15], 0, v[198:199]
	s_add_i32 m0, s22, 0x2000
	s_nop 0
	global_load_lds_dwordx4 v[34:35], off
	s_waitcnt vmcnt(10)
	s_barrier
	s_setprio 1
	v_mfma_f32_16x16x32_f16 v[28:31], v[180:183], v[148:151], v[28:31]
	v_mfma_f32_16x16x32_f16 v[24:27], v[188:191], v[148:151], v[24:27]
	v_mfma_f32_16x16x32_f16 v[20:23], v[180:183], v[156:159], v[20:23]
	v_mfma_f32_16x16x32_f16 v[16:19], v[188:191], v[156:159], v[16:19]
	v_mfma_f32_16x16x32_f16 v[12:15], v[180:183], v[164:167], v[12:15]
	v_mfma_f32_16x16x32_f16 v[8:11], v[188:191], v[164:167], v[8:11]
	v_mfma_f32_16x16x32_f16 v[4:7], v[180:183], v[172:175], v[4:7]
	v_mfma_f32_16x16x32_f16 v[0:3], v[188:191], v[172:175], v[0:3]
	v_mfma_f32_16x16x32_f16 v[28:31], v[184:187], v[152:155], v[28:31]
	v_mfma_f32_16x16x32_f16 v[24:27], v[192:195], v[152:155], v[24:27]
	v_mfma_f32_16x16x32_f16 v[20:23], v[184:187], v[160:163], v[20:23]
	v_mfma_f32_16x16x32_f16 v[16:19], v[192:195], v[160:163], v[16:19]
	v_mfma_f32_16x16x32_f16 v[12:15], v[184:187], v[168:171], v[12:15]
	v_mfma_f32_16x16x32_f16 v[8:11], v[192:195], v[168:171], v[8:11]
	v_mfma_f32_16x16x32_f16 v[4:7], v[184:187], v[176:179], v[4:7]
	v_mfma_f32_16x16x32_f16 v[0:3], v[192:195], v[176:179], v[0:3]
	s_setprio 0
	s_add_i32 s11, s11, 2
	s_add_u32 s1, s1, 0x100
	s_addc_u32 s3, s3, 0
	s_cmp_gt_u32 s11, 13
	s_mov_b64 s[14:15], s[20:21]
	s_barrier
	s_cbranch_scc0 .LBB0_940
	v_lshl_add_u32 v34, s12, 8, v208
	v_lshl_or_b32 v156, s10, 8, v210
	s_cmp_lg_u32 s13, 0
	s_cselect_b64 s[10:11], -1, 0
	s_cmp_eq_u32 s13, 0
	v_ashrrev_i32_e32 v157, 31, v156
	v_ashrrev_i32_e32 v35, 31, v34
	v_mad_i64_i32 v[158:159], s[12:13], v34, s33, 0
	v_or_b32_e32 v160, 16, v34
	v_or_b32_e32 v162, 32, v34
	v_or_b32_e32 v164, 48, v34
	s_cbranch_scc1 .LBB0_946
	v_lshl_add_u64 v[132:133], s[70:71], 0, v[158:159]
	v_lshlrev_b64 v[166:167], 1, v[156:157]
	v_lshl_add_u64 v[132:133], v[132:133], 0, v[166:167]
	s_mov_b64 s[16:17], 0x2800
	v_mov_b64_e32 v[168:169], s[70:71]
	s_movk_i32 s1, 0x2000
	v_lshl_add_u64 v[134:135], v[132:133], 0, s[16:17]
	v_mad_i64_i32 v[136:137], s[12:13], v160, s33, v[168:169]
	v_add_co_u32_e32 v132, vcc, s1, v132
	v_lshl_add_u64 v[136:137], v[136:137], 0, v[166:167]
	s_nop 0
	v_addc_co_u32_e32 v133, vcc, 0, v133, vcc
	v_lshl_add_u64 v[138:139], v[136:137], 0, s[16:17]
	v_mad_i64_i32 v[140:141], s[12:13], v162, s33, v[168:169]
	v_add_co_u32_e32 v136, vcc, s1, v136
	v_lshl_add_u64 v[140:141], v[140:141], 0, v[166:167]
	s_nop 0
	v_addc_co_u32_e32 v137, vcc, 0, v137, vcc
	v_mad_i64_i32 v[144:145], s[12:13], v164, s33, v[168:169]
	global_load_dwordx4 v[170:173], v[132:133], off offset:2048
	global_load_dwordx4 v[152:155], v[136:137], off offset:2048
	global_load_dwordx4 v[174:177], v[134:135], off offset:256
	global_load_dwordx4 v[148:151], v[138:139], off offset:256
	v_add_co_u32_e32 v132, vcc, s1, v140
	v_lshl_add_u64 v[144:145], v[144:145], 0, v[166:167]
	s_nop 0
	v_addc_co_u32_e32 v133, vcc, 0, v141, vcc
	v_add_co_u32_e32 v134, vcc, s1, v144
	v_lshl_add_u64 v[142:143], v[140:141], 0, s[16:17]
	s_nop 0
	v_addc_co_u32_e32 v135, vcc, 0, v145, vcc
	v_lshl_add_u64 v[178:179], v[144:145], 0, s[16:17]
	global_load_dwordx4 v[144:147], v[132:133], off offset:2048
	global_load_dwordx4 v[136:139], v[134:135], off offset:2048
	s_nop 0
	global_load_dwordx4 v[140:143], v[142:143], off offset:256
	s_nop 0
	global_load_dwordx4 v[132:135], v[178:179], off offset:256
	v_ashrrev_i32_e32 v161, 31, v160
	v_ashrrev_i32_e32 v163, 31, v162
	v_ashrrev_i32_e32 v165, 31, v164
	s_waitcnt vmcnt(0)
	v_cvt_f32_f16_e32 v32, v170
	v_cvt_f32_f16_sdwa v170, v170 dst_sel:DWORD dst_unused:UNUSED_PAD src0_sel:WORD_1
	v_lshlrev_b64 v[178:179], 11, v[34:35]
	v_readlane_b32 s14, v252, 9
	v_max_f32_e32 v32, 0xc1f00000, v32
	v_max_f32_e32 v35, 0xc1f00000, v170
	v_cvt_f32_f16_e32 v170, v171
	v_cvt_f32_f16_sdwa v171, v171 dst_sel:DWORD dst_unused:UNUSED_PAD src0_sel:WORD_1
	v_mul_f32_e32 v35, 0xbfb8aa3b, v35
	v_exp_f32_e32 v35, v35
	v_max_f32_e32 v170, 0xc1f00000, v170
	v_mul_f32_e32 v170, 0xbfb8aa3b, v170
	v_exp_f32_e32 v180, v170
	v_max_f32_e32 v170, 0xc1f00000, v171
	v_mul_f32_e32 v170, 0xbfb8aa3b, v170
	v_cvt_f32_f16_e32 v171, v172
	v_exp_f32_e32 v181, v170
	v_cvt_f32_f16_sdwa v170, v172 dst_sel:DWORD dst_unused:UNUSED_PAD src0_sel:WORD_1
	v_mul_f32_e32 v32, 0xbfb8aa3b, v32
	v_max_f32_e32 v171, 0xc1f00000, v171
	v_mul_f32_e32 v171, 0xbfb8aa3b, v171
	v_max_f32_e32 v170, 0xc1f00000, v170
	v_mul_f32_e32 v170, 0xbfb8aa3b, v170
	v_exp_f32_e32 v182, v171
	v_cvt_f32_f16_e32 v171, v173
	v_exp_f32_e32 v183, v170
	v_cvt_f32_f16_sdwa v170, v173 dst_sel:DWORD dst_unused:UNUSED_PAD src0_sel:WORD_1
	v_exp_f32_e32 v32, v32
	v_max_f32_e32 v171, 0xc1f00000, v171
	v_mul_f32_e32 v171, 0xbfb8aa3b, v171
	v_max_f32_e32 v170, 0xc1f00000, v170
	v_mul_f32_e32 v170, 0xbfb8aa3b, v170
	v_add_f32_e32 v35, 1.0, v35
	v_exp_f32_e32 v184, v171
	v_exp_f32_e32 v185, v170
	v_rcp_f32_e32 v170, v35
	v_add_f32_e32 v35, 1.0, v180
	v_rcp_f32_e32 v171, v35
	v_add_f32_e32 v35, 1.0, v181
	v_add_f32_e32 v32, 1.0, v32
	v_rcp_f32_e32 v172, v35
	v_add_f32_e32 v35, 1.0, v182
	v_rcp_f32_e32 v32, v32
	v_rcp_f32_e32 v173, v35
	v_add_f32_e32 v35, 1.0, v183
	v_rcp_f32_e32 v180, v35
	v_add_f32_e32 v35, 1.0, v184
	v_rcp_f32_e32 v181, v35
	v_mov_b32_e32 v182, v129
	v_mov_b32_e32 v183, v130
	v_pk_mul_f32 v[170:171], v[182:183], v[170:171]
	v_pk_mov_b32 v[182:183], v[130:131], v[124:125] op_sel:[1,0]
	v_add_f32_e32 v35, 1.0, v185
	v_fma_mixlo_f16 v32, v128, v32, 0
	v_cvt_pk_f16_f32 v171, v170, v171
	v_pk_mul_f32 v[172:173], v[182:183], v[172:173]
	v_rcp_f32_e32 v35, v35
	v_pack_b32_f16 v170, v32, v171
	v_cvt_pk_f16_f32 v32, v172, v173
	v_mov_b32_e32 v172, v125
	v_mov_b32_e32 v173, v126
	v_pk_mul_f32 v[172:173], v[172:173], v[180:181]
	v_readlane_b32 s15, v252, 10
	v_cvt_pk_f16_f32 v173, v172, v173
	v_alignbit_b32 v172, v173, v32, 16
	v_lshrrev_b32_e32 v173, 16, v173
	v_lshl_add_u64 v[178:179], s[14:15], 0, v[178:179]
	v_alignbit_b32 v171, v32, v171, 16
	v_fma_mixhi_f16 v173, v127, v35, 0
	v_lshl_add_u64 v[178:179], v[178:179], 0, v[166:167]
	global_store_dwordx4 v[178:179], v[170:173], off
	v_cvt_f32_f16_sdwa v35, v174 dst_sel:DWORD dst_unused:UNUSED_PAD src0_sel:WORD_1
	v_cvt_f32_f16_e32 v32, v174
	v_cvt_f32_f16_e32 v170, v175
	v_cvt_f32_f16_sdwa v171, v175 dst_sel:DWORD dst_unused:UNUSED_PAD src0_sel:WORD_1
	v_max_f32_e32 v35, 0xc1f00000, v35
	v_mul_f32_e32 v35, 0xbfb8aa3b, v35
	v_max_f32_e32 v170, 0xc1f00000, v170
	v_mul_f32_e32 v170, 0xbfb8aa3b, v170
	v_exp_f32_e32 v172, v170
	v_max_f32_e32 v170, 0xc1f00000, v171
	v_mul_f32_e32 v170, 0xbfb8aa3b, v170
	v_cvt_f32_f16_e32 v171, v176
	v_exp_f32_e32 v173, v170
	v_cvt_f32_f16_sdwa v170, v176 dst_sel:DWORD dst_unused:UNUSED_PAD src0_sel:WORD_1
	v_exp_f32_e32 v35, v35
	v_max_f32_e32 v171, 0xc1f00000, v171
	v_mul_f32_e32 v171, 0xbfb8aa3b, v171
	v_max_f32_e32 v170, 0xc1f00000, v170
	v_mul_f32_e32 v170, 0xbfb8aa3b, v170
	v_exp_f32_e32 v174, v171
	v_cvt_f32_f16_e32 v171, v177
	v_exp_f32_e32 v175, v170
	v_cvt_f32_f16_sdwa v170, v177 dst_sel:DWORD dst_unused:UNUSED_PAD src0_sel:WORD_1
	v_max_f32_e32 v32, 0xc1f00000, v32
	v_mul_f32_e32 v32, 0xbfb8aa3b, v32
	v_exp_f32_e32 v32, v32
	v_max_f32_e32 v171, 0xc1f00000, v171
	v_max_f32_e32 v170, 0xc1f00000, v170
	v_mul_f32_e32 v171, 0xbfb8aa3b, v171
	v_mul_f32_e32 v170, 0xbfb8aa3b, v170
	v_add_f32_e32 v35, 1.0, v35
	v_exp_f32_e32 v176, v171
	v_exp_f32_e32 v177, v170
	v_rcp_f32_e32 v170, v35
	v_add_f32_e32 v35, 1.0, v172
	v_rcp_f32_e32 v171, v35
	v_add_f32_e32 v35, 1.0, v173
	v_add_f32_e32 v32, 1.0, v32
	v_rcp_f32_e32 v172, v35
	v_add_f32_e32 v35, 1.0, v174
	v_rcp_f32_e32 v32, v32
	v_rcp_f32_e32 v173, v35
	v_add_f32_e32 v35, 1.0, v175
	v_rcp_f32_e32 v174, v35
	v_add_f32_e32 v35, 1.0, v176
	v_rcp_f32_e32 v175, v35
	v_add_f32_e32 v35, 1.0, v177
	v_mov_b32_e32 v176, v97
	v_mov_b32_e32 v177, v98
	v_pk_mul_f32 v[170:171], v[176:177], v[170:171]
	v_pk_mov_b32 v[176:177], v[98:99], v[92:93] op_sel:[1,0]
	v_fma_mixlo_f16 v32, v96, v32, 0
	v_cvt_pk_f16_f32 v171, v170, v171
	v_pk_mul_f32 v[172:173], v[176:177], v[172:173]
	v_rcp_f32_e32 v35, v35
	v_pack_b32_f16 v170, v32, v171
	v_cvt_pk_f16_f32 v32, v172, v173
	v_mov_b32_e32 v172, v93
	v_mov_b32_e32 v173, v94
	v_pk_mul_f32 v[172:173], v[172:173], v[174:175]
	v_alignbit_b32 v171, v32, v171, 16
	v_cvt_pk_f16_f32 v173, v172, v173
	v_alignbit_b32 v172, v173, v32, 16
	v_lshrrev_b32_e32 v173, 16, v173
	v_fma_mixhi_f16 v173, v95, v35, 0
	v_cvt_f32_f16_e32 v32, v152
	v_cvt_f32_f16_sdwa v35, v152 dst_sel:DWORD dst_unused:UNUSED_PAD src0_sel:WORD_1
	v_cvt_f32_f16_e32 v152, v153
	v_cvt_f32_f16_sdwa v153, v153 dst_sel:DWORD dst_unused:UNUSED_PAD src0_sel:WORD_1
	global_store_dwordx4 v[178:179], v[170:173], off offset:256
	v_max_f32_e32 v35, 0xc1f00000, v35
	v_max_f32_e32 v152, 0xc1f00000, v152
	v_mul_f32_e32 v152, 0xbfb8aa3b, v152
	v_lshlrev_b64 v[170:171], 11, v[160:161]
	v_exp_f32_e32 v161, v152
	v_max_f32_e32 v152, 0xc1f00000, v153
	v_mul_f32_e32 v152, 0xbfb8aa3b, v152
	v_cvt_f32_f16_e32 v153, v154
	v_exp_f32_e32 v172, v152
	v_cvt_f32_f16_sdwa v152, v154 dst_sel:DWORD dst_unused:UNUSED_PAD src0_sel:WORD_1
	v_mul_f32_e32 v35, 0xbfb8aa3b, v35
	v_max_f32_e32 v153, 0xc1f00000, v153
	v_mul_f32_e32 v153, 0xbfb8aa3b, v153
	v_max_f32_e32 v152, 0xc1f00000, v152
	v_mul_f32_e32 v152, 0xbfb8aa3b, v152
	v_exp_f32_e32 v173, v153
	v_cvt_f32_f16_e32 v153, v155
	v_exp_f32_e32 v174, v152
	v_cvt_f32_f16_sdwa v152, v155 dst_sel:DWORD dst_unused:UNUSED_PAD src0_sel:WORD_1
	v_exp_f32_e32 v35, v35
	v_max_f32_e32 v32, 0xc1f00000, v32
	v_mul_f32_e32 v32, 0xbfb8aa3b, v32
	v_exp_f32_e32 v32, v32
	v_max_f32_e32 v153, 0xc1f00000, v153
	v_max_f32_e32 v152, 0xc1f00000, v152
	v_mul_f32_e32 v153, 0xbfb8aa3b, v153
	v_mul_f32_e32 v152, 0xbfb8aa3b, v152
	v_add_f32_e32 v35, 1.0, v35
	v_exp_f32_e32 v175, v153
	v_exp_f32_e32 v176, v152
	v_rcp_f32_e32 v152, v35
	v_add_f32_e32 v35, 1.0, v161
	v_rcp_f32_e32 v153, v35
	v_add_f32_e32 v35, 1.0, v172
	v_add_f32_e32 v32, 1.0, v32
	v_rcp_f32_e32 v154, v35
	v_add_f32_e32 v35, 1.0, v173
	v_rcp_f32_e32 v32, v32
	v_rcp_f32_e32 v155, v35
	v_add_f32_e32 v35, 1.0, v174
	v_rcp_f32_e32 v172, v35
	v_add_f32_e32 v35, 1.0, v175
	v_rcp_f32_e32 v173, v35
	v_mov_b32_e32 v174, v121
	v_mov_b32_e32 v175, v122
	v_pk_mul_f32 v[152:153], v[174:175], v[152:153]
	v_pk_mov_b32 v[174:175], v[122:123], v[116:117] op_sel:[1,0]
	v_add_f32_e32 v35, 1.0, v176
	v_fma_mixlo_f16 v32, v120, v32, 0
	v_cvt_pk_f16_f32 v153, v152, v153
	v_pk_mul_f32 v[154:155], v[174:175], v[154:155]
	v_rcp_f32_e32 v35, v35
	v_pack_b32_f16 v152, v32, v153
	v_cvt_pk_f16_f32 v32, v154, v155
	v_mov_b32_e32 v154, v117
	v_mov_b32_e32 v155, v118
	v_pk_mul_f32 v[154:155], v[154:155], v[172:173]
	v_alignbit_b32 v153, v32, v153, 16
	v_cvt_pk_f16_f32 v155, v154, v155
	v_alignbit_b32 v154, v155, v32, 16
	v_lshrrev_b32_e32 v155, 16, v155
	v_fma_mixhi_f16 v155, v119, v35, 0
	v_cvt_f32_f16_e32 v32, v148
	v_cvt_f32_f16_sdwa v35, v148 dst_sel:DWORD dst_unused:UNUSED_PAD src0_sel:WORD_1
	v_cvt_f32_f16_e32 v148, v149
	v_cvt_f32_f16_sdwa v149, v149 dst_sel:DWORD dst_unused:UNUSED_PAD src0_sel:WORD_1
	v_lshl_add_u64 v[170:171], s[14:15], 0, v[170:171]
	v_lshl_add_u64 v[170:171], v[170:171], 0, v[166:167]
	v_max_f32_e32 v148, 0xc1f00000, v148
	v_mul_f32_e32 v148, 0xbfb8aa3b, v148
	global_store_dwordx4 v[170:171], v[152:155], off
	v_max_f32_e32 v35, 0xc1f00000, v35
	v_mul_f32_e32 v35, 0xbfb8aa3b, v35
	v_exp_f32_e32 v152, v148
	v_max_f32_e32 v148, 0xc1f00000, v149
	v_mul_f32_e32 v148, 0xbfb8aa3b, v148
	v_cvt_f32_f16_e32 v149, v150
	v_exp_f32_e32 v153, v148
	v_cvt_f32_f16_sdwa v148, v150 dst_sel:DWORD dst_unused:UNUSED_PAD src0_sel:WORD_1
	v_exp_f32_e32 v35, v35
	v_max_f32_e32 v149, 0xc1f00000, v149
	v_mul_f32_e32 v149, 0xbfb8aa3b, v149
	v_max_f32_e32 v148, 0xc1f00000, v148
	v_mul_f32_e32 v148, 0xbfb8aa3b, v148
	v_exp_f32_e32 v154, v149
	v_cvt_f32_f16_e32 v149, v151
	v_exp_f32_e32 v155, v148
	v_cvt_f32_f16_sdwa v148, v151 dst_sel:DWORD dst_unused:UNUSED_PAD src0_sel:WORD_1
	v_max_f32_e32 v32, 0xc1f00000, v32
	v_mul_f32_e32 v32, 0xbfb8aa3b, v32
	v_exp_f32_e32 v32, v32
	v_max_f32_e32 v149, 0xc1f00000, v149
	v_max_f32_e32 v148, 0xc1f00000, v148
	v_mul_f32_e32 v149, 0xbfb8aa3b, v149
	v_mul_f32_e32 v148, 0xbfb8aa3b, v148
	v_add_f32_e32 v35, 1.0, v35
	v_exp_f32_e32 v161, v149
	v_exp_f32_e32 v172, v148
	v_rcp_f32_e32 v148, v35
	v_add_f32_e32 v35, 1.0, v152
	v_rcp_f32_e32 v149, v35
	v_add_f32_e32 v35, 1.0, v153
	v_add_f32_e32 v32, 1.0, v32
	v_rcp_f32_e32 v150, v35
	v_add_f32_e32 v35, 1.0, v154
	v_rcp_f32_e32 v32, v32
	v_rcp_f32_e32 v151, v35
	v_add_f32_e32 v35, 1.0, v155
	v_rcp_f32_e32 v152, v35
	v_add_f32_e32 v35, 1.0, v161
	v_rcp_f32_e32 v153, v35
	v_mov_b32_e32 v154, v89
	v_mov_b32_e32 v155, v90
	v_pk_mul_f32 v[148:149], v[154:155], v[148:149]
	v_pk_mov_b32 v[154:155], v[90:91], v[84:85] op_sel:[1,0]
	v_add_f32_e32 v35, 1.0, v172
	v_fma_mixlo_f16 v32, v88, v32, 0
	v_cvt_pk_f16_f32 v149, v148, v149
	v_pk_mul_f32 v[150:151], v[154:155], v[150:151]
	v_rcp_f32_e32 v35, v35
	v_pack_b32_f16 v148, v32, v149
	v_cvt_pk_f16_f32 v32, v150, v151
	v_mov_b32_e32 v150, v85
	v_mov_b32_e32 v151, v86
	v_pk_mul_f32 v[150:151], v[150:151], v[152:153]
	v_alignbit_b32 v149, v32, v149, 16
	v_cvt_pk_f16_f32 v151, v150, v151
	v_alignbit_b32 v150, v151, v32, 16
	v_lshrrev_b32_e32 v151, 16, v151
	v_fma_mixhi_f16 v151, v87, v35, 0
	v_cvt_f32_f16_e32 v32, v144
	v_cvt_f32_f16_sdwa v35, v144 dst_sel:DWORD dst_unused:UNUSED_PAD src0_sel:WORD_1
	v_cvt_f32_f16_e32 v144, v145
	v_cvt_f32_f16_sdwa v145, v145 dst_sel:DWORD dst_unused:UNUSED_PAD src0_sel:WORD_1
	global_store_dwordx4 v[170:171], v[148:151], off offset:256
	v_max_f32_e32 v35, 0xc1f00000, v35
	v_max_f32_e32 v144, 0xc1f00000, v144
	v_mul_f32_e32 v144, 0xbfb8aa3b, v144
	v_exp_f32_e32 v150, v144
	v_max_f32_e32 v144, 0xc1f00000, v145
	v_mul_f32_e32 v144, 0xbfb8aa3b, v144
	v_cvt_f32_f16_e32 v145, v146
	v_exp_f32_e32 v151, v144
	v_cvt_f32_f16_sdwa v144, v146 dst_sel:DWORD dst_unused:UNUSED_PAD src0_sel:WORD_1
	v_mul_f32_e32 v35, 0xbfb8aa3b, v35
	v_max_f32_e32 v145, 0xc1f00000, v145
	v_mul_f32_e32 v145, 0xbfb8aa3b, v145
	v_max_f32_e32 v144, 0xc1f00000, v144
	v_mul_f32_e32 v144, 0xbfb8aa3b, v144
	v_exp_f32_e32 v152, v145
	v_cvt_f32_f16_e32 v145, v147
	v_exp_f32_e32 v153, v144
	v_cvt_f32_f16_sdwa v144, v147 dst_sel:DWORD dst_unused:UNUSED_PAD src0_sel:WORD_1
	v_exp_f32_e32 v35, v35
	v_max_f32_e32 v32, 0xc1f00000, v32
	v_mul_f32_e32 v32, 0xbfb8aa3b, v32
	v_exp_f32_e32 v32, v32
	v_max_f32_e32 v145, 0xc1f00000, v145
	v_max_f32_e32 v144, 0xc1f00000, v144
	v_mul_f32_e32 v145, 0xbfb8aa3b, v145
	v_mul_f32_e32 v144, 0xbfb8aa3b, v144
	v_add_f32_e32 v35, 1.0, v35
	v_exp_f32_e32 v154, v145
	v_exp_f32_e32 v155, v144
	v_rcp_f32_e32 v144, v35
	v_add_f32_e32 v35, 1.0, v150
	v_rcp_f32_e32 v145, v35
	v_add_f32_e32 v35, 1.0, v151
	v_add_f32_e32 v32, 1.0, v32
	v_rcp_f32_e32 v146, v35
	v_add_f32_e32 v35, 1.0, v152
	v_rcp_f32_e32 v32, v32
	v_rcp_f32_e32 v147, v35
	v_add_f32_e32 v35, 1.0, v153
	v_rcp_f32_e32 v150, v35
	v_add_f32_e32 v35, 1.0, v154
	v_rcp_f32_e32 v151, v35
	v_mov_b32_e32 v152, v113
	v_mov_b32_e32 v153, v114
	v_pk_mul_f32 v[144:145], v[152:153], v[144:145]
	v_pk_mov_b32 v[152:153], v[114:115], v[108:109] op_sel:[1,0]
	v_add_f32_e32 v35, 1.0, v155
	v_fma_mixlo_f16 v32, v112, v32, 0
	v_cvt_pk_f16_f32 v145, v144, v145
	v_pk_mul_f32 v[146:147], v[152:153], v[146:147]
	v_rcp_f32_e32 v35, v35
	v_pack_b32_f16 v144, v32, v145
	v_cvt_pk_f16_f32 v32, v146, v147
	v_mov_b32_e32 v146, v109
	v_mov_b32_e32 v147, v110
	v_pk_mul_f32 v[146:147], v[146:147], v[150:151]
	v_alignbit_b32 v145, v32, v145, 16
	v_cvt_pk_f16_f32 v147, v146, v147
	v_alignbit_b32 v146, v147, v32, 16
	v_lshrrev_b32_e32 v147, 16, v147
	v_fma_mixhi_f16 v147, v111, v35, 0
	v_cvt_f32_f16_e32 v32, v140
	v_cvt_f32_f16_sdwa v35, v140 dst_sel:DWORD dst_unused:UNUSED_PAD src0_sel:WORD_1
	v_cvt_f32_f16_e32 v140, v141
	v_cvt_f32_f16_sdwa v141, v141 dst_sel:DWORD dst_unused:UNUSED_PAD src0_sel:WORD_1
	v_lshlrev_b64 v[148:149], 11, v[162:163]
	v_lshl_add_u64 v[148:149], s[14:15], 0, v[148:149]
	v_max_f32_e32 v140, 0xc1f00000, v140
	v_lshl_add_u64 v[148:149], v[148:149], 0, v[166:167]
	v_mul_f32_e32 v140, 0xbfb8aa3b, v140
	global_store_dwordx4 v[148:149], v[144:147], off
	v_max_f32_e32 v35, 0xc1f00000, v35
	v_mul_f32_e32 v35, 0xbfb8aa3b, v35
	v_exp_f32_e32 v144, v140
	v_max_f32_e32 v140, 0xc1f00000, v141
	v_mul_f32_e32 v140, 0xbfb8aa3b, v140
	v_cvt_f32_f16_e32 v141, v142
	v_exp_f32_e32 v145, v140
	v_cvt_f32_f16_sdwa v140, v142 dst_sel:DWORD dst_unused:UNUSED_PAD src0_sel:WORD_1
	v_exp_f32_e32 v35, v35
	v_max_f32_e32 v141, 0xc1f00000, v141
	v_mul_f32_e32 v141, 0xbfb8aa3b, v141
	v_max_f32_e32 v140, 0xc1f00000, v140
	v_mul_f32_e32 v140, 0xbfb8aa3b, v140
	v_exp_f32_e32 v146, v141
	v_cvt_f32_f16_e32 v141, v143
	v_exp_f32_e32 v147, v140
	v_cvt_f32_f16_sdwa v140, v143 dst_sel:DWORD dst_unused:UNUSED_PAD src0_sel:WORD_1
	v_max_f32_e32 v32, 0xc1f00000, v32
	v_mul_f32_e32 v32, 0xbfb8aa3b, v32
	v_exp_f32_e32 v32, v32
	v_max_f32_e32 v141, 0xc1f00000, v141
	v_max_f32_e32 v140, 0xc1f00000, v140
	v_mul_f32_e32 v141, 0xbfb8aa3b, v141
	v_mul_f32_e32 v140, 0xbfb8aa3b, v140
	v_add_f32_e32 v35, 1.0, v35
	v_exp_f32_e32 v150, v141
	v_exp_f32_e32 v151, v140
	v_rcp_f32_e32 v140, v35
	v_add_f32_e32 v35, 1.0, v144
	v_rcp_f32_e32 v141, v35
	v_add_f32_e32 v35, 1.0, v145
	v_add_f32_e32 v32, 1.0, v32
	v_rcp_f32_e32 v142, v35
	v_add_f32_e32 v35, 1.0, v146
	v_rcp_f32_e32 v32, v32
	v_rcp_f32_e32 v143, v35
	v_add_f32_e32 v35, 1.0, v147
	v_rcp_f32_e32 v144, v35
	v_add_f32_e32 v35, 1.0, v150
	v_rcp_f32_e32 v145, v35
	v_mov_b32_e32 v146, v81
	v_mov_b32_e32 v147, v82
	v_pk_mul_f32 v[140:141], v[146:147], v[140:141]
	v_pk_mov_b32 v[146:147], v[82:83], v[76:77] op_sel:[1,0]
	v_add_f32_e32 v35, 1.0, v151
	v_fma_mixlo_f16 v32, v80, v32, 0
	v_cvt_pk_f16_f32 v141, v140, v141
	v_pk_mul_f32 v[142:143], v[146:147], v[142:143]
	v_rcp_f32_e32 v35, v35
	v_pack_b32_f16 v140, v32, v141
	v_cvt_pk_f16_f32 v32, v142, v143
	v_mov_b32_e32 v142, v77
	v_mov_b32_e32 v143, v78
	v_pk_mul_f32 v[142:143], v[142:143], v[144:145]
	v_alignbit_b32 v141, v32, v141, 16
	v_cvt_pk_f16_f32 v143, v142, v143
	v_alignbit_b32 v142, v143, v32, 16
	v_lshrrev_b32_e32 v143, 16, v143
	v_fma_mixhi_f16 v143, v79, v35, 0
	v_cvt_f32_f16_e32 v32, v136
	v_cvt_f32_f16_sdwa v35, v136 dst_sel:DWORD dst_unused:UNUSED_PAD src0_sel:WORD_1
	v_cvt_f32_f16_e32 v136, v137
	v_cvt_f32_f16_sdwa v137, v137 dst_sel:DWORD dst_unused:UNUSED_PAD src0_sel:WORD_1
	global_store_dwordx4 v[148:149], v[140:143], off offset:256
	v_max_f32_e32 v35, 0xc1f00000, v35
	v_max_f32_e32 v136, 0xc1f00000, v136
	v_mul_f32_e32 v136, 0xbfb8aa3b, v136
	v_exp_f32_e32 v142, v136
	v_max_f32_e32 v136, 0xc1f00000, v137
	v_mul_f32_e32 v136, 0xbfb8aa3b, v136
	v_cvt_f32_f16_e32 v137, v138
	v_exp_f32_e32 v143, v136
	v_cvt_f32_f16_sdwa v136, v138 dst_sel:DWORD dst_unused:UNUSED_PAD src0_sel:WORD_1
	v_mul_f32_e32 v35, 0xbfb8aa3b, v35
	v_max_f32_e32 v137, 0xc1f00000, v137
	v_mul_f32_e32 v137, 0xbfb8aa3b, v137
	v_max_f32_e32 v136, 0xc1f00000, v136
	v_mul_f32_e32 v136, 0xbfb8aa3b, v136
	v_exp_f32_e32 v144, v137
	v_cvt_f32_f16_e32 v137, v139
	v_exp_f32_e32 v145, v136
	v_cvt_f32_f16_sdwa v136, v139 dst_sel:DWORD dst_unused:UNUSED_PAD src0_sel:WORD_1
	v_exp_f32_e32 v35, v35
	v_max_f32_e32 v32, 0xc1f00000, v32
	v_mul_f32_e32 v32, 0xbfb8aa3b, v32
	v_exp_f32_e32 v32, v32
	v_max_f32_e32 v137, 0xc1f00000, v137
	v_max_f32_e32 v136, 0xc1f00000, v136
	v_mul_f32_e32 v137, 0xbfb8aa3b, v137
	v_mul_f32_e32 v136, 0xbfb8aa3b, v136
	v_add_f32_e32 v35, 1.0, v35
	v_exp_f32_e32 v146, v137
	v_exp_f32_e32 v147, v136
	v_rcp_f32_e32 v136, v35
	v_add_f32_e32 v35, 1.0, v142
	v_rcp_f32_e32 v137, v35
	v_add_f32_e32 v35, 1.0, v143
	v_add_f32_e32 v32, 1.0, v32
	v_rcp_f32_e32 v138, v35
	v_add_f32_e32 v35, 1.0, v144
	v_rcp_f32_e32 v32, v32
	v_rcp_f32_e32 v139, v35
	v_add_f32_e32 v35, 1.0, v145
	v_rcp_f32_e32 v142, v35
	v_add_f32_e32 v35, 1.0, v146
	v_rcp_f32_e32 v143, v35
	v_mov_b32_e32 v144, v105
	v_mov_b32_e32 v145, v106
	v_pk_mul_f32 v[136:137], v[144:145], v[136:137]
	v_pk_mov_b32 v[144:145], v[106:107], v[100:101] op_sel:[1,0]
	v_add_f32_e32 v35, 1.0, v147
	v_fma_mixlo_f16 v32, v104, v32, 0
	v_cvt_pk_f16_f32 v137, v136, v137
	v_pk_mul_f32 v[138:139], v[144:145], v[138:139]
	v_rcp_f32_e32 v35, v35
	v_pack_b32_f16 v136, v32, v137
	v_cvt_pk_f16_f32 v32, v138, v139
	v_mov_b32_e32 v138, v101
	v_mov_b32_e32 v139, v102
	v_pk_mul_f32 v[138:139], v[138:139], v[142:143]
	v_alignbit_b32 v137, v32, v137, 16
	v_cvt_pk_f16_f32 v139, v138, v139
	v_alignbit_b32 v138, v139, v32, 16
	v_lshrrev_b32_e32 v139, 16, v139
	v_fma_mixhi_f16 v139, v103, v35, 0
	v_cvt_f32_f16_e32 v32, v132
	v_cvt_f32_f16_sdwa v35, v132 dst_sel:DWORD dst_unused:UNUSED_PAD src0_sel:WORD_1
	v_cvt_f32_f16_e32 v132, v133
	v_cvt_f32_f16_sdwa v133, v133 dst_sel:DWORD dst_unused:UNUSED_PAD src0_sel:WORD_1
	v_lshlrev_b64 v[140:141], 11, v[164:165]
	v_lshl_add_u64 v[140:141], s[14:15], 0, v[140:141]
	v_max_f32_e32 v132, 0xc1f00000, v132
	v_lshl_add_u64 v[140:141], v[140:141], 0, v[166:167]
	v_mul_f32_e32 v132, 0xbfb8aa3b, v132
	global_store_dwordx4 v[140:141], v[136:139], off
	v_max_f32_e32 v35, 0xc1f00000, v35
	v_mul_f32_e32 v35, 0xbfb8aa3b, v35
	v_exp_f32_e32 v136, v132
	v_max_f32_e32 v132, 0xc1f00000, v133
	v_mul_f32_e32 v132, 0xbfb8aa3b, v132
	v_cvt_f32_f16_e32 v133, v134
	v_exp_f32_e32 v137, v132
	v_cvt_f32_f16_sdwa v132, v134 dst_sel:DWORD dst_unused:UNUSED_PAD src0_sel:WORD_1
	v_exp_f32_e32 v35, v35
	v_max_f32_e32 v133, 0xc1f00000, v133
	v_mul_f32_e32 v133, 0xbfb8aa3b, v133
	v_max_f32_e32 v132, 0xc1f00000, v132
	v_mul_f32_e32 v132, 0xbfb8aa3b, v132
	v_exp_f32_e32 v138, v133
	v_cvt_f32_f16_e32 v133, v135
	v_exp_f32_e32 v139, v132
	v_cvt_f32_f16_sdwa v132, v135 dst_sel:DWORD dst_unused:UNUSED_PAD src0_sel:WORD_1
	v_max_f32_e32 v32, 0xc1f00000, v32
	v_mul_f32_e32 v32, 0xbfb8aa3b, v32
	v_exp_f32_e32 v32, v32
	v_max_f32_e32 v133, 0xc1f00000, v133
	v_max_f32_e32 v132, 0xc1f00000, v132
	v_mul_f32_e32 v133, 0xbfb8aa3b, v133
	v_mul_f32_e32 v132, 0xbfb8aa3b, v132
	v_add_f32_e32 v35, 1.0, v35
	v_exp_f32_e32 v142, v133
	v_exp_f32_e32 v143, v132
	v_rcp_f32_e32 v132, v35
	v_add_f32_e32 v35, 1.0, v136
	v_rcp_f32_e32 v133, v35
	v_add_f32_e32 v35, 1.0, v137
	v_add_f32_e32 v32, 1.0, v32
	v_rcp_f32_e32 v134, v35
	v_add_f32_e32 v35, 1.0, v138
	v_rcp_f32_e32 v32, v32
	v_rcp_f32_e32 v135, v35
	v_add_f32_e32 v35, 1.0, v139
	v_rcp_f32_e32 v136, v35
	v_add_f32_e32 v35, 1.0, v142
	v_rcp_f32_e32 v137, v35
	v_mov_b32_e32 v138, v73
	v_mov_b32_e32 v139, v74
	v_pk_mul_f32 v[132:133], v[138:139], v[132:133]
	v_pk_mov_b32 v[138:139], v[74:75], v[68:69] op_sel:[1,0]
	v_add_f32_e32 v35, 1.0, v143
	v_fma_mixlo_f16 v32, v72, v32, 0
	v_cvt_pk_f16_f32 v133, v132, v133
	v_pk_mul_f32 v[134:135], v[138:139], v[134:135]
	v_rcp_f32_e32 v35, v35
	v_pack_b32_f16 v132, v32, v133
	v_cvt_pk_f16_f32 v32, v134, v135
	v_mov_b32_e32 v134, v69
	v_mov_b32_e32 v135, v70
	v_pk_mul_f32 v[134:135], v[134:135], v[136:137]
	v_alignbit_b32 v133, v32, v133, 16
	v_cvt_pk_f16_f32 v135, v134, v135
	v_alignbit_b32 v134, v135, v32, 16
	v_lshrrev_b32_e32 v135, 16, v135
	v_fma_mixhi_f16 v135, v71, v35, 0
	global_store_dwordx4 v[140:141], v[132:135], off offset:256
	v_add_u32_e32 v184, 0x80, v34
	s_nop 0
	v_mad_i64_i32 v[132:133], s[12:13], v184, s33, v[168:169]
	v_lshl_add_u64 v[132:133], v[132:133], 0, v[166:167]
	v_add_u32_e32 v174, 0x90, v34
	v_lshl_add_u64 v[134:135], v[132:133], 0, s[16:17]
	v_mad_i64_i32 v[136:137], s[12:13], v174, s33, v[168:169]
	v_add_co_u32_e32 v132, vcc, s1, v132
	v_lshl_add_u64 v[136:137], v[136:137], 0, v[166:167]
	v_add_u32_e32 v172, 0xa0, v34
	v_addc_co_u32_e32 v133, vcc, 0, v133, vcc
	v_lshl_add_u64 v[138:139], v[136:137], 0, s[16:17]
	v_mad_i64_i32 v[140:141], s[12:13], v172, s33, v[168:169]
	v_add_co_u32_e32 v136, vcc, s1, v136
	v_lshl_add_u64 v[140:141], v[140:141], 0, v[166:167]
	v_add_u32_e32 v170, 0xb0, v34
	v_addc_co_u32_e32 v137, vcc, 0, v137, vcc
	v_mad_i64_i32 v[144:145], s[12:13], v170, s33, v[168:169]
	global_load_dwordx4 v[176:179], v[132:133], off offset:2048
	global_load_dwordx4 v[152:155], v[136:137], off offset:2048
	global_load_dwordx4 v[180:183], v[134:135], off offset:256
	global_load_dwordx4 v[148:151], v[138:139], off offset:256
	v_add_co_u32_e32 v132, vcc, s1, v140
	v_lshl_add_u64 v[144:145], v[144:145], 0, v[166:167]
	s_nop 0
	v_addc_co_u32_e32 v133, vcc, 0, v141, vcc
	v_add_co_u32_e32 v134, vcc, s1, v144
	v_lshl_add_u64 v[142:143], v[140:141], 0, s[16:17]
	s_nop 0
	v_addc_co_u32_e32 v135, vcc, 0, v145, vcc
	v_lshl_add_u64 v[168:169], v[144:145], 0, s[16:17]
	global_load_dwordx4 v[144:147], v[132:133], off offset:2048
	global_load_dwordx4 v[136:139], v[134:135], off offset:2048
	s_nop 0
	global_load_dwordx4 v[140:143], v[142:143], off offset:256
	s_nop 0
	global_load_dwordx4 v[132:135], v[168:169], off offset:256
	v_ashrrev_i32_e32 v185, 31, v184
	v_ashrrev_i32_e32 v175, 31, v174
	v_ashrrev_i32_e32 v173, 31, v172
	v_ashrrev_i32_e32 v171, 31, v170
	s_waitcnt vmcnt(0)
	v_cvt_f32_f16_e32 v32, v176
	v_cvt_f32_f16_sdwa v35, v176 dst_sel:DWORD dst_unused:UNUSED_PAD src0_sel:WORD_1
	v_cvt_f32_f16_sdwa v176, v178 dst_sel:DWORD dst_unused:UNUSED_PAD src0_sel:WORD_1
	v_cvt_f32_f16_e32 v161, v177
	v_cvt_f32_f16_sdwa v163, v177 dst_sel:DWORD dst_unused:UNUSED_PAD src0_sel:WORD_1
	v_cvt_f32_f16_e32 v165, v178
	v_max_f32_e32 v176, 0xc1f00000, v176
	v_max_f32_e32 v35, 0xc1f00000, v35
	v_mul_f32_e32 v176, 0xbfb8aa3b, v176
	v_lshlrev_b64 v[168:169], 11, v[184:185]
	v_mul_f32_e32 v35, 0xbfb8aa3b, v35
	v_max_f32_e32 v161, 0xc1f00000, v161
	v_cvt_f32_f16_e32 v177, v179
	v_exp_f32_e32 v184, v176
	v_cvt_f32_f16_sdwa v176, v179 dst_sel:DWORD dst_unused:UNUSED_PAD src0_sel:WORD_1
	v_exp_f32_e32 v35, v35
	v_mul_f32_e32 v161, 0xbfb8aa3b, v161
	v_max_f32_e32 v163, 0xc1f00000, v163
	v_max_f32_e32 v32, 0xc1f00000, v32
	v_exp_f32_e32 v161, v161
	v_mul_f32_e32 v163, 0xbfb8aa3b, v163
	v_max_f32_e32 v165, 0xc1f00000, v165
	v_mul_f32_e32 v32, 0xbfb8aa3b, v32
	v_exp_f32_e32 v163, v163
	v_mul_f32_e32 v165, 0xbfb8aa3b, v165
	v_exp_f32_e32 v32, v32
	v_exp_f32_e32 v165, v165
	v_max_f32_e32 v177, 0xc1f00000, v177
	v_max_f32_e32 v176, 0xc1f00000, v176
	v_mul_f32_e32 v177, 0xbfb8aa3b, v177
	v_mul_f32_e32 v176, 0xbfb8aa3b, v176
	v_add_f32_e32 v35, 1.0, v35
	v_exp_f32_e32 v185, v177
	v_exp_f32_e32 v186, v176
	v_rcp_f32_e32 v176, v35
	v_add_f32_e32 v35, 1.0, v161
	v_rcp_f32_e32 v177, v35
	v_add_f32_e32 v35, 1.0, v163
	v_add_f32_e32 v32, 1.0, v32
	v_rcp_f32_e32 v178, v35
	v_add_f32_e32 v35, 1.0, v165
	v_rcp_f32_e32 v32, v32
	v_rcp_f32_e32 v179, v35
	v_add_f32_e32 v35, 1.0, v184
	v_rcp_f32_e32 v184, v35
	v_add_f32_e32 v35, 1.0, v185
	v_rcp_f32_e32 v185, v35
	v_add_f32_e32 v35, 1.0, v186
	v_mov_b32_e32 v186, v65
	v_mov_b32_e32 v187, v66
	v_pk_mul_f32 v[176:177], v[186:187], v[176:177]
	v_pk_mov_b32 v[186:187], v[66:67], v[60:61] op_sel:[1,0]
	v_fma_mixlo_f16 v32, v64, v32, 0
	v_cvt_pk_f16_f32 v161, v176, v177
	v_pk_mul_f32 v[178:179], v[186:187], v[178:179]
	v_rcp_f32_e32 v35, v35
	v_pack_b32_f16 v176, v32, v161
	v_cvt_pk_f16_f32 v32, v178, v179
	v_mov_b32_e32 v178, v61
	v_mov_b32_e32 v179, v62
	v_pk_mul_f32 v[178:179], v[178:179], v[184:185]
	v_alignbit_b32 v177, v32, v161, 16
	v_cvt_pk_f16_f32 v161, v178, v179
	v_lshrrev_b32_e32 v179, 16, v161
	v_lshl_add_u64 v[168:169], s[14:15], 0, v[168:169]
	v_alignbit_b32 v178, v161, v32, 16
	v_fma_mixhi_f16 v179, v63, v35, 0
	v_lshl_add_u64 v[168:169], v[168:169], 0, v[166:167]
	global_store_dwordx4 v[168:169], v[176:179], off
	v_cvt_f32_f16_sdwa v35, v180 dst_sel:DWORD dst_unused:UNUSED_PAD src0_sel:WORD_1
	v_cvt_f32_f16_e32 v161, v181
	v_cvt_f32_f16_sdwa v176, v182 dst_sel:DWORD dst_unused:UNUSED_PAD src0_sel:WORD_1
	v_cvt_f32_f16_sdwa v163, v181 dst_sel:DWORD dst_unused:UNUSED_PAD src0_sel:WORD_1
	v_cvt_f32_f16_e32 v32, v180
	v_cvt_f32_f16_e32 v165, v182
	v_max_f32_e32 v176, 0xc1f00000, v176
	v_max_f32_e32 v35, 0xc1f00000, v35
	v_mul_f32_e32 v176, 0xbfb8aa3b, v176
	v_mul_f32_e32 v35, 0xbfb8aa3b, v35
	v_max_f32_e32 v161, 0xc1f00000, v161
	v_cvt_f32_f16_e32 v177, v183
	v_exp_f32_e32 v180, v176
	v_cvt_f32_f16_sdwa v176, v183 dst_sel:DWORD dst_unused:UNUSED_PAD src0_sel:WORD_1
	v_exp_f32_e32 v35, v35
	v_mul_f32_e32 v161, 0xbfb8aa3b, v161
	v_max_f32_e32 v163, 0xc1f00000, v163
	v_max_f32_e32 v32, 0xc1f00000, v32
	v_exp_f32_e32 v161, v161
	v_mul_f32_e32 v163, 0xbfb8aa3b, v163
	v_max_f32_e32 v165, 0xc1f00000, v165
	v_mul_f32_e32 v32, 0xbfb8aa3b, v32
	v_exp_f32_e32 v163, v163
	v_mul_f32_e32 v165, 0xbfb8aa3b, v165
	v_exp_f32_e32 v32, v32
	v_exp_f32_e32 v165, v165
	v_max_f32_e32 v177, 0xc1f00000, v177
	v_max_f32_e32 v176, 0xc1f00000, v176
	v_mul_f32_e32 v177, 0xbfb8aa3b, v177
	v_mul_f32_e32 v176, 0xbfb8aa3b, v176
	v_add_f32_e32 v35, 1.0, v35
	v_exp_f32_e32 v181, v177
	v_exp_f32_e32 v182, v176
	v_rcp_f32_e32 v176, v35
	v_add_f32_e32 v35, 1.0, v161
	v_rcp_f32_e32 v177, v35
	v_add_f32_e32 v35, 1.0, v163
	v_add_f32_e32 v32, 1.0, v32
	v_rcp_f32_e32 v178, v35
	v_add_f32_e32 v35, 1.0, v165
	v_rcp_f32_e32 v32, v32
	v_rcp_f32_e32 v179, v35
	v_add_f32_e32 v35, 1.0, v180
	v_rcp_f32_e32 v180, v35
	v_add_f32_e32 v35, 1.0, v181
	v_rcp_f32_e32 v181, v35
	v_add_f32_e32 v35, 1.0, v182
	v_mov_b32_e32 v182, v29
	v_mov_b32_e32 v183, v30
	v_pk_mul_f32 v[176:177], v[182:183], v[176:177]
	v_pk_mov_b32 v[182:183], v[30:31], v[24:25] op_sel:[1,0]
	v_fma_mixlo_f16 v32, v28, v32, 0
	v_cvt_pk_f16_f32 v161, v176, v177
	v_pk_mul_f32 v[178:179], v[182:183], v[178:179]
	v_rcp_f32_e32 v35, v35
	v_pack_b32_f16 v176, v32, v161
	v_cvt_pk_f16_f32 v32, v178, v179
	v_mov_b32_e32 v178, v25
	v_mov_b32_e32 v179, v26
	v_pk_mul_f32 v[178:179], v[178:179], v[180:181]
	v_alignbit_b32 v177, v32, v161, 16
	v_cvt_pk_f16_f32 v161, v178, v179
	v_lshrrev_b32_e32 v179, 16, v161
	v_alignbit_b32 v178, v161, v32, 16
	v_fma_mixhi_f16 v179, v27, v35, 0
	v_cvt_f32_f16_e32 v32, v152
	v_cvt_f32_f16_sdwa v35, v152 dst_sel:DWORD dst_unused:UNUSED_PAD src0_sel:WORD_1
	v_cvt_f32_f16_e32 v152, v153
	v_cvt_f32_f16_sdwa v153, v153 dst_sel:DWORD dst_unused:UNUSED_PAD src0_sel:WORD_1
	global_store_dwordx4 v[168:169], v[176:179], off offset:256
	v_max_f32_e32 v35, 0xc1f00000, v35
	v_max_f32_e32 v152, 0xc1f00000, v152
	v_mul_f32_e32 v152, 0xbfb8aa3b, v152
	v_exp_f32_e32 v161, v152
	v_max_f32_e32 v152, 0xc1f00000, v153
	v_mul_f32_e32 v152, 0xbfb8aa3b, v152
	v_cvt_f32_f16_e32 v153, v154
	v_exp_f32_e32 v163, v152
	v_cvt_f32_f16_sdwa v152, v154 dst_sel:DWORD dst_unused:UNUSED_PAD src0_sel:WORD_1
	v_lshlrev_b64 v[168:169], 11, v[174:175]
	v_max_f32_e32 v153, 0xc1f00000, v153
	v_mul_f32_e32 v153, 0xbfb8aa3b, v153
	v_max_f32_e32 v152, 0xc1f00000, v152
	v_mul_f32_e32 v152, 0xbfb8aa3b, v152
	v_mul_f32_e32 v35, 0xbfb8aa3b, v35
	v_exp_f32_e32 v165, v153
	v_cvt_f32_f16_e32 v153, v155
	v_exp_f32_e32 v174, v152
	v_cvt_f32_f16_sdwa v152, v155 dst_sel:DWORD dst_unused:UNUSED_PAD src0_sel:WORD_1
	v_exp_f32_e32 v35, v35
	v_max_f32_e32 v32, 0xc1f00000, v32
	v_mul_f32_e32 v32, 0xbfb8aa3b, v32
	v_exp_f32_e32 v32, v32
	v_max_f32_e32 v153, 0xc1f00000, v153
	v_max_f32_e32 v152, 0xc1f00000, v152
	v_mul_f32_e32 v153, 0xbfb8aa3b, v153
	v_mul_f32_e32 v152, 0xbfb8aa3b, v152
	v_add_f32_e32 v35, 1.0, v35
	v_exp_f32_e32 v175, v153
	v_exp_f32_e32 v176, v152
	v_rcp_f32_e32 v152, v35
	v_add_f32_e32 v35, 1.0, v161
	v_rcp_f32_e32 v153, v35
	v_add_f32_e32 v35, 1.0, v163
	v_add_f32_e32 v32, 1.0, v32
	v_rcp_f32_e32 v154, v35
	v_add_f32_e32 v35, 1.0, v165
	v_rcp_f32_e32 v32, v32
	v_rcp_f32_e32 v155, v35
	v_add_f32_e32 v35, 1.0, v174
	v_rcp_f32_e32 v174, v35
	v_add_f32_e32 v35, 1.0, v175
	v_rcp_f32_e32 v175, v35
	v_add_f32_e32 v35, 1.0, v176
	v_mov_b32_e32 v176, v57
	v_mov_b32_e32 v177, v58
	v_pk_mul_f32 v[152:153], v[176:177], v[152:153]
	v_pk_mov_b32 v[176:177], v[58:59], v[52:53] op_sel:[1,0]
	v_fma_mixlo_f16 v32, v56, v32, 0
	v_cvt_pk_f16_f32 v153, v152, v153
	v_pk_mul_f32 v[154:155], v[176:177], v[154:155]
	v_rcp_f32_e32 v35, v35
	v_pack_b32_f16 v152, v32, v153
	v_cvt_pk_f16_f32 v32, v154, v155
	v_mov_b32_e32 v154, v53
	v_mov_b32_e32 v155, v54
	v_pk_mul_f32 v[154:155], v[154:155], v[174:175]
	v_alignbit_b32 v153, v32, v153, 16
	v_cvt_pk_f16_f32 v155, v154, v155
	v_alignbit_b32 v154, v155, v32, 16
	v_lshrrev_b32_e32 v155, 16, v155
	v_fma_mixhi_f16 v155, v55, v35, 0
	v_cvt_f32_f16_e32 v32, v148
	v_cvt_f32_f16_sdwa v35, v148 dst_sel:DWORD dst_unused:UNUSED_PAD src0_sel:WORD_1
	v_cvt_f32_f16_e32 v148, v149
	v_cvt_f32_f16_sdwa v149, v149 dst_sel:DWORD dst_unused:UNUSED_PAD src0_sel:WORD_1
	v_lshl_add_u64 v[168:169], s[14:15], 0, v[168:169]
	v_lshl_add_u64 v[168:169], v[168:169], 0, v[166:167]
	v_max_f32_e32 v148, 0xc1f00000, v148
	v_mul_f32_e32 v148, 0xbfb8aa3b, v148
	global_store_dwordx4 v[168:169], v[152:155], off
	v_max_f32_e32 v35, 0xc1f00000, v35
	v_mul_f32_e32 v35, 0xbfb8aa3b, v35
	v_exp_f32_e32 v152, v148
	v_max_f32_e32 v148, 0xc1f00000, v149
	v_mul_f32_e32 v148, 0xbfb8aa3b, v148
	v_cvt_f32_f16_e32 v149, v150
	v_exp_f32_e32 v153, v148
	v_cvt_f32_f16_sdwa v148, v150 dst_sel:DWORD dst_unused:UNUSED_PAD src0_sel:WORD_1
	v_exp_f32_e32 v35, v35
	v_max_f32_e32 v149, 0xc1f00000, v149
	v_mul_f32_e32 v149, 0xbfb8aa3b, v149
	v_max_f32_e32 v148, 0xc1f00000, v148
	v_mul_f32_e32 v148, 0xbfb8aa3b, v148
	v_exp_f32_e32 v154, v149
	v_cvt_f32_f16_e32 v149, v151
	v_exp_f32_e32 v155, v148
	v_cvt_f32_f16_sdwa v148, v151 dst_sel:DWORD dst_unused:UNUSED_PAD src0_sel:WORD_1
	v_max_f32_e32 v32, 0xc1f00000, v32
	v_mul_f32_e32 v32, 0xbfb8aa3b, v32
	v_exp_f32_e32 v32, v32
	v_max_f32_e32 v149, 0xc1f00000, v149
	v_max_f32_e32 v148, 0xc1f00000, v148
	v_mul_f32_e32 v149, 0xbfb8aa3b, v149
	v_mul_f32_e32 v148, 0xbfb8aa3b, v148
	v_add_f32_e32 v35, 1.0, v35
	v_exp_f32_e32 v161, v149
	v_exp_f32_e32 v163, v148
	v_rcp_f32_e32 v148, v35
	v_add_f32_e32 v35, 1.0, v152
	v_rcp_f32_e32 v149, v35
	v_add_f32_e32 v35, 1.0, v153
	v_add_f32_e32 v32, 1.0, v32
	v_rcp_f32_e32 v150, v35
	v_add_f32_e32 v35, 1.0, v154
	v_rcp_f32_e32 v32, v32
	v_rcp_f32_e32 v151, v35
	v_add_f32_e32 v35, 1.0, v155
	v_rcp_f32_e32 v152, v35
	v_add_f32_e32 v35, 1.0, v161
	v_rcp_f32_e32 v153, v35
	v_mov_b32_e32 v154, v21
	v_mov_b32_e32 v155, v22
	v_pk_mul_f32 v[148:149], v[154:155], v[148:149]
	v_pk_mov_b32 v[154:155], v[22:23], v[16:17] op_sel:[1,0]
	v_add_f32_e32 v35, 1.0, v163
	v_fma_mixlo_f16 v32, v20, v32, 0
	v_cvt_pk_f16_f32 v149, v148, v149
	v_pk_mul_f32 v[150:151], v[154:155], v[150:151]
	v_rcp_f32_e32 v35, v35
	v_pack_b32_f16 v148, v32, v149
	v_cvt_pk_f16_f32 v32, v150, v151
	v_mov_b32_e32 v150, v17
	v_mov_b32_e32 v151, v18
	v_pk_mul_f32 v[150:151], v[150:151], v[152:153]
	v_alignbit_b32 v149, v32, v149, 16
	v_cvt_pk_f16_f32 v151, v150, v151
	v_alignbit_b32 v150, v151, v32, 16
	v_lshrrev_b32_e32 v151, 16, v151
	v_fma_mixhi_f16 v151, v19, v35, 0
	v_cvt_f32_f16_e32 v32, v144
	v_cvt_f32_f16_sdwa v35, v144 dst_sel:DWORD dst_unused:UNUSED_PAD src0_sel:WORD_1
	v_cvt_f32_f16_e32 v144, v145
	v_cvt_f32_f16_sdwa v145, v145 dst_sel:DWORD dst_unused:UNUSED_PAD src0_sel:WORD_1
	global_store_dwordx4 v[168:169], v[148:151], off offset:256
	v_max_f32_e32 v35, 0xc1f00000, v35
	v_max_f32_e32 v144, 0xc1f00000, v144
	v_mul_f32_e32 v144, 0xbfb8aa3b, v144
	v_exp_f32_e32 v150, v144
	v_max_f32_e32 v144, 0xc1f00000, v145
	v_mul_f32_e32 v144, 0xbfb8aa3b, v144
	v_cvt_f32_f16_e32 v145, v146
	v_exp_f32_e32 v151, v144
	v_cvt_f32_f16_sdwa v144, v146 dst_sel:DWORD dst_unused:UNUSED_PAD src0_sel:WORD_1
	v_mul_f32_e32 v35, 0xbfb8aa3b, v35
	v_max_f32_e32 v145, 0xc1f00000, v145
	v_mul_f32_e32 v145, 0xbfb8aa3b, v145
	v_max_f32_e32 v144, 0xc1f00000, v144
	v_mul_f32_e32 v144, 0xbfb8aa3b, v144
	v_exp_f32_e32 v152, v145
	v_cvt_f32_f16_e32 v145, v147
	v_exp_f32_e32 v153, v144
	v_cvt_f32_f16_sdwa v144, v147 dst_sel:DWORD dst_unused:UNUSED_PAD src0_sel:WORD_1
	v_exp_f32_e32 v35, v35
	v_max_f32_e32 v32, 0xc1f00000, v32
	v_mul_f32_e32 v32, 0xbfb8aa3b, v32
	v_exp_f32_e32 v32, v32
	v_max_f32_e32 v145, 0xc1f00000, v145
	v_max_f32_e32 v144, 0xc1f00000, v144
	v_mul_f32_e32 v145, 0xbfb8aa3b, v145
	v_mul_f32_e32 v144, 0xbfb8aa3b, v144
	v_add_f32_e32 v35, 1.0, v35
	v_exp_f32_e32 v154, v145
	v_exp_f32_e32 v155, v144
	v_rcp_f32_e32 v144, v35
	v_add_f32_e32 v35, 1.0, v150
	v_rcp_f32_e32 v145, v35
	v_add_f32_e32 v35, 1.0, v151
	v_add_f32_e32 v32, 1.0, v32
	v_rcp_f32_e32 v146, v35
	v_add_f32_e32 v35, 1.0, v152
	v_rcp_f32_e32 v32, v32
	v_rcp_f32_e32 v147, v35
	v_add_f32_e32 v35, 1.0, v153
	v_rcp_f32_e32 v150, v35
	v_add_f32_e32 v35, 1.0, v154
	v_rcp_f32_e32 v151, v35
	v_mov_b32_e32 v152, v49
	v_mov_b32_e32 v153, v50
	v_pk_mul_f32 v[144:145], v[152:153], v[144:145]
	v_pk_mov_b32 v[152:153], v[50:51], v[44:45] op_sel:[1,0]
	v_add_f32_e32 v35, 1.0, v155
	v_fma_mixlo_f16 v32, v48, v32, 0
	v_cvt_pk_f16_f32 v145, v144, v145
	v_pk_mul_f32 v[146:147], v[152:153], v[146:147]
	v_rcp_f32_e32 v35, v35
	v_pack_b32_f16 v144, v32, v145
	v_cvt_pk_f16_f32 v32, v146, v147
	v_mov_b32_e32 v146, v45
	v_mov_b32_e32 v147, v46
	v_pk_mul_f32 v[146:147], v[146:147], v[150:151]
	v_alignbit_b32 v145, v32, v145, 16
	v_cvt_pk_f16_f32 v147, v146, v147
	v_alignbit_b32 v146, v147, v32, 16
	v_lshrrev_b32_e32 v147, 16, v147
	v_fma_mixhi_f16 v147, v47, v35, 0
	v_cvt_f32_f16_e32 v32, v140
	v_cvt_f32_f16_sdwa v35, v140 dst_sel:DWORD dst_unused:UNUSED_PAD src0_sel:WORD_1
	v_cvt_f32_f16_e32 v140, v141
	v_cvt_f32_f16_sdwa v141, v141 dst_sel:DWORD dst_unused:UNUSED_PAD src0_sel:WORD_1
	v_lshlrev_b64 v[148:149], 11, v[172:173]
	v_lshl_add_u64 v[148:149], s[14:15], 0, v[148:149]
	v_max_f32_e32 v140, 0xc1f00000, v140
	v_lshl_add_u64 v[148:149], v[148:149], 0, v[166:167]
	v_mul_f32_e32 v140, 0xbfb8aa3b, v140
	global_store_dwordx4 v[148:149], v[144:147], off
	v_max_f32_e32 v35, 0xc1f00000, v35
	v_mul_f32_e32 v35, 0xbfb8aa3b, v35
	v_exp_f32_e32 v144, v140
	v_max_f32_e32 v140, 0xc1f00000, v141
	v_mul_f32_e32 v140, 0xbfb8aa3b, v140
	v_cvt_f32_f16_e32 v141, v142
	v_exp_f32_e32 v145, v140
	v_cvt_f32_f16_sdwa v140, v142 dst_sel:DWORD dst_unused:UNUSED_PAD src0_sel:WORD_1
	v_exp_f32_e32 v35, v35
	v_max_f32_e32 v141, 0xc1f00000, v141
	v_mul_f32_e32 v141, 0xbfb8aa3b, v141
	v_max_f32_e32 v140, 0xc1f00000, v140
	v_mul_f32_e32 v140, 0xbfb8aa3b, v140
	v_exp_f32_e32 v146, v141
	v_cvt_f32_f16_e32 v141, v143
	v_exp_f32_e32 v147, v140
	v_cvt_f32_f16_sdwa v140, v143 dst_sel:DWORD dst_unused:UNUSED_PAD src0_sel:WORD_1
	v_max_f32_e32 v32, 0xc1f00000, v32
	v_mul_f32_e32 v32, 0xbfb8aa3b, v32
	v_exp_f32_e32 v32, v32
	v_max_f32_e32 v141, 0xc1f00000, v141
	v_max_f32_e32 v140, 0xc1f00000, v140
	v_mul_f32_e32 v141, 0xbfb8aa3b, v141
	v_mul_f32_e32 v140, 0xbfb8aa3b, v140
	v_add_f32_e32 v35, 1.0, v35
	v_exp_f32_e32 v150, v141
	v_exp_f32_e32 v151, v140
	v_rcp_f32_e32 v140, v35
	v_add_f32_e32 v35, 1.0, v144
	v_rcp_f32_e32 v141, v35
	v_add_f32_e32 v35, 1.0, v145
	v_add_f32_e32 v32, 1.0, v32
	v_rcp_f32_e32 v142, v35
	v_add_f32_e32 v35, 1.0, v146
	v_rcp_f32_e32 v32, v32
	v_rcp_f32_e32 v143, v35
	v_add_f32_e32 v35, 1.0, v147
	v_rcp_f32_e32 v144, v35
	v_add_f32_e32 v35, 1.0, v150
	v_rcp_f32_e32 v145, v35
	v_mov_b32_e32 v146, v13
	v_mov_b32_e32 v147, v14
	v_pk_mul_f32 v[140:141], v[146:147], v[140:141]
	v_pk_mov_b32 v[146:147], v[14:15], v[8:9] op_sel:[1,0]
	v_add_f32_e32 v35, 1.0, v151
	v_fma_mixlo_f16 v32, v12, v32, 0
	v_cvt_pk_f16_f32 v141, v140, v141
	v_pk_mul_f32 v[142:143], v[146:147], v[142:143]
	v_rcp_f32_e32 v35, v35
	v_pack_b32_f16 v140, v32, v141
	v_cvt_pk_f16_f32 v32, v142, v143
	v_mov_b32_e32 v142, v9
	v_mov_b32_e32 v143, v10
	v_pk_mul_f32 v[142:143], v[142:143], v[144:145]
	v_alignbit_b32 v141, v32, v141, 16
	v_cvt_pk_f16_f32 v143, v142, v143
	v_alignbit_b32 v142, v143, v32, 16
	v_lshrrev_b32_e32 v143, 16, v143
	v_fma_mixhi_f16 v143, v11, v35, 0
	v_cvt_f32_f16_e32 v32, v136
	v_cvt_f32_f16_sdwa v35, v136 dst_sel:DWORD dst_unused:UNUSED_PAD src0_sel:WORD_1
	v_cvt_f32_f16_e32 v136, v137
	v_cvt_f32_f16_sdwa v137, v137 dst_sel:DWORD dst_unused:UNUSED_PAD src0_sel:WORD_1
	global_store_dwordx4 v[148:149], v[140:143], off offset:256
	v_max_f32_e32 v35, 0xc1f00000, v35
	v_max_f32_e32 v136, 0xc1f00000, v136
	v_mul_f32_e32 v136, 0xbfb8aa3b, v136
	v_exp_f32_e32 v142, v136
	v_max_f32_e32 v136, 0xc1f00000, v137
	v_mul_f32_e32 v136, 0xbfb8aa3b, v136
	v_cvt_f32_f16_e32 v137, v138
	v_exp_f32_e32 v143, v136
	v_cvt_f32_f16_sdwa v136, v138 dst_sel:DWORD dst_unused:UNUSED_PAD src0_sel:WORD_1
	v_mul_f32_e32 v35, 0xbfb8aa3b, v35
	v_max_f32_e32 v137, 0xc1f00000, v137
	v_mul_f32_e32 v137, 0xbfb8aa3b, v137
	v_max_f32_e32 v136, 0xc1f00000, v136
	v_mul_f32_e32 v136, 0xbfb8aa3b, v136
	v_exp_f32_e32 v144, v137
	v_cvt_f32_f16_e32 v137, v139
	v_exp_f32_e32 v145, v136
	v_cvt_f32_f16_sdwa v136, v139 dst_sel:DWORD dst_unused:UNUSED_PAD src0_sel:WORD_1
	v_exp_f32_e32 v35, v35
	v_max_f32_e32 v32, 0xc1f00000, v32
	v_mul_f32_e32 v32, 0xbfb8aa3b, v32
	v_exp_f32_e32 v32, v32
	v_max_f32_e32 v137, 0xc1f00000, v137
	v_max_f32_e32 v136, 0xc1f00000, v136
	v_mul_f32_e32 v137, 0xbfb8aa3b, v137
	v_mul_f32_e32 v136, 0xbfb8aa3b, v136
	v_add_f32_e32 v35, 1.0, v35
	v_exp_f32_e32 v146, v137
	v_exp_f32_e32 v147, v136
	v_rcp_f32_e32 v136, v35
	v_add_f32_e32 v35, 1.0, v142
	v_rcp_f32_e32 v137, v35
	v_add_f32_e32 v35, 1.0, v143
	v_add_f32_e32 v32, 1.0, v32
	v_rcp_f32_e32 v138, v35
	v_add_f32_e32 v35, 1.0, v144
	v_rcp_f32_e32 v32, v32
	v_rcp_f32_e32 v139, v35
	v_add_f32_e32 v35, 1.0, v145
	v_rcp_f32_e32 v142, v35
	v_add_f32_e32 v35, 1.0, v146
	v_rcp_f32_e32 v143, v35
	v_mov_b32_e32 v144, v41
	v_mov_b32_e32 v145, v42
	v_pk_mul_f32 v[136:137], v[144:145], v[136:137]
	v_pk_mov_b32 v[144:145], v[42:43], v[36:37] op_sel:[1,0]
	v_add_f32_e32 v35, 1.0, v147
	v_fma_mixlo_f16 v32, v40, v32, 0
	v_cvt_pk_f16_f32 v137, v136, v137
	v_pk_mul_f32 v[138:139], v[144:145], v[138:139]
	v_rcp_f32_e32 v35, v35
	v_pack_b32_f16 v136, v32, v137
	v_cvt_pk_f16_f32 v32, v138, v139
	v_mov_b32_e32 v138, v37
	v_mov_b32_e32 v139, v38
	v_pk_mul_f32 v[138:139], v[138:139], v[142:143]
	v_alignbit_b32 v137, v32, v137, 16
	v_cvt_pk_f16_f32 v139, v138, v139
	v_alignbit_b32 v138, v139, v32, 16
	v_lshrrev_b32_e32 v139, 16, v139
	v_fma_mixhi_f16 v139, v39, v35, 0
	v_cvt_f32_f16_e32 v32, v132
	v_cvt_f32_f16_sdwa v35, v132 dst_sel:DWORD dst_unused:UNUSED_PAD src0_sel:WORD_1
	v_cvt_f32_f16_e32 v132, v133
	v_cvt_f32_f16_sdwa v133, v133 dst_sel:DWORD dst_unused:UNUSED_PAD src0_sel:WORD_1
	v_lshlrev_b64 v[140:141], 11, v[170:171]
	v_lshl_add_u64 v[140:141], s[14:15], 0, v[140:141]
	v_max_f32_e32 v132, 0xc1f00000, v132
	v_lshl_add_u64 v[140:141], v[140:141], 0, v[166:167]
	v_mul_f32_e32 v132, 0xbfb8aa3b, v132
	global_store_dwordx4 v[140:141], v[136:139], off
	v_max_f32_e32 v35, 0xc1f00000, v35
	v_mul_f32_e32 v35, 0xbfb8aa3b, v35
	v_exp_f32_e32 v136, v132
	v_max_f32_e32 v132, 0xc1f00000, v133
	v_mul_f32_e32 v132, 0xbfb8aa3b, v132
	v_cvt_f32_f16_e32 v133, v134
	v_exp_f32_e32 v137, v132
	v_cvt_f32_f16_sdwa v132, v134 dst_sel:DWORD dst_unused:UNUSED_PAD src0_sel:WORD_1
	v_exp_f32_e32 v35, v35
	v_max_f32_e32 v133, 0xc1f00000, v133
	v_mul_f32_e32 v133, 0xbfb8aa3b, v133
	v_max_f32_e32 v132, 0xc1f00000, v132
	v_mul_f32_e32 v132, 0xbfb8aa3b, v132
	v_exp_f32_e32 v138, v133
	v_cvt_f32_f16_e32 v133, v135
	v_exp_f32_e32 v139, v132
	v_cvt_f32_f16_sdwa v132, v135 dst_sel:DWORD dst_unused:UNUSED_PAD src0_sel:WORD_1
	v_max_f32_e32 v32, 0xc1f00000, v32
	v_mul_f32_e32 v32, 0xbfb8aa3b, v32
	v_exp_f32_e32 v32, v32
	v_max_f32_e32 v133, 0xc1f00000, v133
	v_max_f32_e32 v132, 0xc1f00000, v132
	v_mul_f32_e32 v133, 0xbfb8aa3b, v133
	v_mul_f32_e32 v132, 0xbfb8aa3b, v132
	v_add_f32_e32 v35, 1.0, v35
	v_exp_f32_e32 v142, v133
	v_exp_f32_e32 v143, v132
	v_rcp_f32_e32 v132, v35
	v_add_f32_e32 v35, 1.0, v136
	v_rcp_f32_e32 v133, v35
	v_add_f32_e32 v35, 1.0, v137
	v_add_f32_e32 v32, 1.0, v32
	v_rcp_f32_e32 v134, v35
	v_add_f32_e32 v35, 1.0, v138
	v_rcp_f32_e32 v32, v32
	v_rcp_f32_e32 v135, v35
	v_add_f32_e32 v35, 1.0, v139
	v_rcp_f32_e32 v136, v35
	v_add_f32_e32 v35, 1.0, v142
	v_rcp_f32_e32 v137, v35
	v_mov_b32_e32 v138, v5
	v_mov_b32_e32 v139, v6
	v_pk_mul_f32 v[132:133], v[138:139], v[132:133]
	v_pk_mov_b32 v[138:139], v[6:7], v[0:1] op_sel:[1,0]
	v_add_f32_e32 v35, 1.0, v143
	v_fma_mixlo_f16 v32, v4, v32, 0
	v_cvt_pk_f16_f32 v133, v132, v133
	v_pk_mul_f32 v[134:135], v[138:139], v[134:135]
	v_rcp_f32_e32 v35, v35
	v_pack_b32_f16 v132, v32, v133
	v_cvt_pk_f16_f32 v32, v134, v135
	v_mov_b32_e32 v134, v1
	v_mov_b32_e32 v135, v2
	v_pk_mul_f32 v[134:135], v[134:135], v[136:137]
	v_alignbit_b32 v133, v32, v133, 16
	v_cvt_pk_f16_f32 v135, v134, v135
	v_alignbit_b32 v134, v135, v32, 16
	v_lshrrev_b32_e32 v135, 16, v135
	v_fma_mixhi_f16 v135, v3, v35, 0
	global_store_dwordx4 v[140:141], v[132:135], off offset:256
	s_cbranch_execnz .LBB0_944

.LBB0_958:
	s_add_u32 s12, s10, 0x100
	s_addc_u32 s13, s11, 0
	s_add_i32 s38, 0, 0x10000
	v_add_u32_e32 v142, s38, v196
	ds_read_b128 v[122:125], v142
	ds_read_b128 v[138:141], v142 offset:2048
	ds_read_b128 v[130:133], v142 offset:1024
	ds_read_b128 v[142:145], v142 offset:3072
	s_cmp_eq_u32 s37, 12
	s_cselect_b32 s17, s7, s13
	s_cselect_b32 s16, s6, s12
	s_cselect_b32 s15, s9, s36
	s_cselect_b32 s14, s8, s35
	v_lshl_add_u64 v[230:231], s[10:11], 0, v[188:189]
	s_add_i32 m0, s21, 0xc000
	ds_read_b128 v[146:149], v198
	ds_read_b128 v[192:195], v198 offset:2048
	ds_read_b128 v[204:207], v198 offset:4096
	ds_read_b128 v[212:215], v198 offset:6144
	ds_read_b128 v[150:153], v198 offset:1024
	ds_read_b128 v[200:203], v198 offset:3072
	ds_read_b128 v[208:211], v198 offset:5120
	ds_read_b128 v[216:219], v198 offset:7168
	global_load_lds_dwordx4 v[230:231], off
	v_lshl_add_u64 v[230:231], s[10:11], 0, v[190:191]
	s_add_i32 m0, s21, 0xe000
	s_nop 0
	global_load_lds_dwordx4 v[230:231], off
	s_waitcnt lgkmcnt(8)
	s_waitcnt vmcnt(10)
	s_barrier
	s_waitcnt lgkmcnt(7)
	s_setprio 1
	v_mfma_f32_16x16x32_f16 v[134:137], v[122:125], v[146:149], v[134:137]
	v_mfma_f32_16x16x32_f16 v[126:129], v[138:141], v[146:149], v[126:129]
	s_waitcnt lgkmcnt(6)
	v_mfma_f32_16x16x32_f16 v[110:113], v[122:125], v[192:195], v[110:113]
	v_mfma_f32_16x16x32_f16 v[106:109], v[138:141], v[192:195], v[106:109]
	s_waitcnt lgkmcnt(5)
	v_mfma_f32_16x16x32_f16 v[94:97], v[122:125], v[204:207], v[94:97]
	v_mfma_f32_16x16x32_f16 v[90:93], v[138:141], v[204:207], v[90:93]
	s_waitcnt lgkmcnt(4)
	v_mfma_f32_16x16x32_f16 v[78:81], v[122:125], v[212:215], v[78:81]
	v_mfma_f32_16x16x32_f16 v[74:77], v[138:141], v[212:215], v[74:77]
	s_waitcnt lgkmcnt(3)
	v_mfma_f32_16x16x32_f16 v[134:137], v[130:133], v[150:153], v[134:137]
	v_mfma_f32_16x16x32_f16 v[126:129], v[142:145], v[150:153], v[126:129]
	s_waitcnt lgkmcnt(2)
	v_mfma_f32_16x16x32_f16 v[110:113], v[130:133], v[200:203], v[110:113]
	v_mfma_f32_16x16x32_f16 v[106:109], v[142:145], v[200:203], v[106:109]
	s_waitcnt lgkmcnt(1)
	v_mfma_f32_16x16x32_f16 v[94:97], v[130:133], v[208:211], v[94:97]
	v_mfma_f32_16x16x32_f16 v[90:93], v[142:145], v[208:211], v[90:93]
	s_waitcnt lgkmcnt(0)
	v_mfma_f32_16x16x32_f16 v[78:81], v[130:133], v[216:219], v[78:81]
	v_mfma_f32_16x16x32_f16 v[74:77], v[142:145], v[216:219], v[74:77]
	s_setprio 0
	s_barrier
	s_add_i32 s39, 0, 0x14000
	s_add_i32 s10, s38, s20
	v_add_u32_e32 v199, s39, v196
	v_lshl_add_u64 v[246:247], s[14:15], 0, v[32:33]
	s_mov_b32 m0, s10
	ds_read_b128 v[230:233], v199
	ds_read_b128 v[238:241], v199 offset:2048
	ds_read_b128 v[234:237], v199 offset:1024
	ds_read_b128 v[242:245], v199 offset:3072
	global_load_lds_dwordx4 v[246:247], off
	v_lshl_add_u64 v[248:249], s[14:15], 0, v[154:155]
	s_add_i32 m0, s10, 0x2000
	s_nop 0
	global_load_lds_dwordx4 v[248:249], off
	s_waitcnt vmcnt(10)
	s_barrier
	s_waitcnt lgkmcnt(2)
	s_setprio 1
	v_mfma_f32_16x16x32_f16 v[118:121], v[230:233], v[146:149], v[118:121]
	v_mfma_f32_16x16x32_f16 v[114:117], v[238:241], v[146:149], v[114:117]
	v_mfma_f32_16x16x32_f16 v[102:105], v[230:233], v[192:195], v[102:105]
	v_mfma_f32_16x16x32_f16 v[98:101], v[238:241], v[192:195], v[98:101]
	v_mfma_f32_16x16x32_f16 v[86:89], v[230:233], v[204:207], v[86:89]
	v_mfma_f32_16x16x32_f16 v[82:85], v[238:241], v[204:207], v[82:85]
	v_mfma_f32_16x16x32_f16 v[70:73], v[230:233], v[212:215], v[70:73]
	v_mfma_f32_16x16x32_f16 v[66:69], v[238:241], v[212:215], v[66:69]
	s_waitcnt lgkmcnt(0)
	v_mfma_f32_16x16x32_f16 v[118:121], v[234:237], v[150:153], v[118:121]
	v_mfma_f32_16x16x32_f16 v[114:117], v[242:245], v[150:153], v[114:117]
	v_mfma_f32_16x16x32_f16 v[102:105], v[234:237], v[200:203], v[102:105]
	v_mfma_f32_16x16x32_f16 v[98:101], v[242:245], v[200:203], v[98:101]
	v_mfma_f32_16x16x32_f16 v[86:89], v[234:237], v[208:211], v[86:89]
	v_mfma_f32_16x16x32_f16 v[82:85], v[242:245], v[208:211], v[82:85]
	v_mfma_f32_16x16x32_f16 v[70:73], v[234:237], v[216:219], v[70:73]
	v_mfma_f32_16x16x32_f16 v[66:69], v[242:245], v[216:219], v[66:69]
	s_setprio 0
	s_mov_b32 m0, s21
	v_lshl_add_u64 v[228:229], s[16:17], 0, v[32:33]
	s_barrier
	ds_read_b128 v[146:149], v198 offset:16384
	ds_read_b128 v[192:195], v198 offset:18432
	ds_read_b128 v[204:207], v198 offset:20480
	ds_read_b128 v[212:215], v198 offset:22528
	ds_read_b128 v[150:153], v198 offset:17408
	ds_read_b128 v[200:203], v198 offset:19456
	ds_read_b128 v[208:211], v198 offset:21504
	ds_read_b128 v[216:219], v198 offset:23552
	global_load_lds_dwordx4 v[228:229], off
	v_lshl_add_u64 v[222:223], s[16:17], 0, v[154:155]
	s_mov_b32 m0, s22
	s_nop 0
	global_load_lds_dwordx4 v[222:223], off
	s_barrier
	s_waitcnt lgkmcnt(7)
	s_setprio 1
	v_mfma_f32_16x16x32_f16 v[62:65], v[122:125], v[146:149], v[62:65]
	v_mfma_f32_16x16x32_f16 v[58:61], v[138:141], v[146:149], v[58:61]
	s_waitcnt lgkmcnt(6)
	v_mfma_f32_16x16x32_f16 v[46:49], v[122:125], v[192:195], v[46:49]
	v_mfma_f32_16x16x32_f16 v[42:45], v[138:141], v[192:195], v[42:45]
	s_waitcnt lgkmcnt(5)
	v_mfma_f32_16x16x32_f16 v[28:31], v[122:125], v[204:207], v[28:31]
	v_mfma_f32_16x16x32_f16 v[24:27], v[138:141], v[204:207], v[24:27]
	s_waitcnt lgkmcnt(4)
	v_mfma_f32_16x16x32_f16 v[12:15], v[122:125], v[212:215], v[12:15]
	v_mfma_f32_16x16x32_f16 v[8:11], v[138:141], v[212:215], v[8:11]
	s_waitcnt lgkmcnt(3)
	v_mfma_f32_16x16x32_f16 v[62:65], v[130:133], v[150:153], v[62:65]
	v_mfma_f32_16x16x32_f16 v[58:61], v[142:145], v[150:153], v[58:61]
	s_waitcnt lgkmcnt(2)
	v_mfma_f32_16x16x32_f16 v[46:49], v[130:133], v[200:203], v[46:49]
	v_mfma_f32_16x16x32_f16 v[42:45], v[142:145], v[200:203], v[42:45]
	s_waitcnt lgkmcnt(1)
	v_mfma_f32_16x16x32_f16 v[28:31], v[130:133], v[208:211], v[28:31]
	v_mfma_f32_16x16x32_f16 v[24:27], v[142:145], v[208:211], v[24:27]
	s_waitcnt lgkmcnt(0)
	v_mfma_f32_16x16x32_f16 v[12:15], v[130:133], v[216:219], v[12:15]
	v_mfma_f32_16x16x32_f16 v[8:11], v[142:145], v[216:219], v[8:11]
	s_setprio 0
	s_barrier
	s_add_u32 s10, s14, 0x40000
	s_addc_u32 s11, s15, 0
	s_add_i32 s38, s39, s20
	v_lshl_add_u64 v[122:123], s[10:11], 0, v[32:33]
	s_mov_b32 m0, s38
	s_nop 0
	global_load_lds_dwordx4 v[122:123], off
	v_lshl_add_u64 v[122:123], s[10:11], 0, v[154:155]
	s_add_i32 m0, s38, 0x2000
	s_nop 0
	global_load_lds_dwordx4 v[122:123], off
	s_waitcnt vmcnt(10)
	s_barrier
	s_setprio 1
	v_mfma_f32_16x16x32_f16 v[54:57], v[230:233], v[146:149], v[54:57]
	v_mfma_f32_16x16x32_f16 v[50:53], v[238:241], v[146:149], v[50:53]
	v_mfma_f32_16x16x32_f16 v[38:41], v[230:233], v[192:195], v[38:41]
	v_mfma_f32_16x16x32_f16 v[34:37], v[238:241], v[192:195], v[34:37]
	v_mfma_f32_16x16x32_f16 v[20:23], v[230:233], v[204:207], v[20:23]
	v_mfma_f32_16x16x32_f16 v[16:19], v[238:241], v[204:207], v[16:19]
	v_mfma_f32_16x16x32_f16 v[4:7], v[230:233], v[212:215], v[4:7]
	v_mfma_f32_16x16x32_f16 v[0:3], v[238:241], v[212:215], v[0:3]
	v_mfma_f32_16x16x32_f16 v[54:57], v[234:237], v[150:153], v[54:57]
	v_mfma_f32_16x16x32_f16 v[50:53], v[242:245], v[150:153], v[50:53]
	v_mfma_f32_16x16x32_f16 v[38:41], v[234:237], v[200:203], v[38:41]
	v_mfma_f32_16x16x32_f16 v[34:37], v[242:245], v[200:203], v[34:37]
	v_mfma_f32_16x16x32_f16 v[20:23], v[234:237], v[208:211], v[20:23]
	v_mfma_f32_16x16x32_f16 v[16:19], v[242:245], v[208:211], v[16:19]
	v_mfma_f32_16x16x32_f16 v[4:7], v[234:237], v[216:219], v[4:7]
	v_mfma_f32_16x16x32_f16 v[0:3], v[242:245], v[216:219], v[0:3]
	s_setprio 0
	s_add_i32 s38, 0, 0x18000
	v_add_u32_e32 v142, s38, v196
	s_barrier
	ds_read_b128 v[122:125], v142
	ds_read_b128 v[138:141], v142 offset:2048
	ds_read_b128 v[130:133], v142 offset:1024
	ds_read_b128 v[142:145], v142 offset:3072
	s_add_u32 s10, s16, 0x40000
	s_addc_u32 s11, s17, 0
	s_mov_b32 m0, s23
	v_lshl_add_u64 v[230:231], s[10:11], 0, v[32:33]
	ds_read_b128 v[146:149], v198 offset:32768
	ds_read_b128 v[192:195], v198 offset:34816
	ds_read_b128 v[204:207], v198 offset:36864
	ds_read_b128 v[212:215], v198 offset:38912
	ds_read_b128 v[150:153], v198 offset:33792
	ds_read_b128 v[200:203], v198 offset:35840
	ds_read_b128 v[208:211], v198 offset:37888
	ds_read_b128 v[216:219], v198 offset:39936
	global_load_lds_dwordx4 v[230:231], off
	v_lshl_add_u64 v[230:231], s[10:11], 0, v[154:155]
	s_mov_b32 m0, s24
	s_nop 0
	global_load_lds_dwordx4 v[230:231], off
	s_waitcnt lgkmcnt(8)
	s_waitcnt vmcnt(10)
	s_barrier
	s_waitcnt lgkmcnt(7)
	s_setprio 1
	v_mfma_f32_16x16x32_f16 v[134:137], v[122:125], v[146:149], v[134:137]
	v_mfma_f32_16x16x32_f16 v[126:129], v[138:141], v[146:149], v[126:129]
	s_waitcnt lgkmcnt(6)
	v_mfma_f32_16x16x32_f16 v[110:113], v[122:125], v[192:195], v[110:113]
	v_mfma_f32_16x16x32_f16 v[106:109], v[138:141], v[192:195], v[106:109]
	s_waitcnt lgkmcnt(5)
	v_mfma_f32_16x16x32_f16 v[94:97], v[122:125], v[204:207], v[94:97]
	v_mfma_f32_16x16x32_f16 v[90:93], v[138:141], v[204:207], v[90:93]
	s_waitcnt lgkmcnt(4)
	v_mfma_f32_16x16x32_f16 v[78:81], v[122:125], v[212:215], v[78:81]
	v_mfma_f32_16x16x32_f16 v[74:77], v[138:141], v[212:215], v[74:77]
	s_waitcnt lgkmcnt(3)
	v_mfma_f32_16x16x32_f16 v[134:137], v[130:133], v[150:153], v[134:137]
	v_mfma_f32_16x16x32_f16 v[126:129], v[142:145], v[150:153], v[126:129]
	s_waitcnt lgkmcnt(2)
	v_mfma_f32_16x16x32_f16 v[110:113], v[130:133], v[200:203], v[110:113]
	v_mfma_f32_16x16x32_f16 v[106:109], v[142:145], v[200:203], v[106:109]
	s_waitcnt lgkmcnt(1)
	v_mfma_f32_16x16x32_f16 v[94:97], v[130:133], v[208:211], v[94:97]
	v_mfma_f32_16x16x32_f16 v[90:93], v[142:145], v[208:211], v[90:93]
	s_waitcnt lgkmcnt(0)
	v_mfma_f32_16x16x32_f16 v[78:81], v[130:133], v[216:219], v[78:81]
	v_mfma_f32_16x16x32_f16 v[74:77], v[142:145], v[216:219], v[74:77]
	s_setprio 0
	s_barrier
	s_add_i32 s16, 0, 0x1c000
	s_add_i32 s10, s38, s20
	v_add_u32_e32 v199, s16, v196
	v_lshl_add_u64 v[246:247], v[246:247], 0, s[84:85]
	s_mov_b32 m0, s10
	ds_read_b128 v[230:233], v199
	ds_read_b128 v[238:241], v199 offset:2048
	ds_read_b128 v[234:237], v199 offset:1024
	ds_read_b128 v[242:245], v199 offset:3072
	global_load_lds_dwordx4 v[246:247], off
	v_lshl_add_u64 v[246:247], v[248:249], 0, s[84:85]
	s_add_i32 m0, s10, 0x2000
	s_nop 0
	global_load_lds_dwordx4 v[246:247], off
	s_waitcnt vmcnt(10)
	s_barrier
	s_waitcnt lgkmcnt(2)
	s_setprio 1
	v_mfma_f32_16x16x32_f16 v[118:121], v[230:233], v[146:149], v[118:121]
	v_mfma_f32_16x16x32_f16 v[114:117], v[238:241], v[146:149], v[114:117]
	v_mfma_f32_16x16x32_f16 v[102:105], v[230:233], v[192:195], v[102:105]
	v_mfma_f32_16x16x32_f16 v[98:101], v[238:241], v[192:195], v[98:101]
	v_mfma_f32_16x16x32_f16 v[86:89], v[230:233], v[204:207], v[86:89]
	v_mfma_f32_16x16x32_f16 v[82:85], v[238:241], v[204:207], v[82:85]
	v_mfma_f32_16x16x32_f16 v[70:73], v[230:233], v[212:215], v[70:73]
	v_mfma_f32_16x16x32_f16 v[66:69], v[238:241], v[212:215], v[66:69]
	s_waitcnt lgkmcnt(0)
	v_mfma_f32_16x16x32_f16 v[118:121], v[234:237], v[150:153], v[118:121]
	v_mfma_f32_16x16x32_f16 v[114:117], v[242:245], v[150:153], v[114:117]
	v_mfma_f32_16x16x32_f16 v[102:105], v[234:237], v[200:203], v[102:105]
	v_mfma_f32_16x16x32_f16 v[98:101], v[242:245], v[200:203], v[98:101]
	v_mfma_f32_16x16x32_f16 v[86:89], v[234:237], v[208:211], v[86:89]
	v_mfma_f32_16x16x32_f16 v[82:85], v[242:245], v[208:211], v[82:85]
	v_mfma_f32_16x16x32_f16 v[70:73], v[234:237], v[216:219], v[70:73]
	v_mfma_f32_16x16x32_f16 v[66:69], v[242:245], v[216:219], v[66:69]
	s_setprio 0
	s_mov_b32 m0, s25
	v_lshl_add_u64 v[228:229], v[228:229], 0, s[84:85]
	s_barrier
	ds_read_b128 v[146:149], v198 offset:49152
	ds_read_b128 v[192:195], v198 offset:51200
	ds_read_b128 v[204:207], v198 offset:53248
	ds_read_b128 v[212:215], v198 offset:55296
	ds_read_b128 v[150:153], v198 offset:50176
	ds_read_b128 v[200:203], v198 offset:52224
	ds_read_b128 v[208:211], v198 offset:54272
	ds_read_b128 v[216:219], v198 offset:56320
	global_load_lds_dwordx4 v[228:229], off
	v_lshl_add_u64 v[222:223], v[222:223], 0, s[84:85]
	s_mov_b32 m0, s27
	s_nop 0
	global_load_lds_dwordx4 v[222:223], off
	s_barrier
	s_waitcnt lgkmcnt(7)
	s_setprio 1
	v_mfma_f32_16x16x32_f16 v[62:65], v[122:125], v[146:149], v[62:65]
	v_mfma_f32_16x16x32_f16 v[58:61], v[138:141], v[146:149], v[58:61]
	s_waitcnt lgkmcnt(6)
	v_mfma_f32_16x16x32_f16 v[46:49], v[122:125], v[192:195], v[46:49]
	v_mfma_f32_16x16x32_f16 v[42:45], v[138:141], v[192:195], v[42:45]
	s_waitcnt lgkmcnt(5)
	v_mfma_f32_16x16x32_f16 v[28:31], v[122:125], v[204:207], v[28:31]
	v_mfma_f32_16x16x32_f16 v[24:27], v[138:141], v[204:207], v[24:27]
	s_waitcnt lgkmcnt(4)
	v_mfma_f32_16x16x32_f16 v[12:15], v[122:125], v[212:215], v[12:15]
	v_mfma_f32_16x16x32_f16 v[8:11], v[138:141], v[212:215], v[8:11]
	s_waitcnt lgkmcnt(3)
	v_mfma_f32_16x16x32_f16 v[62:65], v[130:133], v[150:153], v[62:65]
	v_mfma_f32_16x16x32_f16 v[58:61], v[142:145], v[150:153], v[58:61]
	s_waitcnt lgkmcnt(2)
	v_mfma_f32_16x16x32_f16 v[46:49], v[130:133], v[200:203], v[46:49]
	v_mfma_f32_16x16x32_f16 v[42:45], v[142:145], v[200:203], v[42:45]
	s_waitcnt lgkmcnt(1)
	v_mfma_f32_16x16x32_f16 v[28:31], v[130:133], v[208:211], v[28:31]
	v_mfma_f32_16x16x32_f16 v[24:27], v[142:145], v[208:211], v[24:27]
	s_waitcnt lgkmcnt(0)
	v_mfma_f32_16x16x32_f16 v[12:15], v[130:133], v[216:219], v[12:15]
	v_mfma_f32_16x16x32_f16 v[8:11], v[142:145], v[216:219], v[8:11]
	s_setprio 0
	s_barrier
	s_add_u32 s10, s14, 0x40080
	s_addc_u32 s11, s15, 0
	s_add_i32 s14, s16, s20
	v_lshl_add_u64 v[122:123], s[10:11], 0, v[32:33]
	s_mov_b32 m0, s14
	s_nop 0
	global_load_lds_dwordx4 v[122:123], off
	v_lshl_add_u64 v[122:123], s[10:11], 0, v[154:155]
	s_add_i32 m0, s14, 0x2000
	s_nop 0
	global_load_lds_dwordx4 v[122:123], off
	s_waitcnt vmcnt(10)
	s_barrier
	s_setprio 1
	v_mfma_f32_16x16x32_f16 v[54:57], v[230:233], v[146:149], v[54:57]
	v_mfma_f32_16x16x32_f16 v[50:53], v[238:241], v[146:149], v[50:53]
	v_mfma_f32_16x16x32_f16 v[38:41], v[230:233], v[192:195], v[38:41]
	v_mfma_f32_16x16x32_f16 v[34:37], v[238:241], v[192:195], v[34:37]
	v_mfma_f32_16x16x32_f16 v[20:23], v[230:233], v[204:207], v[20:23]
	v_mfma_f32_16x16x32_f16 v[16:19], v[238:241], v[204:207], v[16:19]
	v_mfma_f32_16x16x32_f16 v[4:7], v[230:233], v[212:215], v[4:7]
	v_mfma_f32_16x16x32_f16 v[0:3], v[238:241], v[212:215], v[0:3]
	v_mfma_f32_16x16x32_f16 v[54:57], v[234:237], v[150:153], v[54:57]
	v_mfma_f32_16x16x32_f16 v[50:53], v[242:245], v[150:153], v[50:53]
	v_mfma_f32_16x16x32_f16 v[38:41], v[234:237], v[200:203], v[38:41]
	v_mfma_f32_16x16x32_f16 v[34:37], v[242:245], v[200:203], v[34:37]
	v_mfma_f32_16x16x32_f16 v[20:23], v[234:237], v[208:211], v[20:23]
	v_mfma_f32_16x16x32_f16 v[16:19], v[242:245], v[208:211], v[16:19]
	v_mfma_f32_16x16x32_f16 v[4:7], v[234:237], v[216:219], v[4:7]
	v_mfma_f32_16x16x32_f16 v[0:3], v[242:245], v[216:219], v[0:3]
	s_setprio 0
	s_add_i32 s37, s37, 2
	s_add_u32 s35, s35, 0x100
	s_addc_u32 s36, s36, 0
	s_cmp_gt_u32 s37, 13
	s_mov_b64 s[10:11], s[12:13]
	s_barrier
	s_cbranch_scc0 .LBB0_958
	s_cmp_eq_u32 s34, 2
	s_movk_i32 s6, 0x2800
	v_lshl_or_b32 v122, s31, 8, v197
	s_cselect_b32 s6, 0x2000, s6
	s_mov_b32 s7, 0x23a3c000
	s_cselect_b32 s8, s7, 0x23abc000
	s_add_u32 s6, s70, s6
	v_ashrrev_i32_e32 v123, 31, v122
	s_addc_u32 s7, s71, 0
	v_lshlrev_b64 v[192:193], 1, v[122:123]
	v_lshl_add_u64 v[194:195], s[6:7], 0, v[192:193]
	v_lshl_add_u64 v[122:123], v[194:195], 0, v[156:157]
	v_lshl_add_u64 v[124:125], v[194:195], 0, v[158:159]
	v_lshl_add_u64 v[130:131], v[194:195], 0, v[160:161]
	v_lshl_add_u64 v[208:209], v[194:195], 0, v[162:163]
	global_load_dwordx4 v[200:203], v[122:123], off
	global_load_dwordx4 v[204:207], v[122:123], off offset:256
	global_load_dwordx4 v[150:153], v[124:125], off
	global_load_dwordx4 v[146:149], v[124:125], off offset:256
	global_load_dwordx4 v[142:145], v[130:131], off
	global_load_dwordx4 v[138:141], v[130:131], off offset:256
	s_nop 0
	global_load_dwordx4 v[130:133], v[208:209], off
	global_load_dwordx4 v[122:125], v[208:209], off offset:256
	v_readlane_b32 s36, v252, 26
	v_readlane_b32 s42, v252, 32
	v_readlane_b32 s43, v252, 33
	s_add_u32 s6, s42, s8
	s_addc_u32 s7, s43, 0
	v_readlane_b32 s37, v252, 27
	v_readlane_b32 s38, v252, 28
	v_readlane_b32 s39, v252, 29
	v_readlane_b32 s40, v252, 30
	v_readlane_b32 s41, v252, 31
	v_lshl_add_u64 v[192:193], s[6:7], 0, v[192:193]
	s_waitcnt vmcnt(0)
	v_cvt_f32_f16_e32 v199, v200
	v_cvt_f32_f16_sdwa v200, v200 dst_sel:DWORD dst_unused:UNUSED_PAD src0_sel:WORD_1
	v_cvt_f32_f16_e32 v210, v201
	v_lshl_add_u64 v[208:209], v[192:193], 0, v[164:165]
	v_max_f32_e32 v199, 0xc1f00000, v199
	v_mul_f32_e32 v199, 0xbfb8aa3b, v199
	v_exp_f32_e32 v199, v199
	v_max_f32_e32 v200, 0xc1f00000, v200
	v_max_f32_e32 v210, 0xc1f00000, v210
	v_mul_f32_e32 v200, 0xbfb8aa3b, v200
	v_add_f32_e32 v199, 1.0, v199
	v_rcp_f32_e32 v199, v199
	v_exp_f32_e32 v200, v200
	v_mul_f32_e32 v210, 0xbfb8aa3b, v210
	v_exp_f32_e32 v211, v210
	v_fma_mixlo_f16 v199, v134, v199, 0
	v_add_f32_e32 v134, 1.0, v200
	v_rcp_f32_e32 v210, v134
	v_add_f32_e32 v134, 1.0, v211
	v_cvt_f32_f16_sdwa v200, v201 dst_sel:DWORD dst_unused:UNUSED_PAD src0_sel:WORD_1
	v_rcp_f32_e32 v211, v134
	v_mov_b32_e32 v134, v135
	v_mov_b32_e32 v135, v136
	v_cvt_f32_f16_e32 v136, v202
	v_max_f32_e32 v200, 0xc1f00000, v200
	v_mul_f32_e32 v200, 0xbfb8aa3b, v200
	v_exp_f32_e32 v200, v200
	v_max_f32_e32 v136, 0xc1f00000, v136
	v_mul_f32_e32 v136, 0xbfb8aa3b, v136
	v_exp_f32_e32 v136, v136
	v_pk_mul_f32 v[134:135], v[134:135], v[210:211]
	s_nop 0
	v_cvt_pk_f16_f32 v135, v134, v135
	v_add_f32_e32 v134, 1.0, v200
	v_rcp_f32_e32 v200, v134
	v_add_f32_e32 v134, 1.0, v136
	v_rcp_f32_e32 v201, v134
	v_pk_mov_b32 v[136:137], v[136:137], v[126:127] op_sel:[1,0]
	v_cvt_f32_f16_sdwa v126, v202 dst_sel:DWORD dst_unused:UNUSED_PAD src0_sel:WORD_1
	v_pack_b32_f16 v134, v199, v135
	v_pk_mul_f32 v[136:137], v[136:137], v[200:201]
	v_cvt_f32_f16_sdwa v200, v203 dst_sel:DWORD dst_unused:UNUSED_PAD src0_sel:WORD_1
	v_cvt_pk_f16_f32 v199, v136, v137
	v_cvt_f32_f16_e32 v136, v203
	v_max_f32_e32 v126, 0xc1f00000, v126
	v_mul_f32_e32 v126, 0xbfb8aa3b, v126
	v_exp_f32_e32 v126, v126
	v_max_f32_e32 v136, 0xc1f00000, v136
	v_mul_f32_e32 v136, 0xbfb8aa3b, v136
	v_exp_f32_e32 v137, v136
	v_add_f32_e32 v126, 1.0, v126
	v_rcp_f32_e32 v136, v126
	v_alignbit_b32 v135, v199, v135, 16
	v_add_f32_e32 v126, 1.0, v137
	v_rcp_f32_e32 v137, v126
	v_mov_b32_e32 v126, v127
	v_mov_b32_e32 v127, v128
	v_cvt_f32_f16_e32 v128, v204
	v_pk_mul_f32 v[126:127], v[126:127], v[136:137]
	s_nop 0
	v_cvt_pk_f16_f32 v126, v126, v127
	v_max_f32_e32 v127, 0xc1f00000, v200
	v_mul_f32_e32 v127, 0xbfb8aa3b, v127
	v_exp_f32_e32 v127, v127
	v_alignbit_b32 v136, v126, v199, 16
	v_lshrrev_b32_e32 v137, 16, v126
	v_add_f32_e32 v126, 1.0, v127
	v_rcp_f32_e32 v126, v126
	v_max_f32_e32 v127, 0xc1f00000, v128
	v_mul_f32_e32 v127, 0xbfb8aa3b, v127
	v_exp_f32_e32 v127, v127
	v_fma_mixhi_f16 v137, v129, v126, 0
	v_cvt_f32_f16_sdwa v126, v204 dst_sel:DWORD dst_unused:UNUSED_PAD src0_sel:WORD_1
	v_cvt_f32_f16_e32 v128, v205
	v_add_f32_e32 v127, 1.0, v127
	v_rcp_f32_e32 v127, v127
	v_max_f32_e32 v126, 0xc1f00000, v126
	v_mul_f32_e32 v126, 0xbfb8aa3b, v126
	v_max_f32_e32 v128, 0xc1f00000, v128
	v_exp_f32_e32 v126, v126
	v_mul_f32_e32 v128, 0xbfb8aa3b, v128
	v_exp_f32_e32 v128, v128
	v_fma_mixlo_f16 v129, v118, v127, 0
	v_add_f32_e32 v118, 1.0, v126
	v_rcp_f32_e32 v126, v118
	v_add_f32_e32 v118, 1.0, v128
	v_rcp_f32_e32 v127, v118
	v_cvt_f32_f16_sdwa v128, v205 dst_sel:DWORD dst_unused:UNUSED_PAD src0_sel:WORD_1
	v_mov_b32_e32 v118, v119
	v_mov_b32_e32 v119, v120
	v_cvt_f32_f16_e32 v120, v206
	v_max_f32_e32 v128, 0xc1f00000, v128
	v_mul_f32_e32 v128, 0xbfb8aa3b, v128
	v_exp_f32_e32 v128, v128
	v_max_f32_e32 v120, 0xc1f00000, v120
	v_mul_f32_e32 v120, 0xbfb8aa3b, v120
	v_exp_f32_e32 v120, v120
	v_pk_mul_f32 v[118:119], v[118:119], v[126:127]
	v_add_f32_e32 v126, 1.0, v128
	v_rcp_f32_e32 v126, v126
	v_add_f32_e32 v120, 1.0, v120
	v_rcp_f32_e32 v127, v120
	v_pk_mov_b32 v[120:121], v[120:121], v[114:115] op_sel:[1,0]
	v_cvt_f32_f16_sdwa v114, v206 dst_sel:DWORD dst_unused:UNUSED_PAD src0_sel:WORD_1
	v_cvt_pk_f16_f32 v119, v118, v119
	v_pk_mul_f32 v[120:121], v[120:121], v[126:127]
	v_cvt_f32_f16_sdwa v127, v207 dst_sel:DWORD dst_unused:UNUSED_PAD src0_sel:WORD_1
	v_cvt_pk_f16_f32 v126, v120, v121
	v_cvt_f32_f16_e32 v120, v207
	v_max_f32_e32 v114, 0xc1f00000, v114
	v_mul_f32_e32 v114, 0xbfb8aa3b, v114
	v_exp_f32_e32 v114, v114
	v_max_f32_e32 v120, 0xc1f00000, v120
	v_mul_f32_e32 v120, 0xbfb8aa3b, v120
	v_exp_f32_e32 v121, v120
	v_add_f32_e32 v114, 1.0, v114
	v_rcp_f32_e32 v120, v114
	v_pack_b32_f16 v118, v129, v119
	v_add_f32_e32 v114, 1.0, v121
	v_rcp_f32_e32 v121, v114
	v_mov_b32_e32 v114, v115
	v_max_f32_e32 v115, 0xc1f00000, v127
	v_mul_f32_e32 v115, 0xbfb8aa3b, v115
	v_exp_f32_e32 v127, v115
	v_mov_b32_e32 v115, v116
	v_pk_mul_f32 v[114:115], v[114:115], v[120:121]
	v_cvt_f32_f16_e32 v116, v150
	v_cvt_pk_f16_f32 v114, v114, v115
	v_add_f32_e32 v115, 1.0, v127
	v_rcp_f32_e32 v115, v115
	v_alignbit_b32 v120, v114, v126, 16
	v_lshrrev_b32_e32 v121, 16, v114
	v_max_f32_e32 v114, 0xc1f00000, v116
	v_alignbit_b32 v119, v126, v119, 16
	v_fma_mixhi_f16 v121, v117, v115, 0
	v_mul_f32_e32 v114, 0xbfb8aa3b, v114
	v_cvt_f32_f16_sdwa v117, v150 dst_sel:DWORD dst_unused:UNUSED_PAD src0_sel:WORD_1
	v_exp_f32_e32 v116, v114
	global_store_dwordx4 v[208:209], v[118:121], off offset:256
	v_lshl_add_u64 v[114:115], v[192:193], 0, v[166:167]
	v_max_f32_e32 v117, 0xc1f00000, v117
	v_cvt_f32_f16_e32 v118, v151
	v_add_f32_e32 v116, 1.0, v116
	v_mul_f32_e32 v117, 0xbfb8aa3b, v117
	v_rcp_f32_e32 v116, v116
	v_max_f32_e32 v118, 0xc1f00000, v118
	v_exp_f32_e32 v117, v117
	v_mul_f32_e32 v118, 0xbfb8aa3b, v118
	v_exp_f32_e32 v118, v118
	v_fma_mixlo_f16 v119, v110, v116, 0
	v_add_f32_e32 v110, 1.0, v117
	v_rcp_f32_e32 v116, v110
	v_add_f32_e32 v110, 1.0, v118
	v_rcp_f32_e32 v117, v110
	v_cvt_f32_f16_sdwa v118, v151 dst_sel:DWORD dst_unused:UNUSED_PAD src0_sel:WORD_1
	v_mov_b32_e32 v110, v111
	v_mov_b32_e32 v111, v112
	v_cvt_f32_f16_e32 v112, v152
	v_pk_mul_f32 v[110:111], v[110:111], v[116:117]
	v_max_f32_e32 v116, 0xc1f00000, v118
	v_mul_f32_e32 v116, 0xbfb8aa3b, v116
	v_max_f32_e32 v112, 0xc1f00000, v112
	v_exp_f32_e32 v116, v116
	v_mul_f32_e32 v112, 0xbfb8aa3b, v112
	v_exp_f32_e32 v112, v112
	v_cvt_pk_f16_f32 v111, v110, v111
	v_add_f32_e32 v110, 1.0, v116
	v_rcp_f32_e32 v116, v110
	v_add_f32_e32 v110, 1.0, v112
	v_rcp_f32_e32 v117, v110
	v_pk_mov_b32 v[112:113], v[112:113], v[106:107] op_sel:[1,0]
	v_cvt_f32_f16_sdwa v106, v152 dst_sel:DWORD dst_unused:UNUSED_PAD src0_sel:WORD_1
	v_pack_b32_f16 v110, v119, v111
	v_pk_mul_f32 v[112:113], v[112:113], v[116:117]
	v_cvt_f32_f16_sdwa v117, v153 dst_sel:DWORD dst_unused:UNUSED_PAD src0_sel:WORD_1
	v_cvt_pk_f16_f32 v116, v112, v113
	v_cvt_f32_f16_e32 v112, v153
	v_max_f32_e32 v106, 0xc1f00000, v106
	v_mul_f32_e32 v106, 0xbfb8aa3b, v106
	v_exp_f32_e32 v106, v106
	v_max_f32_e32 v112, 0xc1f00000, v112
	v_mul_f32_e32 v112, 0xbfb8aa3b, v112
	v_exp_f32_e32 v113, v112
	v_add_f32_e32 v106, 1.0, v106
	v_rcp_f32_e32 v112, v106
	v_alignbit_b32 v111, v116, v111, 16
	v_add_f32_e32 v106, 1.0, v113
	v_rcp_f32_e32 v113, v106
	v_mov_b32_e32 v106, v107
	v_mov_b32_e32 v107, v108
	v_cvt_f32_f16_e32 v108, v146
	v_pk_mul_f32 v[106:107], v[106:107], v[112:113]
	global_store_dwordx4 v[208:209], v[134:137], off
	v_cvt_pk_f16_f32 v106, v106, v107
	v_max_f32_e32 v107, 0xc1f00000, v117
	v_mul_f32_e32 v107, 0xbfb8aa3b, v107
	v_exp_f32_e32 v107, v107
	v_alignbit_b32 v112, v106, v116, 16
	v_lshrrev_b32_e32 v113, 16, v106
	v_add_f32_e32 v106, 1.0, v107
	v_rcp_f32_e32 v106, v106
	v_max_f32_e32 v107, 0xc1f00000, v108
	v_mul_f32_e32 v107, 0xbfb8aa3b, v107
	v_exp_f32_e32 v107, v107
	v_fma_mixhi_f16 v113, v109, v106, 0
	v_cvt_f32_f16_sdwa v106, v146 dst_sel:DWORD dst_unused:UNUSED_PAD src0_sel:WORD_1
	v_cvt_f32_f16_e32 v108, v147
	v_add_f32_e32 v107, 1.0, v107
	v_rcp_f32_e32 v107, v107
	v_max_f32_e32 v106, 0xc1f00000, v106
	v_mul_f32_e32 v106, 0xbfb8aa3b, v106
	v_max_f32_e32 v108, 0xc1f00000, v108
	v_exp_f32_e32 v106, v106
	v_mul_f32_e32 v108, 0xbfb8aa3b, v108
	v_exp_f32_e32 v108, v108
	v_fma_mixlo_f16 v109, v102, v107, 0
	v_add_f32_e32 v102, 1.0, v106
	v_rcp_f32_e32 v106, v102
	v_add_f32_e32 v102, 1.0, v108
	v_rcp_f32_e32 v107, v102
	v_cvt_f32_f16_sdwa v108, v147 dst_sel:DWORD dst_unused:UNUSED_PAD src0_sel:WORD_1
	v_mov_b32_e32 v102, v103
	v_mov_b32_e32 v103, v104
	v_cvt_f32_f16_e32 v104, v148
	v_max_f32_e32 v108, 0xc1f00000, v108
	v_mul_f32_e32 v108, 0xbfb8aa3b, v108
	v_exp_f32_e32 v108, v108
	v_max_f32_e32 v104, 0xc1f00000, v104
	v_mul_f32_e32 v104, 0xbfb8aa3b, v104
	v_exp_f32_e32 v104, v104
	v_pk_mul_f32 v[102:103], v[102:103], v[106:107]
	v_add_f32_e32 v106, 1.0, v108
	v_rcp_f32_e32 v106, v106
	v_add_f32_e32 v104, 1.0, v104
	v_rcp_f32_e32 v107, v104
	v_pk_mov_b32 v[104:105], v[104:105], v[98:99] op_sel:[1,0]
	v_cvt_f32_f16_sdwa v98, v148 dst_sel:DWORD dst_unused:UNUSED_PAD src0_sel:WORD_1
	v_cvt_pk_f16_f32 v103, v102, v103
	v_pk_mul_f32 v[104:105], v[104:105], v[106:107]
	v_cvt_f32_f16_sdwa v107, v149 dst_sel:DWORD dst_unused:UNUSED_PAD src0_sel:WORD_1
	v_cvt_pk_f16_f32 v106, v104, v105
	v_cvt_f32_f16_e32 v104, v149
	v_max_f32_e32 v98, 0xc1f00000, v98
	v_mul_f32_e32 v98, 0xbfb8aa3b, v98
	v_exp_f32_e32 v98, v98
	v_max_f32_e32 v104, 0xc1f00000, v104
	v_mul_f32_e32 v104, 0xbfb8aa3b, v104
	v_exp_f32_e32 v105, v104
	v_add_f32_e32 v98, 1.0, v98
	v_rcp_f32_e32 v104, v98
	v_pack_b32_f16 v102, v109, v103
	v_add_f32_e32 v98, 1.0, v105
	v_rcp_f32_e32 v105, v98
	v_mov_b32_e32 v98, v99
	v_max_f32_e32 v99, 0xc1f00000, v107
	v_mul_f32_e32 v99, 0xbfb8aa3b, v99
	v_exp_f32_e32 v107, v99
	v_mov_b32_e32 v99, v100
	v_pk_mul_f32 v[98:99], v[98:99], v[104:105]
	v_cvt_f32_f16_e32 v100, v142
	v_cvt_pk_f16_f32 v98, v98, v99
	v_add_f32_e32 v99, 1.0, v107
	v_rcp_f32_e32 v99, v99
	v_alignbit_b32 v104, v98, v106, 16
	v_lshrrev_b32_e32 v105, 16, v98
	v_max_f32_e32 v98, 0xc1f00000, v100
	v_alignbit_b32 v103, v106, v103, 16
	v_fma_mixhi_f16 v105, v101, v99, 0
	v_mul_f32_e32 v98, 0xbfb8aa3b, v98
	v_cvt_f32_f16_sdwa v101, v142 dst_sel:DWORD dst_unused:UNUSED_PAD src0_sel:WORD_1
	v_exp_f32_e32 v100, v98
	global_store_dwordx4 v[114:115], v[102:105], off offset:256
	v_lshl_add_u64 v[98:99], v[192:193], 0, v[168:169]
	v_max_f32_e32 v101, 0xc1f00000, v101
	v_cvt_f32_f16_e32 v102, v143
	v_add_f32_e32 v100, 1.0, v100
	v_mul_f32_e32 v101, 0xbfb8aa3b, v101
	v_rcp_f32_e32 v100, v100
	v_max_f32_e32 v102, 0xc1f00000, v102
	v_exp_f32_e32 v101, v101
	v_mul_f32_e32 v102, 0xbfb8aa3b, v102
	v_exp_f32_e32 v102, v102
	v_fma_mixlo_f16 v103, v94, v100, 0
	v_add_f32_e32 v94, 1.0, v101
	v_rcp_f32_e32 v100, v94
	v_add_f32_e32 v94, 1.0, v102
	v_rcp_f32_e32 v101, v94
	v_cvt_f32_f16_sdwa v102, v143 dst_sel:DWORD dst_unused:UNUSED_PAD src0_sel:WORD_1
	v_mov_b32_e32 v94, v95
	v_mov_b32_e32 v95, v96
	v_cvt_f32_f16_e32 v96, v144
	v_pk_mul_f32 v[94:95], v[94:95], v[100:101]
	v_max_f32_e32 v100, 0xc1f00000, v102
	v_mul_f32_e32 v100, 0xbfb8aa3b, v100
	v_max_f32_e32 v96, 0xc1f00000, v96
	v_exp_f32_e32 v100, v100
	v_mul_f32_e32 v96, 0xbfb8aa3b, v96
	v_exp_f32_e32 v96, v96
	v_cvt_pk_f16_f32 v95, v94, v95
	v_add_f32_e32 v94, 1.0, v100
	v_rcp_f32_e32 v100, v94
	v_add_f32_e32 v94, 1.0, v96
	v_rcp_f32_e32 v101, v94
	v_pk_mov_b32 v[96:97], v[96:97], v[90:91] op_sel:[1,0]
	v_cvt_f32_f16_sdwa v90, v144 dst_sel:DWORD dst_unused:UNUSED_PAD src0_sel:WORD_1
	v_pack_b32_f16 v94, v103, v95
	v_pk_mul_f32 v[96:97], v[96:97], v[100:101]
	v_cvt_f32_f16_sdwa v101, v145 dst_sel:DWORD dst_unused:UNUSED_PAD src0_sel:WORD_1
	v_cvt_pk_f16_f32 v100, v96, v97
	v_cvt_f32_f16_e32 v96, v145
	v_max_f32_e32 v90, 0xc1f00000, v90
	v_mul_f32_e32 v90, 0xbfb8aa3b, v90
	v_exp_f32_e32 v90, v90
	v_max_f32_e32 v96, 0xc1f00000, v96
	v_mul_f32_e32 v96, 0xbfb8aa3b, v96
	v_exp_f32_e32 v97, v96
	v_add_f32_e32 v90, 1.0, v90
	v_rcp_f32_e32 v96, v90
	v_alignbit_b32 v95, v100, v95, 16
	v_add_f32_e32 v90, 1.0, v97
	v_rcp_f32_e32 v97, v90
	v_mov_b32_e32 v90, v91
	v_mov_b32_e32 v91, v92
	v_cvt_f32_f16_e32 v92, v138
	v_pk_mul_f32 v[90:91], v[90:91], v[96:97]
	global_store_dwordx4 v[114:115], v[110:113], off
	v_cvt_pk_f16_f32 v90, v90, v91
	v_max_f32_e32 v91, 0xc1f00000, v101
	v_mul_f32_e32 v91, 0xbfb8aa3b, v91
	v_exp_f32_e32 v91, v91
	v_alignbit_b32 v96, v90, v100, 16
	v_lshrrev_b32_e32 v97, 16, v90
	v_add_f32_e32 v90, 1.0, v91
	v_rcp_f32_e32 v90, v90
	v_max_f32_e32 v91, 0xc1f00000, v92
	v_mul_f32_e32 v91, 0xbfb8aa3b, v91
	v_exp_f32_e32 v91, v91
	v_fma_mixhi_f16 v97, v93, v90, 0
	v_cvt_f32_f16_sdwa v90, v138 dst_sel:DWORD dst_unused:UNUSED_PAD src0_sel:WORD_1
	v_cvt_f32_f16_e32 v92, v139
	v_add_f32_e32 v91, 1.0, v91
	v_rcp_f32_e32 v91, v91
	v_max_f32_e32 v90, 0xc1f00000, v90
	v_mul_f32_e32 v90, 0xbfb8aa3b, v90
	v_max_f32_e32 v92, 0xc1f00000, v92
	v_exp_f32_e32 v90, v90
	v_mul_f32_e32 v92, 0xbfb8aa3b, v92
	v_exp_f32_e32 v92, v92
	v_fma_mixlo_f16 v93, v86, v91, 0
	v_add_f32_e32 v86, 1.0, v90
	v_rcp_f32_e32 v90, v86
	v_add_f32_e32 v86, 1.0, v92
	v_rcp_f32_e32 v91, v86
	v_cvt_f32_f16_sdwa v92, v139 dst_sel:DWORD dst_unused:UNUSED_PAD src0_sel:WORD_1
	v_mov_b32_e32 v86, v87
	v_mov_b32_e32 v87, v88
	v_cvt_f32_f16_e32 v88, v140
	v_max_f32_e32 v92, 0xc1f00000, v92
	v_mul_f32_e32 v92, 0xbfb8aa3b, v92
	v_exp_f32_e32 v92, v92
	v_max_f32_e32 v88, 0xc1f00000, v88
	v_mul_f32_e32 v88, 0xbfb8aa3b, v88
	v_exp_f32_e32 v88, v88
	v_pk_mul_f32 v[86:87], v[86:87], v[90:91]
	v_add_f32_e32 v90, 1.0, v92
	v_rcp_f32_e32 v90, v90
	v_add_f32_e32 v88, 1.0, v88
	v_rcp_f32_e32 v91, v88
	v_pk_mov_b32 v[88:89], v[88:89], v[82:83] op_sel:[1,0]
	v_cvt_f32_f16_sdwa v82, v140 dst_sel:DWORD dst_unused:UNUSED_PAD src0_sel:WORD_1
	v_cvt_pk_f16_f32 v87, v86, v87
	v_pk_mul_f32 v[88:89], v[88:89], v[90:91]
	v_cvt_f32_f16_sdwa v91, v141 dst_sel:DWORD dst_unused:UNUSED_PAD src0_sel:WORD_1
	v_cvt_pk_f16_f32 v90, v88, v89
	v_cvt_f32_f16_e32 v88, v141
	v_max_f32_e32 v82, 0xc1f00000, v82
	v_mul_f32_e32 v82, 0xbfb8aa3b, v82
	v_exp_f32_e32 v82, v82
	v_max_f32_e32 v88, 0xc1f00000, v88
	v_mul_f32_e32 v88, 0xbfb8aa3b, v88
	v_exp_f32_e32 v89, v88
	v_add_f32_e32 v82, 1.0, v82
	v_rcp_f32_e32 v88, v82
	v_pack_b32_f16 v86, v93, v87
	v_add_f32_e32 v82, 1.0, v89
	v_rcp_f32_e32 v89, v82
	v_mov_b32_e32 v82, v83
	v_max_f32_e32 v83, 0xc1f00000, v91
	v_mul_f32_e32 v83, 0xbfb8aa3b, v83
	v_exp_f32_e32 v91, v83
	v_mov_b32_e32 v83, v84
	v_pk_mul_f32 v[82:83], v[82:83], v[88:89]
	v_cvt_f32_f16_e32 v84, v130
	v_cvt_pk_f16_f32 v82, v82, v83
	v_add_f32_e32 v83, 1.0, v91
	v_rcp_f32_e32 v83, v83
	v_alignbit_b32 v88, v82, v90, 16
	v_lshrrev_b32_e32 v89, 16, v82
	v_max_f32_e32 v82, 0xc1f00000, v84
	v_alignbit_b32 v87, v90, v87, 16
	v_fma_mixhi_f16 v89, v85, v83, 0
	v_mul_f32_e32 v82, 0xbfb8aa3b, v82
	v_cvt_f32_f16_sdwa v85, v130 dst_sel:DWORD dst_unused:UNUSED_PAD src0_sel:WORD_1
	v_exp_f32_e32 v84, v82
	global_store_dwordx4 v[98:99], v[86:89], off offset:256
	v_lshl_add_u64 v[82:83], v[192:193], 0, v[170:171]
	v_max_f32_e32 v85, 0xc1f00000, v85
	v_cvt_f32_f16_e32 v86, v131
	v_add_f32_e32 v84, 1.0, v84
	v_mul_f32_e32 v85, 0xbfb8aa3b, v85
	v_rcp_f32_e32 v84, v84
	v_max_f32_e32 v86, 0xc1f00000, v86
	v_exp_f32_e32 v85, v85
	v_mul_f32_e32 v86, 0xbfb8aa3b, v86
	v_exp_f32_e32 v86, v86
	v_fma_mixlo_f16 v87, v78, v84, 0
	v_add_f32_e32 v78, 1.0, v85
	v_rcp_f32_e32 v84, v78
	v_add_f32_e32 v78, 1.0, v86
	v_rcp_f32_e32 v85, v78
	v_cvt_f32_f16_sdwa v86, v131 dst_sel:DWORD dst_unused:UNUSED_PAD src0_sel:WORD_1
	v_mov_b32_e32 v78, v79
	v_mov_b32_e32 v79, v80
	v_cvt_f32_f16_e32 v80, v132
	v_pk_mul_f32 v[78:79], v[78:79], v[84:85]
	v_max_f32_e32 v84, 0xc1f00000, v86
	v_mul_f32_e32 v84, 0xbfb8aa3b, v84
	v_max_f32_e32 v80, 0xc1f00000, v80
	v_exp_f32_e32 v84, v84
	v_mul_f32_e32 v80, 0xbfb8aa3b, v80
	v_exp_f32_e32 v80, v80
	v_cvt_pk_f16_f32 v79, v78, v79
	v_add_f32_e32 v78, 1.0, v84
	v_rcp_f32_e32 v84, v78
	v_add_f32_e32 v78, 1.0, v80
	v_rcp_f32_e32 v85, v78
	v_pk_mov_b32 v[80:81], v[80:81], v[74:75] op_sel:[1,0]
	v_cvt_f32_f16_sdwa v74, v132 dst_sel:DWORD dst_unused:UNUSED_PAD src0_sel:WORD_1
	v_pack_b32_f16 v78, v87, v79
	v_pk_mul_f32 v[80:81], v[80:81], v[84:85]
	v_cvt_f32_f16_sdwa v85, v133 dst_sel:DWORD dst_unused:UNUSED_PAD src0_sel:WORD_1
	v_cvt_pk_f16_f32 v84, v80, v81
	v_cvt_f32_f16_e32 v80, v133
	v_max_f32_e32 v74, 0xc1f00000, v74
	v_mul_f32_e32 v74, 0xbfb8aa3b, v74
	v_exp_f32_e32 v74, v74
	v_max_f32_e32 v80, 0xc1f00000, v80
	v_mul_f32_e32 v80, 0xbfb8aa3b, v80
	v_exp_f32_e32 v81, v80
	v_add_f32_e32 v74, 1.0, v74
	v_rcp_f32_e32 v80, v74
	v_alignbit_b32 v79, v84, v79, 16
	v_add_f32_e32 v74, 1.0, v81
	v_rcp_f32_e32 v81, v74
	v_mov_b32_e32 v74, v75
	v_mov_b32_e32 v75, v76
	v_cvt_f32_f16_e32 v76, v122
	v_pk_mul_f32 v[74:75], v[74:75], v[80:81]
	global_store_dwordx4 v[98:99], v[94:97], off
	v_cvt_pk_f16_f32 v74, v74, v75
	v_max_f32_e32 v75, 0xc1f00000, v85
	v_mul_f32_e32 v75, 0xbfb8aa3b, v75
	v_exp_f32_e32 v75, v75
	v_alignbit_b32 v80, v74, v84, 16
	v_lshrrev_b32_e32 v81, 16, v74
	v_add_f32_e32 v74, 1.0, v75
	v_rcp_f32_e32 v74, v74
	v_max_f32_e32 v75, 0xc1f00000, v76
	v_mul_f32_e32 v75, 0xbfb8aa3b, v75
	v_exp_f32_e32 v75, v75
	v_fma_mixhi_f16 v81, v77, v74, 0
	v_cvt_f32_f16_sdwa v74, v122 dst_sel:DWORD dst_unused:UNUSED_PAD src0_sel:WORD_1
	v_cvt_f32_f16_e32 v76, v123
	v_add_f32_e32 v75, 1.0, v75
	v_rcp_f32_e32 v75, v75
	v_max_f32_e32 v74, 0xc1f00000, v74
	v_mul_f32_e32 v74, 0xbfb8aa3b, v74
	v_max_f32_e32 v76, 0xc1f00000, v76
	v_exp_f32_e32 v74, v74
	v_mul_f32_e32 v76, 0xbfb8aa3b, v76
	v_exp_f32_e32 v76, v76
	v_fma_mixlo_f16 v77, v70, v75, 0
	v_add_f32_e32 v70, 1.0, v74
	v_rcp_f32_e32 v74, v70
	v_add_f32_e32 v70, 1.0, v76
	v_rcp_f32_e32 v75, v70
	v_cvt_f32_f16_sdwa v76, v123 dst_sel:DWORD dst_unused:UNUSED_PAD src0_sel:WORD_1
	v_mov_b32_e32 v70, v71
	v_mov_b32_e32 v71, v72
	v_cvt_f32_f16_e32 v72, v124
	v_max_f32_e32 v76, 0xc1f00000, v76
	v_mul_f32_e32 v76, 0xbfb8aa3b, v76
	v_exp_f32_e32 v76, v76
	v_max_f32_e32 v72, 0xc1f00000, v72
	v_mul_f32_e32 v72, 0xbfb8aa3b, v72
	v_exp_f32_e32 v72, v72
	v_pk_mul_f32 v[70:71], v[70:71], v[74:75]
	v_add_f32_e32 v74, 1.0, v76
	v_rcp_f32_e32 v74, v74
	v_add_f32_e32 v72, 1.0, v72
	v_rcp_f32_e32 v75, v72
	v_pk_mov_b32 v[72:73], v[72:73], v[66:67] op_sel:[1,0]
	v_cvt_f32_f16_sdwa v66, v124 dst_sel:DWORD dst_unused:UNUSED_PAD src0_sel:WORD_1
	v_cvt_pk_f16_f32 v71, v70, v71
	v_pk_mul_f32 v[72:73], v[72:73], v[74:75]
	v_cvt_f32_f16_sdwa v75, v125 dst_sel:DWORD dst_unused:UNUSED_PAD src0_sel:WORD_1
	v_cvt_pk_f16_f32 v74, v72, v73
	v_cvt_f32_f16_e32 v72, v125
	v_max_f32_e32 v66, 0xc1f00000, v66
	v_mul_f32_e32 v66, 0xbfb8aa3b, v66
	v_exp_f32_e32 v66, v66
	v_max_f32_e32 v72, 0xc1f00000, v72
	v_mul_f32_e32 v72, 0xbfb8aa3b, v72
	v_exp_f32_e32 v73, v72
	v_add_f32_e32 v66, 1.0, v66
	v_rcp_f32_e32 v72, v66
	v_pack_b32_f16 v70, v77, v71
	v_add_f32_e32 v66, 1.0, v73
	v_rcp_f32_e32 v73, v66
	v_max_f32_e32 v66, 0xc1f00000, v75
	v_mul_f32_e32 v66, 0xbfb8aa3b, v66
	v_exp_f32_e32 v75, v66
	v_mov_b32_e32 v66, v67
	v_mov_b32_e32 v67, v68
	v_pk_mul_f32 v[66:67], v[66:67], v[72:73]
	v_add_f32_e32 v68, 1.0, v75
	v_rcp_f32_e32 v68, v68
	v_cvt_pk_f16_f32 v66, v66, v67
	v_lshrrev_b32_e32 v73, 16, v66
	v_alignbit_b32 v71, v74, v71, 16
	v_alignbit_b32 v72, v66, v74, 16
	v_fma_mixhi_f16 v73, v69, v68, 0
	global_store_dwordx4 v[82:83], v[78:81], off
	global_store_dwordx4 v[82:83], v[70:73], off offset:256
	v_lshl_add_u64 v[66:67], v[194:195], 0, v[172:173]
	v_lshl_add_u64 v[68:69], v[194:195], 0, v[174:175]
	v_lshl_add_u64 v[70:71], v[194:195], 0, v[176:177]
	v_lshl_add_u64 v[98:99], v[194:195], 0, v[178:179]
	global_load_dwordx4 v[90:93], v[66:67], off
	global_load_dwordx4 v[94:97], v[66:67], off offset:256
	global_load_dwordx4 v[86:89], v[68:69], off
	global_load_dwordx4 v[82:85], v[68:69], off offset:256
	global_load_dwordx4 v[78:81], v[70:71], off
	global_load_dwordx4 v[74:77], v[70:71], off offset:256
	s_nop 0
	global_load_dwordx4 v[70:73], v[98:99], off
	global_load_dwordx4 v[66:69], v[98:99], off offset:256
	s_waitcnt vmcnt(0)
	v_cvt_f32_f16_e32 v100, v90
	v_cvt_f32_f16_sdwa v90, v90 dst_sel:DWORD dst_unused:UNUSED_PAD src0_sel:WORD_1
	v_cvt_f32_f16_e32 v101, v91
	v_lshl_add_u64 v[98:99], v[192:193], 0, v[180:181]
	v_max_f32_e32 v100, 0xc1f00000, v100
	v_mul_f32_e32 v100, 0xbfb8aa3b, v100
	v_exp_f32_e32 v100, v100
	v_max_f32_e32 v90, 0xc1f00000, v90
	v_max_f32_e32 v101, 0xc1f00000, v101
	v_mul_f32_e32 v90, 0xbfb8aa3b, v90
	v_add_f32_e32 v100, 1.0, v100
	v_rcp_f32_e32 v100, v100
	v_exp_f32_e32 v90, v90
	v_mul_f32_e32 v101, 0xbfb8aa3b, v101
	v_exp_f32_e32 v101, v101
	v_fma_mixlo_f16 v102, v62, v100, 0
	v_add_f32_e32 v62, 1.0, v90
	v_rcp_f32_e32 v100, v62
	v_add_f32_e32 v62, 1.0, v101
	v_cvt_f32_f16_sdwa v90, v91 dst_sel:DWORD dst_unused:UNUSED_PAD src0_sel:WORD_1
	v_rcp_f32_e32 v101, v62
	v_mov_b32_e32 v62, v63
	v_mov_b32_e32 v63, v64
	v_cvt_f32_f16_e32 v64, v92
	v_max_f32_e32 v90, 0xc1f00000, v90
	v_mul_f32_e32 v90, 0xbfb8aa3b, v90
	v_exp_f32_e32 v90, v90
	v_max_f32_e32 v64, 0xc1f00000, v64
	v_mul_f32_e32 v64, 0xbfb8aa3b, v64
	v_exp_f32_e32 v64, v64
	v_pk_mul_f32 v[62:63], v[62:63], v[100:101]
	s_nop 0
	v_cvt_pk_f16_f32 v63, v62, v63
	v_add_f32_e32 v62, 1.0, v90
	v_rcp_f32_e32 v90, v62
	v_add_f32_e32 v62, 1.0, v64
	v_rcp_f32_e32 v91, v62
	v_pk_mov_b32 v[64:65], v[64:65], v[58:59] op_sel:[1,0]
	v_cvt_f32_f16_sdwa v58, v92 dst_sel:DWORD dst_unused:UNUSED_PAD src0_sel:WORD_1
	v_pack_b32_f16 v62, v102, v63
	v_pk_mul_f32 v[64:65], v[64:65], v[90:91]
	v_cvt_f32_f16_sdwa v91, v93 dst_sel:DWORD dst_unused:UNUSED_PAD src0_sel:WORD_1
	v_cvt_pk_f16_f32 v90, v64, v65
	v_cvt_f32_f16_e32 v64, v93
	v_max_f32_e32 v58, 0xc1f00000, v58
	v_mul_f32_e32 v58, 0xbfb8aa3b, v58
	v_exp_f32_e32 v58, v58
	v_max_f32_e32 v64, 0xc1f00000, v64
	v_mul_f32_e32 v64, 0xbfb8aa3b, v64
	v_exp_f32_e32 v65, v64
	v_add_f32_e32 v58, 1.0, v58
	v_rcp_f32_e32 v64, v58
	v_alignbit_b32 v63, v90, v63, 16
	v_add_f32_e32 v58, 1.0, v65
	v_rcp_f32_e32 v65, v58
	v_mov_b32_e32 v58, v59
	v_mov_b32_e32 v59, v60
	v_cvt_f32_f16_e32 v60, v94
	v_pk_mul_f32 v[58:59], v[58:59], v[64:65]
	s_nop 0
	v_cvt_pk_f16_f32 v58, v58, v59
	v_max_f32_e32 v59, 0xc1f00000, v91
	v_mul_f32_e32 v59, 0xbfb8aa3b, v59
	v_exp_f32_e32 v59, v59
	v_alignbit_b32 v64, v58, v90, 16
	v_lshrrev_b32_e32 v65, 16, v58
	v_add_f32_e32 v58, 1.0, v59
	v_rcp_f32_e32 v58, v58
	v_max_f32_e32 v59, 0xc1f00000, v60
	v_mul_f32_e32 v59, 0xbfb8aa3b, v59
	v_exp_f32_e32 v59, v59
	v_fma_mixhi_f16 v65, v61, v58, 0
	v_cvt_f32_f16_sdwa v58, v94 dst_sel:DWORD dst_unused:UNUSED_PAD src0_sel:WORD_1
	v_cvt_f32_f16_e32 v60, v95
	v_add_f32_e32 v59, 1.0, v59
	v_rcp_f32_e32 v59, v59
	v_max_f32_e32 v58, 0xc1f00000, v58
	v_mul_f32_e32 v58, 0xbfb8aa3b, v58
	v_max_f32_e32 v60, 0xc1f00000, v60
	v_exp_f32_e32 v58, v58
	v_mul_f32_e32 v60, 0xbfb8aa3b, v60
	v_exp_f32_e32 v60, v60
	v_fma_mixlo_f16 v61, v54, v59, 0
	v_add_f32_e32 v54, 1.0, v58
	v_rcp_f32_e32 v58, v54
	v_add_f32_e32 v54, 1.0, v60
	v_rcp_f32_e32 v59, v54
	v_cvt_f32_f16_sdwa v60, v95 dst_sel:DWORD dst_unused:UNUSED_PAD src0_sel:WORD_1
	v_mov_b32_e32 v54, v55
	v_mov_b32_e32 v55, v56
	v_cvt_f32_f16_e32 v56, v96
	v_max_f32_e32 v60, 0xc1f00000, v60
	v_mul_f32_e32 v60, 0xbfb8aa3b, v60
	v_exp_f32_e32 v60, v60
	v_max_f32_e32 v56, 0xc1f00000, v56
	v_mul_f32_e32 v56, 0xbfb8aa3b, v56
	v_exp_f32_e32 v56, v56
	v_pk_mul_f32 v[54:55], v[54:55], v[58:59]
	v_add_f32_e32 v58, 1.0, v60
	v_rcp_f32_e32 v58, v58
	v_add_f32_e32 v56, 1.0, v56
	v_rcp_f32_e32 v59, v56
	v_pk_mov_b32 v[56:57], v[56:57], v[50:51] op_sel:[1,0]
	v_cvt_f32_f16_sdwa v50, v96 dst_sel:DWORD dst_unused:UNUSED_PAD src0_sel:WORD_1
	v_cvt_pk_f16_f32 v55, v54, v55
	v_pk_mul_f32 v[56:57], v[56:57], v[58:59]
	v_cvt_f32_f16_sdwa v59, v97 dst_sel:DWORD dst_unused:UNUSED_PAD src0_sel:WORD_1
	v_cvt_pk_f16_f32 v58, v56, v57
	v_cvt_f32_f16_e32 v56, v97
	v_max_f32_e32 v50, 0xc1f00000, v50
	v_mul_f32_e32 v50, 0xbfb8aa3b, v50
	v_exp_f32_e32 v50, v50
	v_max_f32_e32 v56, 0xc1f00000, v56
	v_mul_f32_e32 v56, 0xbfb8aa3b, v56
	v_exp_f32_e32 v57, v56
	v_add_f32_e32 v50, 1.0, v50
	v_rcp_f32_e32 v56, v50
	v_pack_b32_f16 v54, v61, v55
	v_add_f32_e32 v50, 1.0, v57
	v_rcp_f32_e32 v57, v50
	v_mov_b32_e32 v50, v51
	v_max_f32_e32 v51, 0xc1f00000, v59
	v_mul_f32_e32 v51, 0xbfb8aa3b, v51
	v_exp_f32_e32 v59, v51
	v_mov_b32_e32 v51, v52
	v_pk_mul_f32 v[50:51], v[50:51], v[56:57]
	v_cvt_f32_f16_e32 v52, v86
	v_cvt_pk_f16_f32 v50, v50, v51
	v_add_f32_e32 v51, 1.0, v59
	v_rcp_f32_e32 v51, v51
	v_alignbit_b32 v56, v50, v58, 16
	v_lshrrev_b32_e32 v57, 16, v50
	v_max_f32_e32 v50, 0xc1f00000, v52
	v_alignbit_b32 v55, v58, v55, 16
	v_fma_mixhi_f16 v57, v53, v51, 0
	v_mul_f32_e32 v50, 0xbfb8aa3b, v50
	v_cvt_f32_f16_sdwa v53, v86 dst_sel:DWORD dst_unused:UNUSED_PAD src0_sel:WORD_1
	v_exp_f32_e32 v52, v50
	global_store_dwordx4 v[98:99], v[54:57], off offset:256
	v_lshl_add_u64 v[50:51], v[192:193], 0, v[182:183]
	v_max_f32_e32 v53, 0xc1f00000, v53
	v_cvt_f32_f16_e32 v54, v87
	v_add_f32_e32 v52, 1.0, v52
	v_mul_f32_e32 v53, 0xbfb8aa3b, v53
	v_rcp_f32_e32 v52, v52
	v_max_f32_e32 v54, 0xc1f00000, v54
	v_exp_f32_e32 v53, v53
	v_mul_f32_e32 v54, 0xbfb8aa3b, v54
	v_exp_f32_e32 v54, v54
	v_fma_mixlo_f16 v55, v46, v52, 0
	v_add_f32_e32 v46, 1.0, v53
	v_rcp_f32_e32 v52, v46
	v_add_f32_e32 v46, 1.0, v54
	v_rcp_f32_e32 v53, v46
	v_cvt_f32_f16_sdwa v54, v87 dst_sel:DWORD dst_unused:UNUSED_PAD src0_sel:WORD_1
	v_mov_b32_e32 v46, v47
	v_mov_b32_e32 v47, v48
	v_cvt_f32_f16_e32 v48, v88
	v_pk_mul_f32 v[46:47], v[46:47], v[52:53]
	v_max_f32_e32 v52, 0xc1f00000, v54
	v_mul_f32_e32 v52, 0xbfb8aa3b, v52
	v_max_f32_e32 v48, 0xc1f00000, v48
	v_exp_f32_e32 v52, v52
	v_mul_f32_e32 v48, 0xbfb8aa3b, v48
	v_exp_f32_e32 v48, v48
	v_cvt_pk_f16_f32 v47, v46, v47
	v_add_f32_e32 v46, 1.0, v52
	v_rcp_f32_e32 v52, v46
	v_add_f32_e32 v46, 1.0, v48
	v_rcp_f32_e32 v53, v46
	v_pk_mov_b32 v[48:49], v[48:49], v[42:43] op_sel:[1,0]
	v_cvt_f32_f16_sdwa v42, v88 dst_sel:DWORD dst_unused:UNUSED_PAD src0_sel:WORD_1
	v_pack_b32_f16 v46, v55, v47
	v_pk_mul_f32 v[48:49], v[48:49], v[52:53]
	v_cvt_f32_f16_sdwa v53, v89 dst_sel:DWORD dst_unused:UNUSED_PAD src0_sel:WORD_1
	v_cvt_pk_f16_f32 v52, v48, v49
	v_cvt_f32_f16_e32 v48, v89
	v_max_f32_e32 v42, 0xc1f00000, v42
	v_mul_f32_e32 v42, 0xbfb8aa3b, v42
	v_exp_f32_e32 v42, v42
	v_max_f32_e32 v48, 0xc1f00000, v48
	v_mul_f32_e32 v48, 0xbfb8aa3b, v48
	v_exp_f32_e32 v49, v48
	v_add_f32_e32 v42, 1.0, v42
	v_rcp_f32_e32 v48, v42
	v_alignbit_b32 v47, v52, v47, 16
	v_add_f32_e32 v42, 1.0, v49
	v_rcp_f32_e32 v49, v42
	v_mov_b32_e32 v42, v43
	v_mov_b32_e32 v43, v44
	v_cvt_f32_f16_e32 v44, v82
	v_pk_mul_f32 v[42:43], v[42:43], v[48:49]
	global_store_dwordx4 v[98:99], v[62:65], off
	v_cvt_pk_f16_f32 v42, v42, v43
	v_max_f32_e32 v43, 0xc1f00000, v53
	v_mul_f32_e32 v43, 0xbfb8aa3b, v43
	v_exp_f32_e32 v43, v43
	v_alignbit_b32 v48, v42, v52, 16
	v_lshrrev_b32_e32 v49, 16, v42
	v_add_f32_e32 v42, 1.0, v43
	v_rcp_f32_e32 v42, v42
	v_max_f32_e32 v43, 0xc1f00000, v44
	v_mul_f32_e32 v43, 0xbfb8aa3b, v43
	v_exp_f32_e32 v43, v43
	v_fma_mixhi_f16 v49, v45, v42, 0
	v_cvt_f32_f16_sdwa v42, v82 dst_sel:DWORD dst_unused:UNUSED_PAD src0_sel:WORD_1
	v_cvt_f32_f16_e32 v44, v83
	v_add_f32_e32 v43, 1.0, v43
	v_rcp_f32_e32 v43, v43
	v_max_f32_e32 v42, 0xc1f00000, v42
	v_mul_f32_e32 v42, 0xbfb8aa3b, v42
	v_max_f32_e32 v44, 0xc1f00000, v44
	v_exp_f32_e32 v42, v42
	v_mul_f32_e32 v44, 0xbfb8aa3b, v44
	v_exp_f32_e32 v44, v44
	v_fma_mixlo_f16 v45, v38, v43, 0
	v_add_f32_e32 v38, 1.0, v42
	v_rcp_f32_e32 v42, v38
	v_add_f32_e32 v38, 1.0, v44
	v_rcp_f32_e32 v43, v38
	v_cvt_f32_f16_sdwa v44, v83 dst_sel:DWORD dst_unused:UNUSED_PAD src0_sel:WORD_1
	v_mov_b32_e32 v38, v39
	v_mov_b32_e32 v39, v40
	v_cvt_f32_f16_e32 v40, v84
	v_max_f32_e32 v44, 0xc1f00000, v44
	v_mul_f32_e32 v44, 0xbfb8aa3b, v44
	v_exp_f32_e32 v44, v44
	v_max_f32_e32 v40, 0xc1f00000, v40
	v_mul_f32_e32 v40, 0xbfb8aa3b, v40
	v_exp_f32_e32 v40, v40
	v_pk_mul_f32 v[38:39], v[38:39], v[42:43]
	v_add_f32_e32 v42, 1.0, v44
	v_rcp_f32_e32 v42, v42
	v_add_f32_e32 v40, 1.0, v40
	v_rcp_f32_e32 v43, v40
	v_pk_mov_b32 v[40:41], v[40:41], v[34:35] op_sel:[1,0]
	v_cvt_f32_f16_sdwa v34, v84 dst_sel:DWORD dst_unused:UNUSED_PAD src0_sel:WORD_1
	v_cvt_pk_f16_f32 v39, v38, v39
	v_pk_mul_f32 v[40:41], v[40:41], v[42:43]
	v_cvt_f32_f16_sdwa v43, v85 dst_sel:DWORD dst_unused:UNUSED_PAD src0_sel:WORD_1
	v_cvt_pk_f16_f32 v42, v40, v41
	v_cvt_f32_f16_e32 v40, v85
	v_max_f32_e32 v34, 0xc1f00000, v34
	v_mul_f32_e32 v34, 0xbfb8aa3b, v34
	v_exp_f32_e32 v34, v34
	v_max_f32_e32 v40, 0xc1f00000, v40
	v_mul_f32_e32 v40, 0xbfb8aa3b, v40
	v_exp_f32_e32 v41, v40
	v_add_f32_e32 v34, 1.0, v34
	v_rcp_f32_e32 v40, v34
	v_pack_b32_f16 v38, v45, v39
	v_add_f32_e32 v34, 1.0, v41
	v_rcp_f32_e32 v41, v34
	v_mov_b32_e32 v34, v35
	v_max_f32_e32 v35, 0xc1f00000, v43
	v_mul_f32_e32 v35, 0xbfb8aa3b, v35
	v_exp_f32_e32 v43, v35
	v_mov_b32_e32 v35, v36
	v_pk_mul_f32 v[34:35], v[34:35], v[40:41]
	v_cvt_f32_f16_e32 v36, v78
	v_cvt_pk_f16_f32 v34, v34, v35
	v_add_f32_e32 v35, 1.0, v43
	v_rcp_f32_e32 v35, v35
	v_alignbit_b32 v40, v34, v42, 16
	v_lshrrev_b32_e32 v41, 16, v34
	v_max_f32_e32 v34, 0xc1f00000, v36
	v_alignbit_b32 v39, v42, v39, 16
	v_fma_mixhi_f16 v41, v37, v35, 0
	v_mul_f32_e32 v34, 0xbfb8aa3b, v34
	v_cvt_f32_f16_sdwa v37, v78 dst_sel:DWORD dst_unused:UNUSED_PAD src0_sel:WORD_1
	v_exp_f32_e32 v36, v34
	global_store_dwordx4 v[50:51], v[38:41], off offset:256
	v_lshl_add_u64 v[34:35], v[192:193], 0, v[184:185]
	v_max_f32_e32 v37, 0xc1f00000, v37
	v_cvt_f32_f16_e32 v38, v79
	v_add_f32_e32 v36, 1.0, v36
	v_mul_f32_e32 v37, 0xbfb8aa3b, v37
	v_rcp_f32_e32 v36, v36
	v_max_f32_e32 v38, 0xc1f00000, v38
	v_exp_f32_e32 v37, v37
	v_mul_f32_e32 v38, 0xbfb8aa3b, v38
	v_exp_f32_e32 v38, v38
	v_fma_mixlo_f16 v39, v28, v36, 0
	v_add_f32_e32 v28, 1.0, v37
	v_rcp_f32_e32 v36, v28
	v_add_f32_e32 v28, 1.0, v38
	v_rcp_f32_e32 v37, v28
	v_cvt_f32_f16_sdwa v38, v79 dst_sel:DWORD dst_unused:UNUSED_PAD src0_sel:WORD_1
	v_mov_b32_e32 v28, v29
	v_mov_b32_e32 v29, v30
	v_cvt_f32_f16_e32 v30, v80
	v_pk_mul_f32 v[28:29], v[28:29], v[36:37]
	v_max_f32_e32 v36, 0xc1f00000, v38
	v_mul_f32_e32 v36, 0xbfb8aa3b, v36
	v_max_f32_e32 v30, 0xc1f00000, v30
	v_exp_f32_e32 v36, v36
	v_mul_f32_e32 v30, 0xbfb8aa3b, v30
	v_exp_f32_e32 v30, v30
	v_cvt_pk_f16_f32 v29, v28, v29
	v_add_f32_e32 v28, 1.0, v36
	v_rcp_f32_e32 v36, v28
	v_add_f32_e32 v28, 1.0, v30
	v_rcp_f32_e32 v37, v28
	v_pk_mov_b32 v[30:31], v[30:31], v[24:25] op_sel:[1,0]
	v_cvt_f32_f16_sdwa v24, v80 dst_sel:DWORD dst_unused:UNUSED_PAD src0_sel:WORD_1
	v_pack_b32_f16 v28, v39, v29
	v_pk_mul_f32 v[30:31], v[30:31], v[36:37]
	v_cvt_f32_f16_sdwa v37, v81 dst_sel:DWORD dst_unused:UNUSED_PAD src0_sel:WORD_1
	v_cvt_pk_f16_f32 v36, v30, v31
	v_cvt_f32_f16_e32 v30, v81
	v_max_f32_e32 v24, 0xc1f00000, v24
	v_mul_f32_e32 v24, 0xbfb8aa3b, v24
	v_exp_f32_e32 v24, v24
	v_max_f32_e32 v30, 0xc1f00000, v30
	v_mul_f32_e32 v30, 0xbfb8aa3b, v30
	v_exp_f32_e32 v31, v30
	v_add_f32_e32 v24, 1.0, v24
	v_rcp_f32_e32 v30, v24
	v_alignbit_b32 v29, v36, v29, 16
	v_add_f32_e32 v24, 1.0, v31
	v_rcp_f32_e32 v31, v24
	v_mov_b32_e32 v24, v25
	v_mov_b32_e32 v25, v26
	v_cvt_f32_f16_e32 v26, v74
	v_pk_mul_f32 v[24:25], v[24:25], v[30:31]
	global_store_dwordx4 v[50:51], v[46:49], off
	v_cvt_pk_f16_f32 v24, v24, v25
	v_max_f32_e32 v25, 0xc1f00000, v37
	v_mul_f32_e32 v25, 0xbfb8aa3b, v25
	v_exp_f32_e32 v25, v25
	v_alignbit_b32 v30, v24, v36, 16
	v_lshrrev_b32_e32 v31, 16, v24
	v_add_f32_e32 v24, 1.0, v25
	v_rcp_f32_e32 v24, v24
	v_max_f32_e32 v25, 0xc1f00000, v26
	v_mul_f32_e32 v25, 0xbfb8aa3b, v25
	v_exp_f32_e32 v25, v25
	v_fma_mixhi_f16 v31, v27, v24, 0
	v_cvt_f32_f16_sdwa v24, v74 dst_sel:DWORD dst_unused:UNUSED_PAD src0_sel:WORD_1
	v_cvt_f32_f16_e32 v26, v75
	v_add_f32_e32 v25, 1.0, v25
	v_rcp_f32_e32 v25, v25
	v_max_f32_e32 v24, 0xc1f00000, v24
	v_mul_f32_e32 v24, 0xbfb8aa3b, v24
	v_max_f32_e32 v26, 0xc1f00000, v26
	v_exp_f32_e32 v24, v24
	v_mul_f32_e32 v26, 0xbfb8aa3b, v26
	v_exp_f32_e32 v26, v26
	v_fma_mixlo_f16 v27, v20, v25, 0
	v_add_f32_e32 v20, 1.0, v24
	v_rcp_f32_e32 v24, v20
	v_add_f32_e32 v20, 1.0, v26
	v_rcp_f32_e32 v25, v20
	v_cvt_f32_f16_sdwa v26, v75 dst_sel:DWORD dst_unused:UNUSED_PAD src0_sel:WORD_1
	v_mov_b32_e32 v20, v21
	v_mov_b32_e32 v21, v22
	v_cvt_f32_f16_e32 v22, v76
	v_max_f32_e32 v26, 0xc1f00000, v26
	v_mul_f32_e32 v26, 0xbfb8aa3b, v26
	v_exp_f32_e32 v26, v26
	v_max_f32_e32 v22, 0xc1f00000, v22
	v_mul_f32_e32 v22, 0xbfb8aa3b, v22
	v_exp_f32_e32 v22, v22
	v_pk_mul_f32 v[20:21], v[20:21], v[24:25]
	v_add_f32_e32 v24, 1.0, v26
	v_rcp_f32_e32 v24, v24
	v_add_f32_e32 v22, 1.0, v22
	v_rcp_f32_e32 v25, v22
	v_pk_mov_b32 v[22:23], v[22:23], v[16:17] op_sel:[1,0]
	v_cvt_f32_f16_sdwa v16, v76 dst_sel:DWORD dst_unused:UNUSED_PAD src0_sel:WORD_1
	v_cvt_pk_f16_f32 v21, v20, v21
	v_pk_mul_f32 v[22:23], v[22:23], v[24:25]
	v_cvt_f32_f16_sdwa v25, v77 dst_sel:DWORD dst_unused:UNUSED_PAD src0_sel:WORD_1
	v_cvt_pk_f16_f32 v24, v22, v23
	v_cvt_f32_f16_e32 v22, v77
	v_max_f32_e32 v16, 0xc1f00000, v16
	v_mul_f32_e32 v16, 0xbfb8aa3b, v16
	v_exp_f32_e32 v16, v16
	v_max_f32_e32 v22, 0xc1f00000, v22
	v_mul_f32_e32 v22, 0xbfb8aa3b, v22
	v_exp_f32_e32 v23, v22
	v_add_f32_e32 v16, 1.0, v16
	v_rcp_f32_e32 v22, v16
	v_pack_b32_f16 v20, v27, v21
	v_add_f32_e32 v16, 1.0, v23
	v_rcp_f32_e32 v23, v16
	v_mov_b32_e32 v16, v17
	v_max_f32_e32 v17, 0xc1f00000, v25
	v_mul_f32_e32 v17, 0xbfb8aa3b, v17
	v_exp_f32_e32 v25, v17
	v_mov_b32_e32 v17, v18
	v_pk_mul_f32 v[16:17], v[16:17], v[22:23]
	v_cvt_f32_f16_e32 v18, v70
	v_cvt_pk_f16_f32 v16, v16, v17
	v_add_f32_e32 v17, 1.0, v25
	v_rcp_f32_e32 v17, v17
	v_alignbit_b32 v22, v16, v24, 16
	v_lshrrev_b32_e32 v23, 16, v16
	v_max_f32_e32 v16, 0xc1f00000, v18
	v_alignbit_b32 v21, v24, v21, 16
	v_fma_mixhi_f16 v23, v19, v17, 0
	v_mul_f32_e32 v16, 0xbfb8aa3b, v16
	v_cvt_f32_f16_sdwa v19, v70 dst_sel:DWORD dst_unused:UNUSED_PAD src0_sel:WORD_1
	v_exp_f32_e32 v18, v16
	global_store_dwordx4 v[34:35], v[20:23], off offset:256
	v_lshl_add_u64 v[16:17], v[192:193], 0, v[186:187]
	v_max_f32_e32 v19, 0xc1f00000, v19
	v_cvt_f32_f16_e32 v20, v71
	v_add_f32_e32 v18, 1.0, v18
	v_mul_f32_e32 v19, 0xbfb8aa3b, v19
	v_rcp_f32_e32 v18, v18
	v_max_f32_e32 v20, 0xc1f00000, v20
	v_exp_f32_e32 v19, v19
	v_mul_f32_e32 v20, 0xbfb8aa3b, v20
	v_exp_f32_e32 v20, v20
	v_fma_mixlo_f16 v21, v12, v18, 0
	v_add_f32_e32 v12, 1.0, v19
	v_rcp_f32_e32 v18, v12
	v_add_f32_e32 v12, 1.0, v20
	v_rcp_f32_e32 v19, v12
	v_cvt_f32_f16_sdwa v20, v71 dst_sel:DWORD dst_unused:UNUSED_PAD src0_sel:WORD_1
	v_mov_b32_e32 v12, v13
	v_mov_b32_e32 v13, v14
	v_cvt_f32_f16_e32 v14, v72
	v_pk_mul_f32 v[12:13], v[12:13], v[18:19]
	v_max_f32_e32 v18, 0xc1f00000, v20
	v_mul_f32_e32 v18, 0xbfb8aa3b, v18
	v_max_f32_e32 v14, 0xc1f00000, v14
	v_exp_f32_e32 v18, v18
	v_mul_f32_e32 v14, 0xbfb8aa3b, v14
	v_exp_f32_e32 v14, v14
	v_cvt_pk_f16_f32 v13, v12, v13
	v_add_f32_e32 v12, 1.0, v18
	v_rcp_f32_e32 v18, v12
	v_add_f32_e32 v12, 1.0, v14
	v_rcp_f32_e32 v19, v12
	v_pk_mov_b32 v[14:15], v[14:15], v[8:9] op_sel:[1,0]
	v_cvt_f32_f16_sdwa v8, v72 dst_sel:DWORD dst_unused:UNUSED_PAD src0_sel:WORD_1
	v_pack_b32_f16 v12, v21, v13
	v_pk_mul_f32 v[14:15], v[14:15], v[18:19]
	v_cvt_f32_f16_sdwa v19, v73 dst_sel:DWORD dst_unused:UNUSED_PAD src0_sel:WORD_1
	v_cvt_pk_f16_f32 v18, v14, v15
	v_cvt_f32_f16_e32 v14, v73
	v_max_f32_e32 v8, 0xc1f00000, v8
	v_mul_f32_e32 v8, 0xbfb8aa3b, v8
	v_exp_f32_e32 v8, v8
	v_max_f32_e32 v14, 0xc1f00000, v14
	v_mul_f32_e32 v14, 0xbfb8aa3b, v14
	v_exp_f32_e32 v15, v14
	v_add_f32_e32 v8, 1.0, v8
	v_rcp_f32_e32 v14, v8
	v_alignbit_b32 v13, v18, v13, 16
	v_add_f32_e32 v8, 1.0, v15
	v_rcp_f32_e32 v15, v8
	v_mov_b32_e32 v8, v9
	v_mov_b32_e32 v9, v10
	v_cvt_f32_f16_e32 v10, v66
	v_pk_mul_f32 v[8:9], v[8:9], v[14:15]
	global_store_dwordx4 v[34:35], v[28:31], off
	v_cvt_pk_f16_f32 v8, v8, v9
	v_max_f32_e32 v9, 0xc1f00000, v19
	v_mul_f32_e32 v9, 0xbfb8aa3b, v9
	v_exp_f32_e32 v9, v9
	v_alignbit_b32 v14, v8, v18, 16
	v_lshrrev_b32_e32 v15, 16, v8
	v_add_f32_e32 v8, 1.0, v9
	v_rcp_f32_e32 v8, v8
	v_max_f32_e32 v9, 0xc1f00000, v10
	v_mul_f32_e32 v9, 0xbfb8aa3b, v9
	v_exp_f32_e32 v9, v9
	v_fma_mixhi_f16 v15, v11, v8, 0
	v_cvt_f32_f16_sdwa v8, v66 dst_sel:DWORD dst_unused:UNUSED_PAD src0_sel:WORD_1
	v_cvt_f32_f16_e32 v10, v67
	v_add_f32_e32 v9, 1.0, v9
	v_rcp_f32_e32 v9, v9
	v_max_f32_e32 v8, 0xc1f00000, v8
	v_mul_f32_e32 v8, 0xbfb8aa3b, v8
	v_max_f32_e32 v10, 0xc1f00000, v10
	v_exp_f32_e32 v8, v8
	v_mul_f32_e32 v10, 0xbfb8aa3b, v10
	v_exp_f32_e32 v10, v10
	v_fma_mixlo_f16 v11, v4, v9, 0
	v_add_f32_e32 v4, 1.0, v8
	v_rcp_f32_e32 v8, v4
	v_add_f32_e32 v4, 1.0, v10
	v_rcp_f32_e32 v9, v4
	v_cvt_f32_f16_sdwa v10, v67 dst_sel:DWORD dst_unused:UNUSED_PAD src0_sel:WORD_1
	v_mov_b32_e32 v4, v5
	v_mov_b32_e32 v5, v6
	v_cvt_f32_f16_e32 v6, v68
	v_max_f32_e32 v10, 0xc1f00000, v10
	v_mul_f32_e32 v10, 0xbfb8aa3b, v10
	v_exp_f32_e32 v10, v10
	v_max_f32_e32 v6, 0xc1f00000, v6
	v_mul_f32_e32 v6, 0xbfb8aa3b, v6
	v_exp_f32_e32 v6, v6
	v_pk_mul_f32 v[4:5], v[4:5], v[8:9]
	v_add_f32_e32 v8, 1.0, v10
	v_rcp_f32_e32 v8, v8
	v_add_f32_e32 v6, 1.0, v6
	v_rcp_f32_e32 v9, v6
	v_pk_mov_b32 v[6:7], v[6:7], v[0:1] op_sel:[1,0]
	v_cvt_f32_f16_sdwa v0, v68 dst_sel:DWORD dst_unused:UNUSED_PAD src0_sel:WORD_1
	v_cvt_pk_f16_f32 v5, v4, v5
	v_pk_mul_f32 v[6:7], v[6:7], v[8:9]
	v_cvt_f32_f16_sdwa v9, v69 dst_sel:DWORD dst_unused:UNUSED_PAD src0_sel:WORD_1
	v_cvt_pk_f16_f32 v8, v6, v7
	v_cvt_f32_f16_e32 v6, v69
	v_max_f32_e32 v0, 0xc1f00000, v0
	v_mul_f32_e32 v0, 0xbfb8aa3b, v0
	v_exp_f32_e32 v0, v0
	v_max_f32_e32 v6, 0xc1f00000, v6
	v_mul_f32_e32 v6, 0xbfb8aa3b, v6
	v_exp_f32_e32 v7, v6
	v_add_f32_e32 v0, 1.0, v0
	v_rcp_f32_e32 v6, v0
	v_pack_b32_f16 v4, v11, v5
	v_add_f32_e32 v0, 1.0, v7
	v_rcp_f32_e32 v7, v0
	v_max_f32_e32 v0, 0xc1f00000, v9
	v_mul_f32_e32 v0, 0xbfb8aa3b, v0
	v_exp_f32_e32 v9, v0
	v_mov_b32_e32 v0, v1
	v_mov_b32_e32 v1, v2
	v_pk_mul_f32 v[0:1], v[0:1], v[6:7]
	v_add_f32_e32 v2, 1.0, v9
	v_rcp_f32_e32 v2, v2
	v_cvt_pk_f16_f32 v0, v0, v1
	v_lshrrev_b32_e32 v7, 16, v0
	v_alignbit_b32 v5, v8, v5, 16
	v_alignbit_b32 v6, v0, v8, 16
	v_fma_mixhi_f16 v7, v3, v2, 0
	global_store_dwordx4 v[16:17], v[12:15], off
	global_store_dwordx4 v[16:17], v[4:7], off offset:256
	s_and_b64 vcc, exec, s[4:5]
	s_mov_b32 s31, s30
	s_mov_b32 s34, s29
	s_mov_b64 s[12:13], s[0:1]
	s_mov_b64 s[10:11], s[2:3]
	s_cbranch_vccz .LBB0_955
	s_waitcnt vmcnt(0)
	s_cmpk_gt_u32 s19, 0xff
	s_cbranch_scc1 .LBB0_962
	s_barrier

.LBB0_1117:
	s_add_i32 s41, s22, 2
	s_add_u32 s20, s14, 0x100
	s_addc_u32 s21, s15, 0
	s_add_i32 s42, 0, 0x10000
	s_waitcnt vmcnt(0)
	v_add_u32_e32 v102, s42, v230
	ds_read_b128 v[78:81], v102
	ds_read_b128 v[94:97], v102 offset:2048
	ds_read_b128 v[86:89], v102 offset:1024
	ds_read_b128 v[102:105], v102 offset:3072
	s_cmp_eq_u32 s38, s22
	s_cselect_b32 s22, s18, s39
	s_cselect_b32 s25, s17, s21
	s_cselect_b32 s24, s16, s20
	s_cselect_b32 s23, s19, s40
	v_lshl_add_u64 v[178:179], s[14:15], 0, v[200:201]
	s_add_i32 m0, s28, 0xc000
	ds_read_b128 v[122:125], v232
	ds_read_b128 v[130:133], v232 offset:2048
	ds_read_b128 v[154:157], v232 offset:4096
	ds_read_b128 v[170:173], v232 offset:6144
	ds_read_b128 v[126:129], v232 offset:1024
	ds_read_b128 v[134:137], v232 offset:3072
	ds_read_b128 v[158:161], v232 offset:5120
	ds_read_b128 v[174:177], v232 offset:7168
	global_load_lds_dwordx4 v[178:179], off
	v_lshl_add_u64 v[178:179], s[14:15], 0, v[202:203]
	s_add_i32 m0, s28, 0xe000
	s_nop 0
	global_load_lds_dwordx4 v[178:179], off
	s_waitcnt lgkmcnt(8)
	s_waitcnt vmcnt(10)
	s_barrier
	s_waitcnt lgkmcnt(7)
	s_setprio 1
	v_mfma_f32_16x16x32_f16 v[166:169], v[78:81], v[122:125], v[166:169]
	v_mfma_f32_16x16x32_f16 v[162:165], v[94:97], v[122:125], v[162:165]
	s_waitcnt lgkmcnt(6)
	v_mfma_f32_16x16x32_f16 v[150:153], v[78:81], v[130:133], v[150:153]
	v_mfma_f32_16x16x32_f16 v[142:145], v[94:97], v[130:133], v[142:145]
	s_waitcnt lgkmcnt(5)
	v_mfma_f32_16x16x32_f16 v[110:113], v[78:81], v[154:157], v[110:113]
	v_mfma_f32_16x16x32_f16 v[106:109], v[94:97], v[154:157], v[106:109]
	s_waitcnt lgkmcnt(4)
	v_mfma_f32_16x16x32_f16 v[82:85], v[78:81], v[170:173], v[82:85]
	v_mfma_f32_16x16x32_f16 v[74:77], v[94:97], v[170:173], v[74:77]
	s_waitcnt lgkmcnt(3)
	v_mfma_f32_16x16x32_f16 v[166:169], v[86:89], v[126:129], v[166:169]
	v_mfma_f32_16x16x32_f16 v[162:165], v[102:105], v[126:129], v[162:165]
	s_waitcnt lgkmcnt(2)
	v_mfma_f32_16x16x32_f16 v[150:153], v[86:89], v[134:137], v[150:153]
	v_mfma_f32_16x16x32_f16 v[142:145], v[102:105], v[134:137], v[142:145]
	s_waitcnt lgkmcnt(1)
	v_mfma_f32_16x16x32_f16 v[110:113], v[86:89], v[158:161], v[110:113]
	v_mfma_f32_16x16x32_f16 v[106:109], v[102:105], v[158:161], v[106:109]
	s_waitcnt lgkmcnt(0)
	v_mfma_f32_16x16x32_f16 v[82:85], v[86:89], v[174:177], v[82:85]
	v_mfma_f32_16x16x32_f16 v[74:77], v[102:105], v[174:177], v[74:77]
	s_setprio 0
	s_barrier
	s_add_i32 s43, 0, 0x14000
	s_add_i32 s14, s42, s13
	v_add_u32_e32 v190, s43, v230
	v_lshl_add_u64 v[204:205], s[22:23], 0, v[32:33]
	s_mov_b32 m0, s14
	ds_read_b128 v[178:181], v190
	ds_read_b128 v[186:189], v190 offset:2048
	ds_read_b128 v[182:185], v190 offset:1024
	ds_read_b128 v[190:193], v190 offset:3072
	global_load_lds_dwordx4 v[204:205], off
	v_lshl_add_u64 v[206:207], s[22:23], 0, v[198:199]
	s_add_i32 m0, s14, 0x2000
	s_nop 0
	global_load_lds_dwordx4 v[206:207], off
	s_waitcnt vmcnt(10)
	s_barrier
	s_waitcnt lgkmcnt(3)
	s_setprio 1
	v_mfma_f32_16x16x32_f16 v[146:149], v[178:181], v[122:125], v[146:149]
	v_mfma_f32_16x16x32_f16 v[118:121], v[178:181], v[130:133], v[118:121]
	s_waitcnt lgkmcnt(2)
	v_mfma_f32_16x16x32_f16 v[114:117], v[186:189], v[130:133], v[114:117]
	v_mfma_f32_16x16x32_f16 v[98:101], v[178:181], v[154:157], v[98:101]
	v_mfma_f32_16x16x32_f16 v[90:93], v[186:189], v[154:157], v[90:93]
	v_mfma_f32_16x16x32_f16 v[70:73], v[178:181], v[170:173], v[70:73]
	s_waitcnt lgkmcnt(1)
	v_mfma_f32_16x16x32_f16 v[66:69], v[186:189], v[170:173], v[66:69]
	v_mfma_f32_16x16x32_f16 v[146:149], v[182:185], v[126:129], v[146:149]
	v_mfma_f32_16x16x32_f16 v[122:125], v[186:189], v[122:125], v[138:141]
	v_mfma_f32_16x16x32_f16 v[118:121], v[182:185], v[134:137], v[118:121]
	s_waitcnt lgkmcnt(0)
	v_mfma_f32_16x16x32_f16 v[114:117], v[190:193], v[134:137], v[114:117]
	v_mfma_f32_16x16x32_f16 v[98:101], v[182:185], v[158:161], v[98:101]
	v_mfma_f32_16x16x32_f16 v[90:93], v[190:193], v[158:161], v[90:93]
	v_mfma_f32_16x16x32_f16 v[70:73], v[182:185], v[174:177], v[70:73]
	v_mfma_f32_16x16x32_f16 v[66:69], v[190:193], v[174:177], v[66:69]
	v_mfma_f32_16x16x32_f16 v[122:125], v[190:193], v[126:129], v[122:125]
	s_setprio 0
	s_mov_b32 m0, s28
	v_lshl_add_u64 v[208:209], s[24:25], 0, v[32:33]
	s_barrier
	ds_read_b128 v[126:129], v232 offset:16384
	ds_read_b128 v[134:137], v232 offset:18432
	ds_read_b128 v[154:157], v232 offset:20480
	ds_read_b128 v[170:173], v232 offset:22528
	ds_read_b128 v[130:133], v232 offset:17408
	ds_read_b128 v[138:141], v232 offset:19456
	ds_read_b128 v[158:161], v232 offset:21504
	ds_read_b128 v[174:177], v232 offset:23552
	global_load_lds_dwordx4 v[208:209], off
	v_lshl_add_u64 v[210:211], s[24:25], 0, v[198:199]
	s_mov_b32 m0, s29
	s_nop 0
	global_load_lds_dwordx4 v[210:211], off
	s_barrier
	s_waitcnt lgkmcnt(7)
	s_setprio 1
	v_mfma_f32_16x16x32_f16 v[62:65], v[78:81], v[126:129], v[62:65]
	v_mfma_f32_16x16x32_f16 v[58:61], v[94:97], v[126:129], v[58:61]
	s_waitcnt lgkmcnt(6)
	v_mfma_f32_16x16x32_f16 v[46:49], v[78:81], v[134:137], v[46:49]
	v_mfma_f32_16x16x32_f16 v[42:45], v[94:97], v[134:137], v[42:45]
	s_waitcnt lgkmcnt(5)
	v_mfma_f32_16x16x32_f16 v[28:31], v[78:81], v[154:157], v[28:31]
	v_mfma_f32_16x16x32_f16 v[24:27], v[94:97], v[154:157], v[24:27]
	s_waitcnt lgkmcnt(4)
	v_mfma_f32_16x16x32_f16 v[12:15], v[78:81], v[170:173], v[12:15]
	v_mfma_f32_16x16x32_f16 v[8:11], v[94:97], v[170:173], v[8:11]
	s_waitcnt lgkmcnt(3)
	v_mfma_f32_16x16x32_f16 v[62:65], v[86:89], v[130:133], v[62:65]
	v_mfma_f32_16x16x32_f16 v[58:61], v[102:105], v[130:133], v[58:61]
	s_waitcnt lgkmcnt(2)
	v_mfma_f32_16x16x32_f16 v[46:49], v[86:89], v[138:141], v[46:49]
	v_mfma_f32_16x16x32_f16 v[42:45], v[102:105], v[138:141], v[42:45]
	s_waitcnt lgkmcnt(1)
	v_mfma_f32_16x16x32_f16 v[28:31], v[86:89], v[158:161], v[28:31]
	v_mfma_f32_16x16x32_f16 v[24:27], v[102:105], v[158:161], v[24:27]
	s_waitcnt lgkmcnt(0)
	v_mfma_f32_16x16x32_f16 v[12:15], v[86:89], v[174:177], v[12:15]
	v_mfma_f32_16x16x32_f16 v[8:11], v[102:105], v[174:177], v[8:11]
	s_setprio 0
	s_barrier
	s_add_u32 s14, s22, 0x40000
	s_addc_u32 s15, s23, 0
	s_add_i32 s42, s43, s13
	v_lshl_add_u64 v[78:79], s[14:15], 0, v[32:33]
	s_mov_b32 m0, s42
	s_nop 0
	global_load_lds_dwordx4 v[78:79], off
	v_lshl_add_u64 v[78:79], s[14:15], 0, v[198:199]
	s_add_i32 m0, s42, 0x2000
	s_nop 0
	global_load_lds_dwordx4 v[78:79], off
	s_waitcnt vmcnt(10)
	s_barrier
	s_setprio 1
	v_mfma_f32_16x16x32_f16 v[54:57], v[178:181], v[126:129], v[54:57]
	v_mfma_f32_16x16x32_f16 v[50:53], v[186:189], v[126:129], v[50:53]
	v_mfma_f32_16x16x32_f16 v[38:41], v[178:181], v[134:137], v[38:41]
	v_mfma_f32_16x16x32_f16 v[34:37], v[186:189], v[134:137], v[34:37]
	v_mfma_f32_16x16x32_f16 v[20:23], v[178:181], v[154:157], v[20:23]
	v_mfma_f32_16x16x32_f16 v[16:19], v[186:189], v[154:157], v[16:19]
	v_mfma_f32_16x16x32_f16 v[4:7], v[178:181], v[170:173], v[4:7]
	v_mfma_f32_16x16x32_f16 v[0:3], v[186:189], v[170:173], v[0:3]
	v_mfma_f32_16x16x32_f16 v[54:57], v[182:185], v[130:133], v[54:57]
	v_mfma_f32_16x16x32_f16 v[50:53], v[190:193], v[130:133], v[50:53]
	v_mfma_f32_16x16x32_f16 v[38:41], v[182:185], v[138:141], v[38:41]
	v_mfma_f32_16x16x32_f16 v[34:37], v[190:193], v[138:141], v[34:37]
	v_mfma_f32_16x16x32_f16 v[20:23], v[182:185], v[158:161], v[20:23]
	v_mfma_f32_16x16x32_f16 v[16:19], v[190:193], v[158:161], v[16:19]
	v_mfma_f32_16x16x32_f16 v[4:7], v[182:185], v[174:177], v[4:7]
	v_mfma_f32_16x16x32_f16 v[0:3], v[190:193], v[174:177], v[0:3]
	s_setprio 0
	s_add_i32 s42, 0, 0x18000
	v_add_u32_e32 v102, s42, v230
	s_barrier
	ds_read_b128 v[78:81], v102
	ds_read_b128 v[86:89], v102 offset:1024
	ds_read_b128 v[94:97], v102 offset:2048
	ds_read_b128 v[102:105], v102 offset:3072
	s_add_u32 s14, s24, 0x40000
	s_addc_u32 s15, s25, 0
	s_mov_b32 m0, s30
	v_lshl_add_u64 v[138:139], s[14:15], 0, v[32:33]
	ds_read_b128 v[126:129], v232 offset:32768
	ds_read_b128 v[130:133], v232 offset:33792
	ds_read_b128 v[134:137], v232 offset:34816
	ds_read_b128 v[154:157], v232 offset:35840
	ds_read_b128 v[158:161], v232 offset:36864
	ds_read_b128 v[174:177], v232 offset:38912
	ds_read_b128 v[170:173], v232 offset:37888
	ds_read_b128 v[178:181], v232 offset:39936
	global_load_lds_dwordx4 v[138:139], off
	v_lshl_add_u64 v[138:139], s[14:15], 0, v[198:199]
	s_mov_b32 m0, s31
	s_nop 0
	global_load_lds_dwordx4 v[138:139], off
	s_waitcnt lgkmcnt(8)
	s_waitcnt vmcnt(10)
	s_barrier
	s_waitcnt lgkmcnt(6)
	s_setprio 1
	v_mfma_f32_16x16x32_f16 v[138:141], v[78:81], v[126:129], v[166:169]
	v_mfma_f32_16x16x32_f16 v[166:169], v[86:89], v[130:133], v[138:141]
	v_mfma_f32_16x16x32_f16 v[138:141], v[94:97], v[126:129], v[162:165]
	v_mfma_f32_16x16x32_f16 v[162:165], v[102:105], v[130:133], v[138:141]
	s_waitcnt lgkmcnt(4)
	v_mfma_f32_16x16x32_f16 v[138:141], v[78:81], v[134:137], v[150:153]
	v_mfma_f32_16x16x32_f16 v[150:153], v[86:89], v[154:157], v[138:141]
	s_waitcnt lgkmcnt(3)
	v_mfma_f32_16x16x32_f16 v[138:141], v[94:97], v[134:137], v[142:145]
	v_mfma_f32_16x16x32_f16 v[110:113], v[78:81], v[158:161], v[110:113]
	s_waitcnt lgkmcnt(2)
	v_mfma_f32_16x16x32_f16 v[106:109], v[94:97], v[158:161], v[106:109]
	v_mfma_f32_16x16x32_f16 v[82:85], v[78:81], v[174:177], v[82:85]
	v_mfma_f32_16x16x32_f16 v[74:77], v[94:97], v[174:177], v[74:77]
	v_mfma_f32_16x16x32_f16 v[142:145], v[102:105], v[154:157], v[138:141]
	s_waitcnt lgkmcnt(1)
	v_mfma_f32_16x16x32_f16 v[110:113], v[86:89], v[170:173], v[110:113]
	v_mfma_f32_16x16x32_f16 v[106:109], v[102:105], v[170:173], v[106:109]
	s_waitcnt lgkmcnt(0)
	v_mfma_f32_16x16x32_f16 v[82:85], v[86:89], v[178:181], v[82:85]
	v_mfma_f32_16x16x32_f16 v[74:77], v[102:105], v[178:181], v[74:77]
	s_setprio 0
	s_barrier
	s_add_i32 s24, 0, 0x1c000
	v_add_u32_e32 v138, s24, v230
	s_add_i32 s14, s42, s13
	ds_read_b128 v[182:185], v138
	ds_read_b128 v[190:193], v138 offset:2048
	ds_read_b128 v[186:189], v138 offset:1024
	ds_read_b128 v[194:197], v138 offset:3072
	v_lshl_add_u64 v[138:139], v[204:205], 0, s[84:85]
	s_mov_b32 m0, s14
	s_nop 0
	global_load_lds_dwordx4 v[138:139], off
	v_lshl_add_u64 v[138:139], v[206:207], 0, s[84:85]
	s_add_i32 m0, s14, 0x2000
	s_nop 0
	global_load_lds_dwordx4 v[138:139], off
	s_waitcnt vmcnt(10)
	s_barrier
	s_waitcnt lgkmcnt(2)
	s_setprio 1
	v_mfma_f32_16x16x32_f16 v[138:141], v[182:185], v[126:129], v[146:149]
	v_mfma_f32_16x16x32_f16 v[122:125], v[190:193], v[126:129], v[122:125]
	v_mfma_f32_16x16x32_f16 v[118:121], v[182:185], v[134:137], v[118:121]
	v_mfma_f32_16x16x32_f16 v[114:117], v[190:193], v[134:137], v[114:117]
	v_mfma_f32_16x16x32_f16 v[98:101], v[182:185], v[158:161], v[98:101]
	v_mfma_f32_16x16x32_f16 v[90:93], v[190:193], v[158:161], v[90:93]
	v_mfma_f32_16x16x32_f16 v[70:73], v[182:185], v[174:177], v[70:73]
	v_mfma_f32_16x16x32_f16 v[66:69], v[190:193], v[174:177], v[66:69]
	s_waitcnt lgkmcnt(0)
	v_mfma_f32_16x16x32_f16 v[146:149], v[186:189], v[130:133], v[138:141]
	v_mfma_f32_16x16x32_f16 v[138:141], v[194:197], v[130:133], v[122:125]
	v_mfma_f32_16x16x32_f16 v[118:121], v[186:189], v[154:157], v[118:121]
	v_mfma_f32_16x16x32_f16 v[114:117], v[194:197], v[154:157], v[114:117]
	v_mfma_f32_16x16x32_f16 v[98:101], v[186:189], v[170:173], v[98:101]
	v_mfma_f32_16x16x32_f16 v[90:93], v[194:197], v[170:173], v[90:93]
	v_mfma_f32_16x16x32_f16 v[70:73], v[186:189], v[178:181], v[70:73]
	v_mfma_f32_16x16x32_f16 v[66:69], v[194:197], v[178:181], v[66:69]
	s_setprio 0
	s_mov_b32 m0, s34
	v_lshl_add_u64 v[178:179], v[208:209], 0, s[84:85]
	s_barrier
	ds_read_b128 v[122:125], v232 offset:49152
	ds_read_b128 v[130:133], v232 offset:51200
	ds_read_b128 v[154:157], v232 offset:53248
	ds_read_b128 v[170:173], v232 offset:55296
	ds_read_b128 v[126:129], v232 offset:50176
	ds_read_b128 v[134:137], v232 offset:52224
	ds_read_b128 v[158:161], v232 offset:54272
	ds_read_b128 v[174:177], v232 offset:56320
	global_load_lds_dwordx4 v[178:179], off
	v_lshl_add_u64 v[178:179], v[210:211], 0, s[84:85]
	s_mov_b32 m0, s35
	s_nop 0
	global_load_lds_dwordx4 v[178:179], off
	s_barrier
	s_waitcnt lgkmcnt(7)
	s_setprio 1
	v_mfma_f32_16x16x32_f16 v[62:65], v[78:81], v[122:125], v[62:65]
	v_mfma_f32_16x16x32_f16 v[58:61], v[94:97], v[122:125], v[58:61]
	s_waitcnt lgkmcnt(6)
	v_mfma_f32_16x16x32_f16 v[46:49], v[78:81], v[130:133], v[46:49]
	v_mfma_f32_16x16x32_f16 v[42:45], v[94:97], v[130:133], v[42:45]
	s_waitcnt lgkmcnt(5)
	v_mfma_f32_16x16x32_f16 v[28:31], v[78:81], v[154:157], v[28:31]
	v_mfma_f32_16x16x32_f16 v[24:27], v[94:97], v[154:157], v[24:27]
	s_waitcnt lgkmcnt(4)
	v_mfma_f32_16x16x32_f16 v[12:15], v[78:81], v[170:173], v[12:15]
	v_mfma_f32_16x16x32_f16 v[8:11], v[94:97], v[170:173], v[8:11]
	s_waitcnt lgkmcnt(3)
	v_mfma_f32_16x16x32_f16 v[62:65], v[86:89], v[126:129], v[62:65]
	v_mfma_f32_16x16x32_f16 v[58:61], v[102:105], v[126:129], v[58:61]
	s_waitcnt lgkmcnt(2)
	v_mfma_f32_16x16x32_f16 v[46:49], v[86:89], v[134:137], v[46:49]
	v_mfma_f32_16x16x32_f16 v[42:45], v[102:105], v[134:137], v[42:45]
	s_waitcnt lgkmcnt(1)
	v_mfma_f32_16x16x32_f16 v[28:31], v[86:89], v[158:161], v[28:31]
	v_mfma_f32_16x16x32_f16 v[24:27], v[102:105], v[158:161], v[24:27]
	s_waitcnt lgkmcnt(0)
	v_mfma_f32_16x16x32_f16 v[12:15], v[86:89], v[174:177], v[12:15]
	v_mfma_f32_16x16x32_f16 v[8:11], v[102:105], v[174:177], v[8:11]
	s_setprio 0
	s_barrier
	s_add_u32 s14, s22, 0x40080
	s_addc_u32 s15, s23, 0
	s_add_i32 s22, s24, s13
	v_lshl_add_u64 v[78:79], s[14:15], 0, v[32:33]
	s_mov_b32 m0, s22
	s_nop 0
	global_load_lds_dwordx4 v[78:79], off
	v_lshl_add_u64 v[78:79], s[14:15], 0, v[198:199]
	s_add_i32 m0, s22, 0x2000
	s_nop 0
	global_load_lds_dwordx4 v[78:79], off
	s_waitcnt vmcnt(10)
	s_barrier
	s_setprio 1
	v_mfma_f32_16x16x32_f16 v[54:57], v[182:185], v[122:125], v[54:57]
	v_mfma_f32_16x16x32_f16 v[50:53], v[190:193], v[122:125], v[50:53]
	v_mfma_f32_16x16x32_f16 v[38:41], v[182:185], v[130:133], v[38:41]
	v_mfma_f32_16x16x32_f16 v[34:37], v[190:193], v[130:133], v[34:37]
	v_mfma_f32_16x16x32_f16 v[20:23], v[182:185], v[154:157], v[20:23]
	v_mfma_f32_16x16x32_f16 v[16:19], v[190:193], v[154:157], v[16:19]
	v_mfma_f32_16x16x32_f16 v[4:7], v[182:185], v[170:173], v[4:7]
	v_mfma_f32_16x16x32_f16 v[0:3], v[190:193], v[170:173], v[0:3]
	v_mfma_f32_16x16x32_f16 v[54:57], v[186:189], v[126:129], v[54:57]
	v_mfma_f32_16x16x32_f16 v[50:53], v[194:197], v[126:129], v[50:53]
	v_mfma_f32_16x16x32_f16 v[38:41], v[186:189], v[134:137], v[38:41]
	v_mfma_f32_16x16x32_f16 v[34:37], v[194:197], v[134:137], v[34:37]
	v_mfma_f32_16x16x32_f16 v[20:23], v[186:189], v[158:161], v[20:23]
	v_mfma_f32_16x16x32_f16 v[16:19], v[194:197], v[158:161], v[16:19]
	v_mfma_f32_16x16x32_f16 v[4:7], v[186:189], v[174:177], v[4:7]
	v_mfma_f32_16x16x32_f16 v[0:3], v[194:197], v[174:177], v[0:3]
	s_setprio 0
	s_add_u32 s39, s39, 0x100
	s_addc_u32 s40, s40, 0
	s_cmp_ge_u32 s41, s37
	s_mov_b64 s[14:15], s[20:21]
	s_mov_b32 s22, s41
	s_barrier
	s_cbranch_scc0 .LBB0_1117
	v_lshl_or_b32 v124, s12, 8, v231
	s_cmp_eq_u32 s10, 0
	s_movk_i32 s12, 0x5000
	s_cselect_b32 s12, 0xe000, s12
	v_readlane_b32 s14, v252, 51
	s_add_u32 s14, s14, s12
	v_readlane_b32 s12, v252, 52
	s_addc_u32 s15, s12, 0
	v_ashrrev_i32_e32 v125, 31, v124
	v_lshl_add_u64 v[86:87], v[124:125], 2, s[14:15]
	global_load_dwordx4 v[94:97], v[86:87], off offset:16
	global_load_dwordx4 v[102:105], v[86:87], off
	global_load_dwordx4 v[78:81], v[86:87], off offset:528
	s_nop 0
	global_load_dwordx4 v[86:89], v[86:87], off offset:512
	v_lshl_add_u32 v130, s10, 8, v229
	v_or_b32_e32 v128, 16, v130
	v_or_b32_e32 v126, 32, v130
	v_or_b32_e32 v122, 48, v130
	s_cmp_eq_u32 s11, 0
	v_ashrrev_i32_e32 v131, 31, v130
	v_ashrrev_i32_e32 v129, 31, v128
	v_ashrrev_i32_e32 v127, 31, v126
	v_ashrrev_i32_e32 v123, 31, v122
	s_cbranch_scc1 .LBB0_1120
	s_add_i32 s96, s11, -1
	s_lshl_b64 s[10:11], s[96:97], 20
	v_readlane_b32 s14, v252, 11
	v_readlane_b32 s15, v252, 12
	s_add_u32 s10, s14, s10
	s_addc_u32 s11, s15, s11
	v_lshlrev_b64 v[132:133], 2, v[124:125]
	v_lshrrev_b32_e32 v134, 5, v220
	v_mul_u32_u24_e32 v134, 48, v134
	s_nop 0
	v_sub_co_u32_e32 v132, vcc, v132, v134
	s_nop 1
	v_subbrev_co_u32_e32 v133, vcc, 0, v133, vcc
	v_lshl_add_u64 v[132:133], s[10:11], 0, v[132:133]
	s_mov_b64 s[10:11], 0x80000
	v_lshlrev_b64 v[204:205], 12, v[130:131]
	v_lshl_add_u64 v[204:205], v[204:205], 0, v[132:133]
	v_lshl_add_u64 v[212:213], v[204:205], 0, s[10:11]
	v_lshlrev_b64 v[206:207], 12, v[128:129]
	v_lshl_add_u64 v[206:207], v[206:207], 0, v[132:133]
	v_lshl_add_u64 v[214:215], v[206:207], 0, s[10:11]
	v_lshlrev_b64 v[208:209], 12, v[126:127]
	v_lshl_add_u64 v[208:209], v[208:209], 0, v[132:133]
	v_lshl_add_u64 v[216:217], v[208:209], 0, s[10:11]
	v_lshlrev_b64 v[210:211], 12, v[122:123]
	v_lshl_add_u64 v[210:211], v[210:211], 0, v[132:133]
	v_lshl_add_u64 v[218:219], v[210:211], 0, s[10:11]
	s_waitcnt vmcnt(0)
	v_pk_mul_f32 v[172:173], v[166:167], v[102:103]
	v_pk_mul_f32 v[174:175], v[168:169], v[104:105]
	v_pk_mul_f32 v[176:177], v[162:163], v[94:95]
	v_pk_mul_f32 v[178:179], v[164:165], v[96:97]
	s_nop 1
	v_permlane32_swap_b32_e32 v172, v176
	v_permlane32_swap_b32_e32 v173, v177
	v_permlane32_swap_b32_e32 v174, v178
	v_permlane32_swap_b32_e32 v175, v179
	s_nop 0
	global_store_dwordx4 v[204:205], v[172:175], off
	global_store_dwordx4 v[204:205], v[176:179], off offset:64
	v_pk_mul_f32 v[180:181], v[146:147], v[86:87]
	v_pk_mul_f32 v[182:183], v[148:149], v[88:89]
	v_pk_mul_f32 v[184:185], v[138:139], v[78:79]
	v_pk_mul_f32 v[186:187], v[140:141], v[80:81]
	s_nop 1
	v_permlane32_swap_b32_e32 v180, v184
	v_permlane32_swap_b32_e32 v181, v185
	v_permlane32_swap_b32_e32 v182, v186
	v_permlane32_swap_b32_e32 v183, v187
	s_nop 0
	global_store_dwordx4 v[204:205], v[180:183], off offset:512
	global_store_dwordx4 v[204:205], v[184:187], off offset:576
	v_pk_mul_f32 v[188:189], v[150:151], v[102:103]
	v_pk_mul_f32 v[190:191], v[152:153], v[104:105]
	v_pk_mul_f32 v[192:193], v[142:143], v[94:95]
	v_pk_mul_f32 v[194:195], v[144:145], v[96:97]
	s_nop 1
	v_permlane32_swap_b32_e32 v188, v192
	v_permlane32_swap_b32_e32 v189, v193
	v_permlane32_swap_b32_e32 v190, v194
	v_permlane32_swap_b32_e32 v191, v195
	s_nop 0
	global_store_dwordx4 v[206:207], v[188:191], off
	global_store_dwordx4 v[206:207], v[192:195], off offset:64
	v_pk_mul_f32 v[154:155], v[118:119], v[86:87]
	v_pk_mul_f32 v[156:157], v[120:121], v[88:89]
	v_pk_mul_f32 v[158:159], v[114:115], v[78:79]
	v_pk_mul_f32 v[160:161], v[116:117], v[80:81]
	s_nop 1
	v_permlane32_swap_b32_e32 v154, v158
	v_permlane32_swap_b32_e32 v155, v159
	v_permlane32_swap_b32_e32 v156, v160
	v_permlane32_swap_b32_e32 v157, v161
	s_nop 0
	global_store_dwordx4 v[206:207], v[154:157], off offset:512
	global_store_dwordx4 v[206:207], v[158:161], off offset:576
	v_pk_mul_f32 v[172:173], v[110:111], v[102:103]
	v_pk_mul_f32 v[174:175], v[112:113], v[104:105]
	v_pk_mul_f32 v[176:177], v[106:107], v[94:95]
	v_pk_mul_f32 v[178:179], v[108:109], v[96:97]
	s_nop 1
	v_permlane32_swap_b32_e32 v172, v176
	v_permlane32_swap_b32_e32 v173, v177
	v_permlane32_swap_b32_e32 v174, v178
	v_permlane32_swap_b32_e32 v175, v179
	s_nop 0
	global_store_dwordx4 v[208:209], v[172:175], off
	global_store_dwordx4 v[208:209], v[176:179], off offset:64
	v_pk_mul_f32 v[180:181], v[98:99], v[86:87]
	v_pk_mul_f32 v[182:183], v[100:101], v[88:89]
	v_pk_mul_f32 v[184:185], v[90:91], v[78:79]
	v_pk_mul_f32 v[186:187], v[92:93], v[80:81]
	s_nop 1
	v_permlane32_swap_b32_e32 v180, v184
	v_permlane32_swap_b32_e32 v181, v185
	v_permlane32_swap_b32_e32 v182, v186
	v_permlane32_swap_b32_e32 v183, v187
	s_nop 0
	global_store_dwordx4 v[208:209], v[180:183], off offset:512
	global_store_dwordx4 v[208:209], v[184:187], off offset:576
	v_pk_mul_f32 v[188:189], v[82:83], v[102:103]
	v_pk_mul_f32 v[190:191], v[84:85], v[104:105]
	v_pk_mul_f32 v[192:193], v[74:75], v[94:95]
	v_pk_mul_f32 v[194:195], v[76:77], v[96:97]
	s_nop 1
	v_permlane32_swap_b32_e32 v188, v192
	v_permlane32_swap_b32_e32 v189, v193
	v_permlane32_swap_b32_e32 v190, v194
	v_permlane32_swap_b32_e32 v191, v195
	s_nop 0
	global_store_dwordx4 v[210:211], v[188:191], off
	global_store_dwordx4 v[210:211], v[192:195], off offset:64
	v_pk_mul_f32 v[154:155], v[70:71], v[86:87]
	v_pk_mul_f32 v[156:157], v[72:73], v[88:89]
	v_pk_mul_f32 v[158:159], v[66:67], v[78:79]
	v_pk_mul_f32 v[160:161], v[68:69], v[80:81]
	s_nop 1
	v_permlane32_swap_b32_e32 v154, v158
	v_permlane32_swap_b32_e32 v155, v159
	v_permlane32_swap_b32_e32 v156, v160
	v_permlane32_swap_b32_e32 v157, v161
	s_nop 0
	global_store_dwordx4 v[210:211], v[154:157], off offset:512
	global_store_dwordx4 v[210:211], v[158:161], off offset:576
	v_pk_mul_f32 v[172:173], v[62:63], v[102:103]
	v_pk_mul_f32 v[174:175], v[64:65], v[104:105]
	v_pk_mul_f32 v[176:177], v[58:59], v[94:95]
	v_pk_mul_f32 v[178:179], v[60:61], v[96:97]
	s_nop 1
	v_permlane32_swap_b32_e32 v172, v176
	v_permlane32_swap_b32_e32 v173, v177
	v_permlane32_swap_b32_e32 v174, v178
	v_permlane32_swap_b32_e32 v175, v179
	s_nop 0
	global_store_dwordx4 v[212:213], v[172:175], off
	global_store_dwordx4 v[212:213], v[176:179], off offset:64
	v_pk_mul_f32 v[180:181], v[54:55], v[86:87]
	v_pk_mul_f32 v[182:183], v[56:57], v[88:89]
	v_pk_mul_f32 v[184:185], v[50:51], v[78:79]
	v_pk_mul_f32 v[186:187], v[52:53], v[80:81]
	s_nop 1
	v_permlane32_swap_b32_e32 v180, v184
	v_permlane32_swap_b32_e32 v181, v185
	v_permlane32_swap_b32_e32 v182, v186
	v_permlane32_swap_b32_e32 v183, v187
	s_nop 0
	global_store_dwordx4 v[212:213], v[180:183], off offset:512
	global_store_dwordx4 v[212:213], v[184:187], off offset:576
	v_pk_mul_f32 v[188:189], v[46:47], v[102:103]
	v_pk_mul_f32 v[190:191], v[48:49], v[104:105]
	v_pk_mul_f32 v[192:193], v[42:43], v[94:95]
	v_pk_mul_f32 v[194:195], v[44:45], v[96:97]
	s_nop 1
	v_permlane32_swap_b32_e32 v188, v192
	v_permlane32_swap_b32_e32 v189, v193
	v_permlane32_swap_b32_e32 v190, v194
	v_permlane32_swap_b32_e32 v191, v195
	s_nop 0
	global_store_dwordx4 v[214:215], v[188:191], off
	global_store_dwordx4 v[214:215], v[192:195], off offset:64
	v_pk_mul_f32 v[154:155], v[38:39], v[86:87]
	v_pk_mul_f32 v[156:157], v[40:41], v[88:89]
	v_pk_mul_f32 v[158:159], v[34:35], v[78:79]
	v_pk_mul_f32 v[160:161], v[36:37], v[80:81]
	s_nop 1
	v_permlane32_swap_b32_e32 v154, v158
	v_permlane32_swap_b32_e32 v155, v159
	v_permlane32_swap_b32_e32 v156, v160
	v_permlane32_swap_b32_e32 v157, v161
	s_nop 0
	global_store_dwordx4 v[214:215], v[154:157], off offset:512
	global_store_dwordx4 v[214:215], v[158:161], off offset:576
	v_pk_mul_f32 v[172:173], v[28:29], v[102:103]
	v_pk_mul_f32 v[174:175], v[30:31], v[104:105]
	v_pk_mul_f32 v[176:177], v[24:25], v[94:95]
	v_pk_mul_f32 v[178:179], v[26:27], v[96:97]
	s_nop 1
	v_permlane32_swap_b32_e32 v172, v176
	v_permlane32_swap_b32_e32 v173, v177
	v_permlane32_swap_b32_e32 v174, v178
	v_permlane32_swap_b32_e32 v175, v179
	s_nop 0
	global_store_dwordx4 v[216:217], v[172:175], off
	global_store_dwordx4 v[216:217], v[176:179], off offset:64
	v_pk_mul_f32 v[180:181], v[20:21], v[86:87]
	v_pk_mul_f32 v[182:183], v[22:23], v[88:89]
	v_pk_mul_f32 v[184:185], v[16:17], v[78:79]
	v_pk_mul_f32 v[186:187], v[18:19], v[80:81]
	s_nop 1
	v_permlane32_swap_b32_e32 v180, v184
	v_permlane32_swap_b32_e32 v181, v185
	v_permlane32_swap_b32_e32 v182, v186
	v_permlane32_swap_b32_e32 v183, v187
	s_nop 0
	global_store_dwordx4 v[216:217], v[180:183], off offset:512
	global_store_dwordx4 v[216:217], v[184:187], off offset:576
	v_pk_mul_f32 v[188:189], v[12:13], v[102:103]
	v_pk_mul_f32 v[190:191], v[14:15], v[104:105]
	v_pk_mul_f32 v[192:193], v[8:9], v[94:95]
	v_pk_mul_f32 v[194:195], v[10:11], v[96:97]
	s_nop 1
	v_permlane32_swap_b32_e32 v188, v192
	v_permlane32_swap_b32_e32 v189, v193
	v_permlane32_swap_b32_e32 v190, v194
	v_permlane32_swap_b32_e32 v191, v195
	s_nop 0
	global_store_dwordx4 v[218:219], v[188:191], off
	global_store_dwordx4 v[218:219], v[192:195], off offset:64
	v_pk_mul_f32 v[154:155], v[4:5], v[86:87]
	v_pk_mul_f32 v[156:157], v[6:7], v[88:89]
	v_pk_mul_f32 v[158:159], v[0:1], v[78:79]
	v_pk_mul_f32 v[160:161], v[2:3], v[80:81]
	s_nop 1
	v_permlane32_swap_b32_e32 v154, v158
	v_permlane32_swap_b32_e32 v155, v159
	v_permlane32_swap_b32_e32 v156, v160
	v_permlane32_swap_b32_e32 v157, v161
	s_nop 0
	global_store_dwordx4 v[218:219], v[154:157], off offset:512
	global_store_dwordx4 v[218:219], v[158:161], off offset:576
	s_cbranch_execnz .LBB0_1104
	s_branch .LBB0_1103

.LBB0_1276:
	s_add_u32 s16, s14, 0x100
	s_addc_u32 s17, s15, 0
	s_add_i32 s39, 0, 0x10000
	v_add_u32_e32 v152, s39, v137
	ds_read_b128 v[140:143], v152
	ds_read_b128 v[148:151], v152 offset:2048
	ds_read_b128 v[144:147], v152 offset:1024
	ds_read_b128 v[152:155], v152 offset:3072
	s_cmp_eq_u32 s38, 12
	s_cselect_b32 s21, s11, s17
	s_cselect_b32 s20, s10, s16
	s_cselect_b32 s19, s13, s37
	s_cselect_b32 s18, s12, s3
	v_lshl_add_u64 v[188:189], s[14:15], 0, v[132:133]
	s_add_i32 m0, s9, 0xc000
	ds_read_b128 v[156:159], v139
	ds_read_b128 v[164:167], v139 offset:2048
	ds_read_b128 v[172:175], v139 offset:4096
	ds_read_b128 v[180:183], v139 offset:6144
	ds_read_b128 v[160:163], v139 offset:1024
	ds_read_b128 v[168:171], v139 offset:3072
	ds_read_b128 v[176:179], v139 offset:5120
	ds_read_b128 v[184:187], v139 offset:7168
	global_load_lds_dwordx4 v[188:189], off
	v_lshl_add_u64 v[188:189], s[14:15], 0, v[134:135]
	s_add_i32 m0, s9, 0xe000
	s_nop 0
	global_load_lds_dwordx4 v[188:189], off
	s_waitcnt lgkmcnt(8)
	s_waitcnt vmcnt(10)
	s_barrier
	s_waitcnt lgkmcnt(7)
	s_setprio 1
	v_mfma_f32_16x16x32_f16 v[126:129], v[140:143], v[156:159], v[126:129]
	v_mfma_f32_16x16x32_f16 v[122:125], v[148:151], v[156:159], v[122:125]
	s_waitcnt lgkmcnt(6)
	v_mfma_f32_16x16x32_f16 v[110:113], v[140:143], v[164:167], v[110:113]
	v_mfma_f32_16x16x32_f16 v[106:109], v[148:151], v[164:167], v[106:109]
	s_waitcnt lgkmcnt(5)
	v_mfma_f32_16x16x32_f16 v[94:97], v[140:143], v[172:175], v[94:97]
	v_mfma_f32_16x16x32_f16 v[90:93], v[148:151], v[172:175], v[90:93]
	s_waitcnt lgkmcnt(4)
	v_mfma_f32_16x16x32_f16 v[78:81], v[140:143], v[180:183], v[78:81]
	v_mfma_f32_16x16x32_f16 v[74:77], v[148:151], v[180:183], v[74:77]
	s_waitcnt lgkmcnt(3)
	v_mfma_f32_16x16x32_f16 v[126:129], v[144:147], v[160:163], v[126:129]
	v_mfma_f32_16x16x32_f16 v[122:125], v[152:155], v[160:163], v[122:125]
	s_waitcnt lgkmcnt(2)
	v_mfma_f32_16x16x32_f16 v[110:113], v[144:147], v[168:171], v[110:113]
	v_mfma_f32_16x16x32_f16 v[106:109], v[152:155], v[168:171], v[106:109]
	s_waitcnt lgkmcnt(1)
	v_mfma_f32_16x16x32_f16 v[94:97], v[144:147], v[176:179], v[94:97]
	v_mfma_f32_16x16x32_f16 v[90:93], v[152:155], v[176:179], v[90:93]
	s_waitcnt lgkmcnt(0)
	v_mfma_f32_16x16x32_f16 v[78:81], v[144:147], v[184:187], v[78:81]
	v_mfma_f32_16x16x32_f16 v[74:77], v[152:155], v[184:187], v[74:77]
	s_setprio 0
	s_barrier
	s_add_i32 s40, 0, 0x14000
	s_add_i32 s14, s39, s26
	v_add_u32_e32 v200, s40, v137
	v_lshl_add_u64 v[204:205], s[18:19], 0, v[32:33]
	s_mov_b32 m0, s14
	ds_read_b128 v[188:191], v200
	ds_read_b128 v[196:199], v200 offset:2048
	ds_read_b128 v[192:195], v200 offset:1024
	ds_read_b128 v[200:203], v200 offset:3072
	global_load_lds_dwordx4 v[204:205], off
	v_lshl_add_u64 v[206:207], s[18:19], 0, v[130:131]
	s_add_i32 m0, s14, 0x2000
	s_nop 0
	global_load_lds_dwordx4 v[206:207], off
	s_waitcnt vmcnt(10)
	s_barrier
	s_waitcnt lgkmcnt(2)
	s_setprio 1
	v_mfma_f32_16x16x32_f16 v[118:121], v[188:191], v[156:159], v[118:121]
	v_mfma_f32_16x16x32_f16 v[114:117], v[196:199], v[156:159], v[114:117]
	v_mfma_f32_16x16x32_f16 v[102:105], v[188:191], v[164:167], v[102:105]
	v_mfma_f32_16x16x32_f16 v[98:101], v[196:199], v[164:167], v[98:101]
	v_mfma_f32_16x16x32_f16 v[86:89], v[188:191], v[172:175], v[86:89]
	v_mfma_f32_16x16x32_f16 v[82:85], v[196:199], v[172:175], v[82:85]
	v_mfma_f32_16x16x32_f16 v[70:73], v[188:191], v[180:183], v[70:73]
	v_mfma_f32_16x16x32_f16 v[66:69], v[196:199], v[180:183], v[66:69]
	s_waitcnt lgkmcnt(0)
	v_mfma_f32_16x16x32_f16 v[118:121], v[192:195], v[160:163], v[118:121]
	v_mfma_f32_16x16x32_f16 v[114:117], v[200:203], v[160:163], v[114:117]
	v_mfma_f32_16x16x32_f16 v[102:105], v[192:195], v[168:171], v[102:105]
	v_mfma_f32_16x16x32_f16 v[98:101], v[200:203], v[168:171], v[98:101]
	v_mfma_f32_16x16x32_f16 v[86:89], v[192:195], v[176:179], v[86:89]
	v_mfma_f32_16x16x32_f16 v[82:85], v[200:203], v[176:179], v[82:85]
	v_mfma_f32_16x16x32_f16 v[70:73], v[192:195], v[184:187], v[70:73]
	v_mfma_f32_16x16x32_f16 v[66:69], v[200:203], v[184:187], v[66:69]
	s_setprio 0
	s_mov_b32 m0, s9
	v_lshl_add_u64 v[208:209], s[20:21], 0, v[32:33]
	s_barrier
	ds_read_b128 v[156:159], v139 offset:16384
	ds_read_b128 v[164:167], v139 offset:18432
	ds_read_b128 v[172:175], v139 offset:20480
	ds_read_b128 v[180:183], v139 offset:22528
	ds_read_b128 v[160:163], v139 offset:17408
	ds_read_b128 v[168:171], v139 offset:19456
	ds_read_b128 v[176:179], v139 offset:21504
	ds_read_b128 v[184:187], v139 offset:23552
	global_load_lds_dwordx4 v[208:209], off
	v_lshl_add_u64 v[210:211], s[20:21], 0, v[130:131]
	s_mov_b32 m0, s27
	s_nop 0
	global_load_lds_dwordx4 v[210:211], off
	s_barrier
	s_waitcnt lgkmcnt(7)
	s_setprio 1
	v_mfma_f32_16x16x32_f16 v[62:65], v[140:143], v[156:159], v[62:65]
	v_mfma_f32_16x16x32_f16 v[58:61], v[148:151], v[156:159], v[58:61]
	s_waitcnt lgkmcnt(6)
	v_mfma_f32_16x16x32_f16 v[46:49], v[140:143], v[164:167], v[46:49]
	v_mfma_f32_16x16x32_f16 v[42:45], v[148:151], v[164:167], v[42:45]
	s_waitcnt lgkmcnt(5)
	v_mfma_f32_16x16x32_f16 v[28:31], v[140:143], v[172:175], v[28:31]
	v_mfma_f32_16x16x32_f16 v[24:27], v[148:151], v[172:175], v[24:27]
	s_waitcnt lgkmcnt(4)
	v_mfma_f32_16x16x32_f16 v[12:15], v[140:143], v[180:183], v[12:15]
	v_mfma_f32_16x16x32_f16 v[8:11], v[148:151], v[180:183], v[8:11]
	s_waitcnt lgkmcnt(3)
	v_mfma_f32_16x16x32_f16 v[62:65], v[144:147], v[160:163], v[62:65]
	v_mfma_f32_16x16x32_f16 v[58:61], v[152:155], v[160:163], v[58:61]
	s_waitcnt lgkmcnt(2)
	v_mfma_f32_16x16x32_f16 v[46:49], v[144:147], v[168:171], v[46:49]
	v_mfma_f32_16x16x32_f16 v[42:45], v[152:155], v[168:171], v[42:45]
	s_waitcnt lgkmcnt(1)
	v_mfma_f32_16x16x32_f16 v[28:31], v[144:147], v[176:179], v[28:31]
	v_mfma_f32_16x16x32_f16 v[24:27], v[152:155], v[176:179], v[24:27]
	s_waitcnt lgkmcnt(0)
	v_mfma_f32_16x16x32_f16 v[12:15], v[144:147], v[184:187], v[12:15]
	v_mfma_f32_16x16x32_f16 v[8:11], v[152:155], v[184:187], v[8:11]
	s_setprio 0
	s_barrier
	s_add_u32 s14, s18, 0x40000
	s_addc_u32 s15, s19, 0
	s_add_i32 s39, s40, s26
	v_lshl_add_u64 v[140:141], s[14:15], 0, v[32:33]
	s_mov_b32 m0, s39
	s_nop 0
	global_load_lds_dwordx4 v[140:141], off
	v_lshl_add_u64 v[140:141], s[14:15], 0, v[130:131]
	s_add_i32 m0, s39, 0x2000
	s_nop 0
	global_load_lds_dwordx4 v[140:141], off
	s_waitcnt vmcnt(10)
	s_barrier
	s_setprio 1
	v_mfma_f32_16x16x32_f16 v[54:57], v[188:191], v[156:159], v[54:57]
	v_mfma_f32_16x16x32_f16 v[50:53], v[196:199], v[156:159], v[50:53]
	v_mfma_f32_16x16x32_f16 v[38:41], v[188:191], v[164:167], v[38:41]
	v_mfma_f32_16x16x32_f16 v[34:37], v[196:199], v[164:167], v[34:37]
	v_mfma_f32_16x16x32_f16 v[20:23], v[188:191], v[172:175], v[20:23]
	v_mfma_f32_16x16x32_f16 v[16:19], v[196:199], v[172:175], v[16:19]
	v_mfma_f32_16x16x32_f16 v[4:7], v[188:191], v[180:183], v[4:7]
	v_mfma_f32_16x16x32_f16 v[0:3], v[196:199], v[180:183], v[0:3]
	v_mfma_f32_16x16x32_f16 v[54:57], v[192:195], v[160:163], v[54:57]
	v_mfma_f32_16x16x32_f16 v[50:53], v[200:203], v[160:163], v[50:53]
	v_mfma_f32_16x16x32_f16 v[38:41], v[192:195], v[168:171], v[38:41]
	v_mfma_f32_16x16x32_f16 v[34:37], v[200:203], v[168:171], v[34:37]
	v_mfma_f32_16x16x32_f16 v[20:23], v[192:195], v[176:179], v[20:23]
	v_mfma_f32_16x16x32_f16 v[16:19], v[200:203], v[176:179], v[16:19]
	v_mfma_f32_16x16x32_f16 v[4:7], v[192:195], v[184:187], v[4:7]
	v_mfma_f32_16x16x32_f16 v[0:3], v[200:203], v[184:187], v[0:3]
	s_setprio 0
	s_add_i32 s39, 0, 0x18000
	v_add_u32_e32 v152, s39, v137
	s_barrier
	ds_read_b128 v[140:143], v152
	ds_read_b128 v[148:151], v152 offset:2048
	ds_read_b128 v[144:147], v152 offset:1024
	ds_read_b128 v[152:155], v152 offset:3072
	s_add_u32 s14, s20, 0x40000
	s_addc_u32 s15, s21, 0
	s_mov_b32 m0, s28
	v_lshl_add_u64 v[188:189], s[14:15], 0, v[32:33]
	ds_read_b128 v[156:159], v139 offset:32768
	ds_read_b128 v[164:167], v139 offset:34816
	ds_read_b128 v[172:175], v139 offset:36864
	ds_read_b128 v[180:183], v139 offset:38912
	ds_read_b128 v[160:163], v139 offset:33792
	ds_read_b128 v[168:171], v139 offset:35840
	ds_read_b128 v[176:179], v139 offset:37888
	ds_read_b128 v[184:187], v139 offset:39936
	global_load_lds_dwordx4 v[188:189], off
	v_lshl_add_u64 v[188:189], s[14:15], 0, v[130:131]
	s_mov_b32 m0, s29
	s_nop 0
	global_load_lds_dwordx4 v[188:189], off
	s_waitcnt lgkmcnt(8)
	s_waitcnt vmcnt(10)
	s_barrier
	s_waitcnt lgkmcnt(7)
	s_setprio 1
	v_mfma_f32_16x16x32_f16 v[126:129], v[140:143], v[156:159], v[126:129]
	v_mfma_f32_16x16x32_f16 v[122:125], v[148:151], v[156:159], v[122:125]
	s_waitcnt lgkmcnt(6)
	v_mfma_f32_16x16x32_f16 v[110:113], v[140:143], v[164:167], v[110:113]
	v_mfma_f32_16x16x32_f16 v[106:109], v[148:151], v[164:167], v[106:109]
	s_waitcnt lgkmcnt(5)
	v_mfma_f32_16x16x32_f16 v[94:97], v[140:143], v[172:175], v[94:97]
	v_mfma_f32_16x16x32_f16 v[90:93], v[148:151], v[172:175], v[90:93]
	s_waitcnt lgkmcnt(4)
	v_mfma_f32_16x16x32_f16 v[78:81], v[140:143], v[180:183], v[78:81]
	v_mfma_f32_16x16x32_f16 v[74:77], v[148:151], v[180:183], v[74:77]
	s_waitcnt lgkmcnt(3)
	v_mfma_f32_16x16x32_f16 v[126:129], v[144:147], v[160:163], v[126:129]
	v_mfma_f32_16x16x32_f16 v[122:125], v[152:155], v[160:163], v[122:125]
	s_waitcnt lgkmcnt(2)
	v_mfma_f32_16x16x32_f16 v[110:113], v[144:147], v[168:171], v[110:113]
	v_mfma_f32_16x16x32_f16 v[106:109], v[152:155], v[168:171], v[106:109]
	s_waitcnt lgkmcnt(1)
	v_mfma_f32_16x16x32_f16 v[94:97], v[144:147], v[176:179], v[94:97]
	v_mfma_f32_16x16x32_f16 v[90:93], v[152:155], v[176:179], v[90:93]
	s_waitcnt lgkmcnt(0)
	v_mfma_f32_16x16x32_f16 v[78:81], v[144:147], v[184:187], v[78:81]
	v_mfma_f32_16x16x32_f16 v[74:77], v[152:155], v[184:187], v[74:77]
	s_setprio 0
	s_barrier
	s_add_i32 s20, 0, 0x1c000
	s_add_i32 s14, s39, s26
	v_add_u32_e32 v200, s20, v137
	v_lshl_add_u64 v[204:205], v[204:205], 0, s[84:85]
	s_mov_b32 m0, s14
	ds_read_b128 v[188:191], v200
	ds_read_b128 v[196:199], v200 offset:2048
	ds_read_b128 v[192:195], v200 offset:1024
	ds_read_b128 v[200:203], v200 offset:3072
	global_load_lds_dwordx4 v[204:205], off
	v_lshl_add_u64 v[204:205], v[206:207], 0, s[84:85]
	s_add_i32 m0, s14, 0x2000
	s_nop 0
	global_load_lds_dwordx4 v[204:205], off
	s_waitcnt vmcnt(10)
	s_barrier
	s_waitcnt lgkmcnt(2)
	s_setprio 1
	v_mfma_f32_16x16x32_f16 v[118:121], v[188:191], v[156:159], v[118:121]
	v_mfma_f32_16x16x32_f16 v[114:117], v[196:199], v[156:159], v[114:117]
	v_mfma_f32_16x16x32_f16 v[102:105], v[188:191], v[164:167], v[102:105]
	v_mfma_f32_16x16x32_f16 v[98:101], v[196:199], v[164:167], v[98:101]
	v_mfma_f32_16x16x32_f16 v[86:89], v[188:191], v[172:175], v[86:89]
	v_mfma_f32_16x16x32_f16 v[82:85], v[196:199], v[172:175], v[82:85]
	v_mfma_f32_16x16x32_f16 v[70:73], v[188:191], v[180:183], v[70:73]
	v_mfma_f32_16x16x32_f16 v[66:69], v[196:199], v[180:183], v[66:69]
	s_waitcnt lgkmcnt(0)
	v_mfma_f32_16x16x32_f16 v[118:121], v[192:195], v[160:163], v[118:121]
	v_mfma_f32_16x16x32_f16 v[114:117], v[200:203], v[160:163], v[114:117]
	v_mfma_f32_16x16x32_f16 v[102:105], v[192:195], v[168:171], v[102:105]
	v_mfma_f32_16x16x32_f16 v[98:101], v[200:203], v[168:171], v[98:101]
	v_mfma_f32_16x16x32_f16 v[86:89], v[192:195], v[176:179], v[86:89]
	v_mfma_f32_16x16x32_f16 v[82:85], v[200:203], v[176:179], v[82:85]
	v_mfma_f32_16x16x32_f16 v[70:73], v[192:195], v[184:187], v[70:73]
	v_mfma_f32_16x16x32_f16 v[66:69], v[200:203], v[184:187], v[66:69]
	s_setprio 0
	s_mov_b32 m0, s30
	v_lshl_add_u64 v[204:205], v[208:209], 0, s[84:85]
	s_barrier
	ds_read_b128 v[156:159], v139 offset:49152
	ds_read_b128 v[164:167], v139 offset:51200
	ds_read_b128 v[172:175], v139 offset:53248
	ds_read_b128 v[180:183], v139 offset:55296
	ds_read_b128 v[160:163], v139 offset:50176
	ds_read_b128 v[168:171], v139 offset:52224
	ds_read_b128 v[176:179], v139 offset:54272
	ds_read_b128 v[184:187], v139 offset:56320
	global_load_lds_dwordx4 v[204:205], off
	v_lshl_add_u64 v[204:205], v[210:211], 0, s[84:85]
	s_mov_b32 m0, s31
	s_nop 0
	global_load_lds_dwordx4 v[204:205], off
	s_barrier
	s_waitcnt lgkmcnt(7)
	s_setprio 1
	v_mfma_f32_16x16x32_f16 v[62:65], v[140:143], v[156:159], v[62:65]
	v_mfma_f32_16x16x32_f16 v[58:61], v[148:151], v[156:159], v[58:61]
	s_waitcnt lgkmcnt(6)
	v_mfma_f32_16x16x32_f16 v[46:49], v[140:143], v[164:167], v[46:49]
	v_mfma_f32_16x16x32_f16 v[42:45], v[148:151], v[164:167], v[42:45]
	s_waitcnt lgkmcnt(5)
	v_mfma_f32_16x16x32_f16 v[28:31], v[140:143], v[172:175], v[28:31]
	v_mfma_f32_16x16x32_f16 v[24:27], v[148:151], v[172:175], v[24:27]
	s_waitcnt lgkmcnt(4)
	v_mfma_f32_16x16x32_f16 v[12:15], v[140:143], v[180:183], v[12:15]
	v_mfma_f32_16x16x32_f16 v[8:11], v[148:151], v[180:183], v[8:11]
	s_waitcnt lgkmcnt(3)
	v_mfma_f32_16x16x32_f16 v[62:65], v[144:147], v[160:163], v[62:65]
	v_mfma_f32_16x16x32_f16 v[58:61], v[152:155], v[160:163], v[58:61]
	s_waitcnt lgkmcnt(2)
	v_mfma_f32_16x16x32_f16 v[46:49], v[144:147], v[168:171], v[46:49]
	v_mfma_f32_16x16x32_f16 v[42:45], v[152:155], v[168:171], v[42:45]
	s_waitcnt lgkmcnt(1)
	v_mfma_f32_16x16x32_f16 v[28:31], v[144:147], v[176:179], v[28:31]
	v_mfma_f32_16x16x32_f16 v[24:27], v[152:155], v[176:179], v[24:27]
	s_waitcnt lgkmcnt(0)
	v_mfma_f32_16x16x32_f16 v[12:15], v[144:147], v[184:187], v[12:15]
	v_mfma_f32_16x16x32_f16 v[8:11], v[152:155], v[184:187], v[8:11]
	s_setprio 0
	s_barrier
	s_add_u32 s14, s18, 0x40080
	s_addc_u32 s15, s19, 0
	s_add_i32 s18, s20, s26
	v_lshl_add_u64 v[140:141], s[14:15], 0, v[32:33]
	s_mov_b32 m0, s18
	s_nop 0
	global_load_lds_dwordx4 v[140:141], off
	v_lshl_add_u64 v[140:141], s[14:15], 0, v[130:131]
	s_add_i32 m0, s18, 0x2000
	s_nop 0
	global_load_lds_dwordx4 v[140:141], off
	s_waitcnt vmcnt(10)
	s_barrier
	s_setprio 1
	v_mfma_f32_16x16x32_f16 v[54:57], v[188:191], v[156:159], v[54:57]
	v_mfma_f32_16x16x32_f16 v[50:53], v[196:199], v[156:159], v[50:53]
	v_mfma_f32_16x16x32_f16 v[38:41], v[188:191], v[164:167], v[38:41]
	v_mfma_f32_16x16x32_f16 v[34:37], v[196:199], v[164:167], v[34:37]
	v_mfma_f32_16x16x32_f16 v[20:23], v[188:191], v[172:175], v[20:23]
	v_mfma_f32_16x16x32_f16 v[16:19], v[196:199], v[172:175], v[16:19]
	v_mfma_f32_16x16x32_f16 v[4:7], v[188:191], v[180:183], v[4:7]
	v_mfma_f32_16x16x32_f16 v[0:3], v[196:199], v[180:183], v[0:3]
	v_mfma_f32_16x16x32_f16 v[54:57], v[192:195], v[160:163], v[54:57]
	v_mfma_f32_16x16x32_f16 v[50:53], v[200:203], v[160:163], v[50:53]
	v_mfma_f32_16x16x32_f16 v[38:41], v[192:195], v[168:171], v[38:41]
	v_mfma_f32_16x16x32_f16 v[34:37], v[200:203], v[168:171], v[34:37]
	v_mfma_f32_16x16x32_f16 v[20:23], v[192:195], v[176:179], v[20:23]
	v_mfma_f32_16x16x32_f16 v[16:19], v[200:203], v[176:179], v[16:19]
	v_mfma_f32_16x16x32_f16 v[4:7], v[192:195], v[184:187], v[4:7]
	v_mfma_f32_16x16x32_f16 v[0:3], v[200:203], v[184:187], v[0:3]
	s_setprio 0
	s_add_i32 s38, s38, 2
	s_add_u32 s3, s3, 0x100
	s_addc_u32 s37, s37, 0
	s_cmp_gt_u32 s38, 13
	s_mov_b64 s[14:15], s[16:17]
	s_barrier
	s_cbranch_scc0 .LBB0_1276
	v_mul_f32_e32 v144, 0xbfb8aa3b, v127
	v_mul_f32_e32 v141, 0xbfb8aa3b, v126
	v_exp_f32_e32 v145, v144
	v_mul_f32_e32 v144, 0xbfb8aa3b, v128
	v_exp_f32_e32 v141, v141
	v_exp_f32_e32 v146, v144
	v_mul_f32_e32 v144, 0xbfb8aa3b, v129
	v_exp_f32_e32 v147, v144
	v_mul_f32_e32 v144, 0xbfb8aa3b, v122
	v_exp_f32_e32 v148, v144
	v_mul_f32_e32 v144, 0xbfb8aa3b, v123
	v_exp_f32_e32 v149, v144
	v_mul_f32_e32 v144, 0xbfb8aa3b, v124
	v_exp_f32_e32 v150, v144
	v_mul_f32_e32 v144, 0xbfb8aa3b, v125
	v_add_f32_e32 v141, 1.0, v141
	v_exp_f32_e32 v151, v144
	v_rcp_f32_e32 v144, v141
	v_add_f32_e32 v141, 1.0, v145
	v_rcp_f32_e32 v145, v141
	v_add_f32_e32 v141, 1.0, v146
	v_rcp_f32_e32 v146, v141
	v_add_f32_e32 v141, 1.0, v147
	v_rcp_f32_e32 v147, v141
	v_add_f32_e32 v141, 1.0, v148
	v_rcp_f32_e32 v148, v141
	v_add_f32_e32 v141, 1.0, v149
	v_rcp_f32_e32 v149, v141
	v_add_f32_e32 v141, 1.0, v150
	v_rcp_f32_e32 v150, v141
	v_add_f32_e32 v141, 1.0, v151
	v_pk_mul_f32 v[126:127], v[126:127], v[144:145]
	v_rcp_f32_e32 v151, v141
	v_pk_mul_f32 v[118:119], v[126:127], v[118:119]
	v_pk_mul_f32 v[126:127], v[128:129], v[146:147]
	v_cvt_pk_f16_f32 v118, v118, v119
	v_pk_mul_f32 v[120:121], v[126:127], v[120:121]
	v_lshl_or_b32 v142, s36, 7, v138
	v_cvt_pk_f16_f32 v119, v120, v121
	v_pk_mul_f32 v[120:121], v[122:123], v[148:149]
	v_lshl_add_u32 v140, s8, 8, v136
	v_pk_mul_f32 v[114:115], v[120:121], v[114:115]
	v_ashrrev_i32_e32 v143, 31, v142
	v_cvt_pk_f16_f32 v120, v114, v115
	v_pk_mul_f32 v[114:115], v[124:125], v[150:151]
	s_movk_i32 s3, 0x1600
	v_pk_mul_f32 v[114:115], v[114:115], v[116:117]
	v_lshlrev_b64 v[116:117], 1, v[142:143]
	v_cvt_pk_f16_f32 v121, v114, v115
	v_mov_b64_e32 v[114:115], s[92:93]
	v_mad_i64_i32 v[122:123], s[10:11], v140, s3, v[114:115]
	v_lshl_add_u64 v[122:123], v[122:123], 0, v[116:117]
	global_store_dwordx4 v[122:123], v[118:121], off
	v_mul_f32_e32 v122, 0xbfb8aa3b, v106
	v_mul_f32_e32 v123, 0xbfb8aa3b, v107
	v_mul_f32_e32 v118, 0xbfb8aa3b, v110
	v_mul_f32_e32 v119, 0xbfb8aa3b, v111
	v_exp_f32_e32 v118, v118
	v_exp_f32_e32 v119, v119
	v_mul_f32_e32 v120, 0xbfb8aa3b, v112
	v_mul_f32_e32 v121, 0xbfb8aa3b, v113
	v_exp_f32_e32 v120, v120
	v_exp_f32_e32 v121, v121
	v_exp_f32_e32 v122, v122
	v_exp_f32_e32 v123, v123
	v_mul_f32_e32 v124, 0xbfb8aa3b, v108
	v_mul_f32_e32 v125, 0xbfb8aa3b, v109
	v_add_f32_e32 v118, 1.0, v118
	v_add_f32_e32 v119, 1.0, v119
	v_exp_f32_e32 v124, v124
	v_exp_f32_e32 v125, v125
	v_rcp_f32_e32 v118, v118
	v_rcp_f32_e32 v119, v119
	v_add_f32_e32 v120, 1.0, v120
	v_add_f32_e32 v121, 1.0, v121
	v_rcp_f32_e32 v120, v120
	v_rcp_f32_e32 v121, v121
	v_add_f32_e32 v122, 1.0, v122
	v_add_f32_e32 v123, 1.0, v123
	v_rcp_f32_e32 v122, v122
	v_rcp_f32_e32 v123, v123
	v_add_f32_e32 v124, 1.0, v124
	v_add_f32_e32 v125, 1.0, v125
	v_pk_mul_f32 v[110:111], v[110:111], v[118:119]
	v_rcp_f32_e32 v124, v124
	v_rcp_f32_e32 v125, v125
	v_pk_mul_f32 v[102:103], v[110:111], v[102:103]
	v_pk_mul_f32 v[110:111], v[112:113], v[120:121]
	v_cvt_pk_f16_f32 v102, v102, v103
	v_pk_mul_f32 v[104:105], v[110:111], v[104:105]
	s_and_b64 vcc, exec, s[0:1]
	v_cvt_pk_f16_f32 v103, v104, v105
	v_pk_mul_f32 v[104:105], v[106:107], v[122:123]
	s_mov_b32 s36, s35
	v_pk_mul_f32 v[98:99], v[104:105], v[98:99]
	s_mov_b32 s8, s2
	v_cvt_pk_f16_f32 v104, v98, v99
	v_pk_mul_f32 v[98:99], v[108:109], v[124:125]
	s_mov_b64 s[16:17], s[6:7]
	v_pk_mul_f32 v[98:99], v[98:99], v[100:101]
	v_mul_f32_e32 v100, 0xbfb8aa3b, v96
	v_cvt_pk_f16_f32 v105, v98, v99
	v_or_b32_e32 v98, 16, v140
	v_mad_i64_i32 v[98:99], s[10:11], v98, s3, v[114:115]
	v_lshl_add_u64 v[98:99], v[98:99], 0, v[116:117]
	global_store_dwordx4 v[98:99], v[102:105], off
	v_mul_f32_e32 v98, 0xbfb8aa3b, v94
	v_mul_f32_e32 v99, 0xbfb8aa3b, v95
	v_exp_f32_e32 v98, v98
	v_exp_f32_e32 v99, v99
	v_mul_f32_e32 v101, 0xbfb8aa3b, v97
	v_exp_f32_e32 v100, v100
	v_exp_f32_e32 v101, v101
	v_mul_f32_e32 v102, 0xbfb8aa3b, v90
	v_mul_f32_e32 v103, 0xbfb8aa3b, v91
	v_exp_f32_e32 v102, v102
	v_exp_f32_e32 v103, v103
	v_mul_f32_e32 v104, 0xbfb8aa3b, v92
	v_mul_f32_e32 v105, 0xbfb8aa3b, v93
	v_add_f32_e32 v98, 1.0, v98
	v_add_f32_e32 v99, 1.0, v99
	v_exp_f32_e32 v104, v104
	v_exp_f32_e32 v105, v105
	v_rcp_f32_e32 v98, v98
	v_rcp_f32_e32 v99, v99
	v_add_f32_e32 v100, 1.0, v100
	v_add_f32_e32 v101, 1.0, v101
	v_rcp_f32_e32 v100, v100
	v_rcp_f32_e32 v101, v101
	v_add_f32_e32 v102, 1.0, v102
	v_add_f32_e32 v103, 1.0, v103
	v_rcp_f32_e32 v102, v102
	v_rcp_f32_e32 v103, v103
	v_add_f32_e32 v104, 1.0, v104
	v_add_f32_e32 v105, 1.0, v105
	v_pk_mul_f32 v[94:95], v[94:95], v[98:99]
	v_rcp_f32_e32 v104, v104
	v_rcp_f32_e32 v105, v105
	v_pk_mul_f32 v[86:87], v[94:95], v[86:87]
	v_pk_mul_f32 v[94:95], v[96:97], v[100:101]
	v_cvt_pk_f16_f32 v86, v86, v87
	v_pk_mul_f32 v[88:89], v[94:95], v[88:89]
	s_mov_b64 s[14:15], s[4:5]
	v_cvt_pk_f16_f32 v87, v88, v89
	v_pk_mul_f32 v[88:89], v[90:91], v[102:103]
	s_nop 0
	v_pk_mul_f32 v[82:83], v[88:89], v[82:83]
	s_nop 0
	v_cvt_pk_f16_f32 v88, v82, v83
	v_pk_mul_f32 v[82:83], v[92:93], v[104:105]
	s_nop 0
	v_pk_mul_f32 v[82:83], v[82:83], v[84:85]
	v_mul_f32_e32 v84, 0xbfb8aa3b, v80
	v_cvt_pk_f16_f32 v89, v82, v83
	v_or_b32_e32 v82, 32, v140
	v_mad_i64_i32 v[82:83], s[10:11], v82, s3, v[114:115]
	v_lshl_add_u64 v[82:83], v[82:83], 0, v[116:117]
	global_store_dwordx4 v[82:83], v[86:89], off
	v_mul_f32_e32 v82, 0xbfb8aa3b, v78
	v_mul_f32_e32 v83, 0xbfb8aa3b, v79
	v_exp_f32_e32 v82, v82
	v_exp_f32_e32 v83, v83
	v_mul_f32_e32 v85, 0xbfb8aa3b, v81
	v_exp_f32_e32 v84, v84
	v_exp_f32_e32 v85, v85
	v_mul_f32_e32 v86, 0xbfb8aa3b, v74
	v_mul_f32_e32 v87, 0xbfb8aa3b, v75
	v_exp_f32_e32 v86, v86
	v_exp_f32_e32 v87, v87
	v_mul_f32_e32 v88, 0xbfb8aa3b, v76
	v_mul_f32_e32 v89, 0xbfb8aa3b, v77
	v_add_f32_e32 v82, 1.0, v82
	v_add_f32_e32 v83, 1.0, v83
	v_exp_f32_e32 v88, v88
	v_exp_f32_e32 v89, v89
	v_rcp_f32_e32 v82, v82
	v_rcp_f32_e32 v83, v83
	v_add_f32_e32 v84, 1.0, v84
	v_add_f32_e32 v85, 1.0, v85
	v_rcp_f32_e32 v84, v84
	v_rcp_f32_e32 v85, v85
	v_add_f32_e32 v86, 1.0, v86
	v_add_f32_e32 v87, 1.0, v87
	v_rcp_f32_e32 v86, v86
	v_rcp_f32_e32 v87, v87
	v_add_f32_e32 v88, 1.0, v88
	v_add_f32_e32 v89, 1.0, v89
	v_pk_mul_f32 v[78:79], v[78:79], v[82:83]
	v_rcp_f32_e32 v88, v88
	v_rcp_f32_e32 v89, v89
	v_pk_mul_f32 v[70:71], v[78:79], v[70:71]
	v_pk_mul_f32 v[78:79], v[80:81], v[84:85]
	v_cvt_pk_f16_f32 v70, v70, v71
	v_pk_mul_f32 v[72:73], v[78:79], v[72:73]
	s_nop 0
	v_cvt_pk_f16_f32 v71, v72, v73
	v_pk_mul_f32 v[72:73], v[74:75], v[86:87]
	v_add_u32_e32 v74, 0x80, v140
	v_pk_mul_f32 v[66:67], v[72:73], v[66:67]
	s_nop 0
	v_cvt_pk_f16_f32 v72, v66, v67
	v_pk_mul_f32 v[66:67], v[76:77], v[88:89]
	s_nop 0
	v_pk_mul_f32 v[66:67], v[66:67], v[68:69]
	v_mul_f32_e32 v68, 0xbfb8aa3b, v64
	v_cvt_pk_f16_f32 v73, v66, v67
	v_or_b32_e32 v66, 48, v140
	v_mad_i64_i32 v[66:67], s[10:11], v66, s3, v[114:115]
	v_lshl_add_u64 v[66:67], v[66:67], 0, v[116:117]
	global_store_dwordx4 v[66:67], v[70:73], off
	v_mul_f32_e32 v66, 0xbfb8aa3b, v62
	v_mul_f32_e32 v67, 0xbfb8aa3b, v63
	v_exp_f32_e32 v66, v66
	v_exp_f32_e32 v67, v67
	v_mul_f32_e32 v69, 0xbfb8aa3b, v65
	v_exp_f32_e32 v68, v68
	v_exp_f32_e32 v69, v69
	v_mul_f32_e32 v70, 0xbfb8aa3b, v58
	v_mul_f32_e32 v71, 0xbfb8aa3b, v59
	v_exp_f32_e32 v70, v70
	v_exp_f32_e32 v71, v71
	v_mul_f32_e32 v72, 0xbfb8aa3b, v60
	v_mul_f32_e32 v73, 0xbfb8aa3b, v61
	v_add_f32_e32 v66, 1.0, v66
	v_add_f32_e32 v67, 1.0, v67
	v_exp_f32_e32 v72, v72
	v_exp_f32_e32 v73, v73
	v_rcp_f32_e32 v66, v66
	v_rcp_f32_e32 v67, v67
	v_add_f32_e32 v68, 1.0, v68
	v_add_f32_e32 v69, 1.0, v69
	v_rcp_f32_e32 v68, v68
	v_rcp_f32_e32 v69, v69
	v_add_f32_e32 v70, 1.0, v70
	v_add_f32_e32 v71, 1.0, v71
	v_rcp_f32_e32 v70, v70
	v_rcp_f32_e32 v71, v71
	v_add_f32_e32 v72, 1.0, v72
	v_add_f32_e32 v73, 1.0, v73
	v_pk_mul_f32 v[62:63], v[62:63], v[66:67]
	v_rcp_f32_e32 v72, v72
	v_rcp_f32_e32 v73, v73
	v_pk_mul_f32 v[54:55], v[62:63], v[54:55]
	v_pk_mul_f32 v[62:63], v[64:65], v[68:69]
	v_cvt_pk_f16_f32 v54, v54, v55
	v_pk_mul_f32 v[56:57], v[62:63], v[56:57]
	s_nop 0
	v_cvt_pk_f16_f32 v55, v56, v57
	v_pk_mul_f32 v[56:57], v[58:59], v[70:71]
	s_nop 0
	v_pk_mul_f32 v[50:51], v[56:57], v[50:51]
	s_nop 0
	v_cvt_pk_f16_f32 v56, v50, v51
	v_pk_mul_f32 v[50:51], v[60:61], v[72:73]
	s_nop 0
	v_pk_mul_f32 v[50:51], v[50:51], v[52:53]
	v_mul_f32_e32 v52, 0xbfb8aa3b, v48
	v_cvt_pk_f16_f32 v57, v50, v51
	v_mad_i64_i32 v[50:51], s[10:11], v74, s3, v[114:115]
	v_lshl_add_u64 v[50:51], v[50:51], 0, v[116:117]
	global_store_dwordx4 v[50:51], v[54:57], off
	v_mul_f32_e32 v50, 0xbfb8aa3b, v46
	v_mul_f32_e32 v51, 0xbfb8aa3b, v47
	v_exp_f32_e32 v50, v50
	v_exp_f32_e32 v51, v51
	v_mul_f32_e32 v53, 0xbfb8aa3b, v49
	v_exp_f32_e32 v52, v52
	v_exp_f32_e32 v53, v53
	v_mul_f32_e32 v54, 0xbfb8aa3b, v42
	v_mul_f32_e32 v55, 0xbfb8aa3b, v43
	v_exp_f32_e32 v54, v54
	v_exp_f32_e32 v55, v55
	v_mul_f32_e32 v56, 0xbfb8aa3b, v44
	v_mul_f32_e32 v57, 0xbfb8aa3b, v45
	v_add_f32_e32 v50, 1.0, v50
	v_add_f32_e32 v51, 1.0, v51
	v_exp_f32_e32 v56, v56
	v_exp_f32_e32 v57, v57
	v_rcp_f32_e32 v50, v50
	v_rcp_f32_e32 v51, v51
	v_add_f32_e32 v52, 1.0, v52
	v_add_f32_e32 v53, 1.0, v53
	v_rcp_f32_e32 v52, v52
	v_rcp_f32_e32 v53, v53
	v_add_f32_e32 v54, 1.0, v54
	v_add_f32_e32 v55, 1.0, v55
	v_rcp_f32_e32 v54, v54
	v_rcp_f32_e32 v55, v55
	v_add_f32_e32 v56, 1.0, v56
	v_add_f32_e32 v57, 1.0, v57
	v_pk_mul_f32 v[46:47], v[46:47], v[50:51]
	v_rcp_f32_e32 v56, v56
	v_rcp_f32_e32 v57, v57
	v_pk_mul_f32 v[38:39], v[46:47], v[38:39]
	v_pk_mul_f32 v[46:47], v[48:49], v[52:53]
	v_cvt_pk_f16_f32 v38, v38, v39
	v_pk_mul_f32 v[40:41], v[46:47], v[40:41]
	s_nop 0
	v_cvt_pk_f16_f32 v39, v40, v41
	v_pk_mul_f32 v[40:41], v[42:43], v[54:55]
	s_nop 0
	v_pk_mul_f32 v[34:35], v[40:41], v[34:35]
	s_nop 0
	v_cvt_pk_f16_f32 v40, v34, v35
	v_pk_mul_f32 v[34:35], v[44:45], v[56:57]
	s_nop 0
	v_pk_mul_f32 v[34:35], v[34:35], v[36:37]
	v_mul_f32_e32 v36, 0xbfb8aa3b, v30
	v_cvt_pk_f16_f32 v41, v34, v35
	v_add_u32_e32 v34, 0x90, v140
	v_mad_i64_i32 v[34:35], s[10:11], v34, s3, v[114:115]
	v_lshl_add_u64 v[34:35], v[34:35], 0, v[116:117]
	global_store_dwordx4 v[34:35], v[38:41], off
	v_mul_f32_e32 v34, 0xbfb8aa3b, v28
	v_mul_f32_e32 v35, 0xbfb8aa3b, v29
	v_exp_f32_e32 v34, v34
	v_exp_f32_e32 v35, v35
	v_mul_f32_e32 v37, 0xbfb8aa3b, v31
	v_exp_f32_e32 v36, v36
	v_exp_f32_e32 v37, v37
	v_mul_f32_e32 v38, 0xbfb8aa3b, v24
	v_mul_f32_e32 v39, 0xbfb8aa3b, v25
	v_exp_f32_e32 v38, v38
	v_exp_f32_e32 v39, v39
	v_mul_f32_e32 v40, 0xbfb8aa3b, v26
	v_mul_f32_e32 v41, 0xbfb8aa3b, v27
	v_add_f32_e32 v34, 1.0, v34
	v_add_f32_e32 v35, 1.0, v35
	v_exp_f32_e32 v40, v40
	v_exp_f32_e32 v41, v41
	v_rcp_f32_e32 v34, v34
	v_rcp_f32_e32 v35, v35
	v_add_f32_e32 v36, 1.0, v36
	v_add_f32_e32 v37, 1.0, v37
	v_rcp_f32_e32 v36, v36
	v_rcp_f32_e32 v37, v37
	v_add_f32_e32 v38, 1.0, v38
	v_add_f32_e32 v39, 1.0, v39
	v_rcp_f32_e32 v38, v38
	v_rcp_f32_e32 v39, v39
	v_add_f32_e32 v40, 1.0, v40
	v_add_f32_e32 v41, 1.0, v41
	v_pk_mul_f32 v[28:29], v[28:29], v[34:35]
	v_rcp_f32_e32 v40, v40
	v_rcp_f32_e32 v41, v41
	v_pk_mul_f32 v[20:21], v[28:29], v[20:21]
	v_pk_mul_f32 v[28:29], v[30:31], v[36:37]
	v_cvt_pk_f16_f32 v20, v20, v21
	v_pk_mul_f32 v[22:23], v[28:29], v[22:23]
	s_nop 0
	v_cvt_pk_f16_f32 v21, v22, v23
	v_pk_mul_f32 v[22:23], v[24:25], v[38:39]
	s_nop 0
	v_pk_mul_f32 v[16:17], v[22:23], v[16:17]
	s_nop 0
	v_cvt_pk_f16_f32 v22, v16, v17
	v_pk_mul_f32 v[16:17], v[26:27], v[40:41]
	s_nop 0
	v_pk_mul_f32 v[16:17], v[16:17], v[18:19]
	v_mul_f32_e32 v18, 0xbfb8aa3b, v14
	v_cvt_pk_f16_f32 v23, v16, v17
	v_add_u32_e32 v16, 0xa0, v140
	v_mad_i64_i32 v[16:17], s[10:11], v16, s3, v[114:115]
	v_lshl_add_u64 v[16:17], v[16:17], 0, v[116:117]
	global_store_dwordx4 v[16:17], v[20:23], off
	v_mul_f32_e32 v16, 0xbfb8aa3b, v12
	v_mul_f32_e32 v17, 0xbfb8aa3b, v13
	v_exp_f32_e32 v16, v16
	v_exp_f32_e32 v17, v17
	v_mul_f32_e32 v19, 0xbfb8aa3b, v15
	v_exp_f32_e32 v18, v18
	v_exp_f32_e32 v19, v19
	v_mul_f32_e32 v20, 0xbfb8aa3b, v8
	v_mul_f32_e32 v21, 0xbfb8aa3b, v9
	v_exp_f32_e32 v20, v20
	v_exp_f32_e32 v21, v21
	v_mul_f32_e32 v22, 0xbfb8aa3b, v10
	v_mul_f32_e32 v23, 0xbfb8aa3b, v11
	v_add_f32_e32 v16, 1.0, v16
	v_add_f32_e32 v17, 1.0, v17
	v_exp_f32_e32 v22, v22
	v_exp_f32_e32 v23, v23
	v_rcp_f32_e32 v16, v16
	v_rcp_f32_e32 v17, v17
	v_add_f32_e32 v18, 1.0, v18
	v_add_f32_e32 v19, 1.0, v19
	v_rcp_f32_e32 v18, v18
	v_rcp_f32_e32 v19, v19
	v_add_f32_e32 v20, 1.0, v20
	v_add_f32_e32 v21, 1.0, v21
	v_rcp_f32_e32 v20, v20
	v_rcp_f32_e32 v21, v21
	v_add_f32_e32 v22, 1.0, v22
	v_add_f32_e32 v23, 1.0, v23
	v_pk_mul_f32 v[12:13], v[12:13], v[16:17]
	v_rcp_f32_e32 v22, v22
	v_rcp_f32_e32 v23, v23
	v_pk_mul_f32 v[4:5], v[12:13], v[4:5]
	v_pk_mul_f32 v[12:13], v[14:15], v[18:19]
	v_cvt_pk_f16_f32 v4, v4, v5
	v_pk_mul_f32 v[6:7], v[12:13], v[6:7]
	s_nop 0
	v_cvt_pk_f16_f32 v5, v6, v7
	v_pk_mul_f32 v[6:7], v[8:9], v[20:21]
	s_nop 0
	v_pk_mul_f32 v[0:1], v[6:7], v[0:1]
	s_nop 0
	v_cvt_pk_f16_f32 v6, v0, v1
	v_pk_mul_f32 v[0:1], v[10:11], v[22:23]
	s_nop 0
	v_pk_mul_f32 v[0:1], v[0:1], v[2:3]
	s_nop 0
	v_cvt_pk_f16_f32 v7, v0, v1
	v_add_u32_e32 v0, 0xb0, v140
	v_mad_i64_i32 v[0:1], s[10:11], v0, s3, v[114:115]
	v_lshl_add_u64 v[0:1], v[0:1], 0, v[116:117]
	global_store_dwordx4 v[0:1], v[4:7], off
	s_cmp_lg_u32 s34, 1
	s_cbranch_scc1 .Lups_skip
	s_and_b32 s0, s91, 63
	s_cmp_gt_u32 s0, 5
	s_cbranch_scc1 .Lups_skip
	s_cmp_gt_u32 s91, 196
	s_cbranch_scc1 .Lups_skip
	s_waitcnt vmcnt(0)
	s_barrier
	v_readlane_b32 s0, v251, 36
	s_cmp_lg_u32 s0, 0
	s_cbranch_scc1 .Lups_skip
	buffer_wbl2 sc1
	s_waitcnt vmcnt(0)
	v_readlane_b32 s2, v255, 45
	v_readlane_b32 s3, v254, 25
	s_lshl_b32 s2, s2, 1
	s_cmp_eq_u32 s3, 0
	s_cselect_b32 s3, 1, 0
	s_add_i32 s2, s2, s3
	s_lshl_b32 s2, s2, 2
	s_add_i32 s2, s2, 14016
	v_readlane_b32 s0, v251, 32
	v_readlane_b32 s1, v251, 33
	s_add_u32 s0, s0, s2
	s_addc_u32 s1, s1, 0
	s_mov_b64 s[2:3], exec
	s_mov_b64 exec, 1
	global_atomic_add v33, v248, s[0:1]
	s_mov_b64 exec, s[2:3]

.LBB0_1365:
	s_add_i32 s46, s14, 2
	s_add_u32 s12, s10, 0x100
	s_addc_u32 s13, s11, 0
	s_add_i32 s47, 0, 0x10000
	v_add_u32_e32 v134, s47, v230
	ds_read_b128 v[106:109], v134
	ds_read_b128 v[114:117], v134 offset:2048
	ds_read_b128 v[110:113], v134 offset:1024
	ds_read_b128 v[134:137], v134 offset:3072
	s_cmp_eq_u32 s43, s14
	s_cselect_b32 s14, s8, s44
	s_cselect_b32 s17, s7, s13
	s_cselect_b32 s16, s6, s12
	s_cselect_b32 s15, s9, s45
	v_lshl_add_u64 v[178:179], s[10:11], 0, v[184:185]
	s_add_i32 m0, s24, 0xc000
	ds_read_b128 v[138:141], v232
	ds_read_b128 v[154:157], v232 offset:2048
	ds_read_b128 v[162:165], v232 offset:4096
	ds_read_b128 v[170:173], v232 offset:6144
	ds_read_b128 v[150:153], v232 offset:1024
	ds_read_b128 v[158:161], v232 offset:3072
	ds_read_b128 v[166:169], v232 offset:5120
	ds_read_b128 v[174:177], v232 offset:7168
	global_load_lds_dwordx4 v[178:179], off
	v_lshl_add_u64 v[178:179], s[10:11], 0, v[186:187]
	s_add_i32 m0, s24, 0xe000
	s_nop 0
	global_load_lds_dwordx4 v[178:179], off
	s_waitcnt lgkmcnt(8)
	s_waitcnt vmcnt(10)
	s_barrier
	s_waitcnt lgkmcnt(7)
	s_setprio 1
	v_mfma_f32_16x16x32_f16 v[146:149], v[106:109], v[138:141], v[146:149]
	v_mfma_f32_16x16x32_f16 v[142:145], v[114:117], v[138:141], v[142:145]
	s_waitcnt lgkmcnt(6)
	v_mfma_f32_16x16x32_f16 v[130:133], v[106:109], v[154:157], v[130:133]
	v_mfma_f32_16x16x32_f16 v[122:125], v[114:117], v[154:157], v[122:125]
	s_waitcnt lgkmcnt(5)
	v_mfma_f32_16x16x32_f16 v[94:97], v[106:109], v[162:165], v[94:97]
	v_mfma_f32_16x16x32_f16 v[90:93], v[114:117], v[162:165], v[90:93]
	s_waitcnt lgkmcnt(4)
	v_mfma_f32_16x16x32_f16 v[78:81], v[106:109], v[170:173], v[78:81]
	v_mfma_f32_16x16x32_f16 v[74:77], v[114:117], v[170:173], v[74:77]
	s_waitcnt lgkmcnt(3)
	v_mfma_f32_16x16x32_f16 v[146:149], v[110:113], v[150:153], v[146:149]
	v_mfma_f32_16x16x32_f16 v[142:145], v[134:137], v[150:153], v[142:145]
	s_waitcnt lgkmcnt(2)
	v_mfma_f32_16x16x32_f16 v[130:133], v[110:113], v[158:161], v[130:133]
	v_mfma_f32_16x16x32_f16 v[122:125], v[134:137], v[158:161], v[122:125]
	s_waitcnt lgkmcnt(1)
	v_mfma_f32_16x16x32_f16 v[94:97], v[110:113], v[166:169], v[94:97]
	v_mfma_f32_16x16x32_f16 v[90:93], v[134:137], v[166:169], v[90:93]
	s_waitcnt lgkmcnt(0)
	v_mfma_f32_16x16x32_f16 v[78:81], v[110:113], v[174:177], v[78:81]
	v_mfma_f32_16x16x32_f16 v[74:77], v[134:137], v[174:177], v[74:77]
	s_setprio 0
	s_barrier
	s_add_i32 s48, 0, 0x14000
	s_add_i32 s10, s47, s23
	v_add_u32_e32 v196, s48, v230
	v_lshl_add_u64 v[200:201], s[14:15], 0, v[32:33]
	s_mov_b32 m0, s10
	ds_read_b128 v[178:181], v196
	ds_read_b128 v[192:195], v196 offset:2048
	ds_read_b128 v[188:191], v196 offset:1024
	ds_read_b128 v[196:199], v196 offset:3072
	global_load_lds_dwordx4 v[200:201], off
	v_lshl_add_u64 v[202:203], s[14:15], 0, v[182:183]
	s_add_i32 m0, s10, 0x2000
	s_nop 0
	global_load_lds_dwordx4 v[202:203], off
	s_waitcnt vmcnt(10)
	s_barrier
	s_waitcnt lgkmcnt(2)
	s_setprio 1
	v_mfma_f32_16x16x32_f16 v[126:129], v[178:181], v[138:141], v[126:129]
	v_mfma_f32_16x16x32_f16 v[118:121], v[192:195], v[138:141], v[118:121]
	v_mfma_f32_16x16x32_f16 v[102:105], v[178:181], v[154:157], v[102:105]
	v_mfma_f32_16x16x32_f16 v[98:101], v[192:195], v[154:157], v[98:101]
	v_mfma_f32_16x16x32_f16 v[86:89], v[178:181], v[162:165], v[86:89]
	v_mfma_f32_16x16x32_f16 v[82:85], v[192:195], v[162:165], v[82:85]
	v_mfma_f32_16x16x32_f16 v[70:73], v[178:181], v[170:173], v[70:73]
	v_mfma_f32_16x16x32_f16 v[66:69], v[192:195], v[170:173], v[66:69]
	s_waitcnt lgkmcnt(0)
	v_mfma_f32_16x16x32_f16 v[126:129], v[188:191], v[150:153], v[126:129]
	v_mfma_f32_16x16x32_f16 v[118:121], v[196:199], v[150:153], v[118:121]
	v_mfma_f32_16x16x32_f16 v[102:105], v[188:191], v[158:161], v[102:105]
	v_mfma_f32_16x16x32_f16 v[98:101], v[196:199], v[158:161], v[98:101]
	v_mfma_f32_16x16x32_f16 v[86:89], v[188:191], v[166:169], v[86:89]
	v_mfma_f32_16x16x32_f16 v[82:85], v[196:199], v[166:169], v[82:85]
	v_mfma_f32_16x16x32_f16 v[70:73], v[188:191], v[174:177], v[70:73]
	v_mfma_f32_16x16x32_f16 v[66:69], v[196:199], v[174:177], v[66:69]
	s_setprio 0
	s_mov_b32 m0, s24
	v_lshl_add_u64 v[204:205], s[16:17], 0, v[32:33]
	s_barrier
	ds_read_b128 v[138:141], v232 offset:16384
	ds_read_b128 v[154:157], v232 offset:18432
	ds_read_b128 v[162:165], v232 offset:20480
	ds_read_b128 v[170:173], v232 offset:22528
	ds_read_b128 v[150:153], v232 offset:17408
	ds_read_b128 v[158:161], v232 offset:19456
	ds_read_b128 v[166:169], v232 offset:21504
	ds_read_b128 v[174:177], v232 offset:23552
	global_load_lds_dwordx4 v[204:205], off
	v_lshl_add_u64 v[206:207], s[16:17], 0, v[182:183]
	s_mov_b32 m0, s25
	s_nop 0
	global_load_lds_dwordx4 v[206:207], off
	s_barrier
	s_waitcnt lgkmcnt(7)
	s_setprio 1
	v_mfma_f32_16x16x32_f16 v[62:65], v[106:109], v[138:141], v[62:65]
	v_mfma_f32_16x16x32_f16 v[58:61], v[114:117], v[138:141], v[58:61]
	s_waitcnt lgkmcnt(6)
	v_mfma_f32_16x16x32_f16 v[46:49], v[106:109], v[154:157], v[46:49]
	v_mfma_f32_16x16x32_f16 v[42:45], v[114:117], v[154:157], v[42:45]
	s_waitcnt lgkmcnt(5)
	v_mfma_f32_16x16x32_f16 v[28:31], v[106:109], v[162:165], v[28:31]
	v_mfma_f32_16x16x32_f16 v[24:27], v[114:117], v[162:165], v[24:27]
	s_waitcnt lgkmcnt(4)
	v_mfma_f32_16x16x32_f16 v[12:15], v[106:109], v[170:173], v[12:15]
	v_mfma_f32_16x16x32_f16 v[8:11], v[114:117], v[170:173], v[8:11]
	s_waitcnt lgkmcnt(3)
	v_mfma_f32_16x16x32_f16 v[62:65], v[110:113], v[150:153], v[62:65]
	v_mfma_f32_16x16x32_f16 v[58:61], v[134:137], v[150:153], v[58:61]
	s_waitcnt lgkmcnt(2)
	v_mfma_f32_16x16x32_f16 v[46:49], v[110:113], v[158:161], v[46:49]
	v_mfma_f32_16x16x32_f16 v[42:45], v[134:137], v[158:161], v[42:45]
	s_waitcnt lgkmcnt(1)
	v_mfma_f32_16x16x32_f16 v[28:31], v[110:113], v[166:169], v[28:31]
	v_mfma_f32_16x16x32_f16 v[24:27], v[134:137], v[166:169], v[24:27]
	s_waitcnt lgkmcnt(0)
	v_mfma_f32_16x16x32_f16 v[12:15], v[110:113], v[174:177], v[12:15]
	v_mfma_f32_16x16x32_f16 v[8:11], v[134:137], v[174:177], v[8:11]
	s_setprio 0
	s_barrier
	s_add_u32 s10, s14, 0xb0000
	s_addc_u32 s11, s15, 0
	s_add_i32 s47, s48, s23
	v_lshl_add_u64 v[106:107], s[10:11], 0, v[32:33]
	s_mov_b32 m0, s47
	s_nop 0
	global_load_lds_dwordx4 v[106:107], off
	v_lshl_add_u64 v[106:107], s[10:11], 0, v[182:183]
	s_add_i32 m0, s47, 0x2000
	s_nop 0
	global_load_lds_dwordx4 v[106:107], off
	s_waitcnt vmcnt(10)
	s_barrier
	s_setprio 1
	v_mfma_f32_16x16x32_f16 v[54:57], v[178:181], v[138:141], v[54:57]
	v_mfma_f32_16x16x32_f16 v[50:53], v[192:195], v[138:141], v[50:53]
	v_mfma_f32_16x16x32_f16 v[38:41], v[178:181], v[154:157], v[38:41]
	v_mfma_f32_16x16x32_f16 v[34:37], v[192:195], v[154:157], v[34:37]
	v_mfma_f32_16x16x32_f16 v[20:23], v[178:181], v[162:165], v[20:23]
	v_mfma_f32_16x16x32_f16 v[16:19], v[192:195], v[162:165], v[16:19]
	v_mfma_f32_16x16x32_f16 v[4:7], v[178:181], v[170:173], v[4:7]
	v_mfma_f32_16x16x32_f16 v[0:3], v[192:195], v[170:173], v[0:3]
	v_mfma_f32_16x16x32_f16 v[54:57], v[188:191], v[150:153], v[54:57]
	v_mfma_f32_16x16x32_f16 v[50:53], v[196:199], v[150:153], v[50:53]
	v_mfma_f32_16x16x32_f16 v[38:41], v[188:191], v[158:161], v[38:41]
	v_mfma_f32_16x16x32_f16 v[34:37], v[196:199], v[158:161], v[34:37]
	v_mfma_f32_16x16x32_f16 v[20:23], v[188:191], v[166:169], v[20:23]
	v_mfma_f32_16x16x32_f16 v[16:19], v[196:199], v[166:169], v[16:19]
	v_mfma_f32_16x16x32_f16 v[4:7], v[188:191], v[174:177], v[4:7]
	v_mfma_f32_16x16x32_f16 v[0:3], v[196:199], v[174:177], v[0:3]
	s_setprio 0
	s_add_i32 s47, 0, 0x18000
	v_add_u32_e32 v134, s47, v230
	s_barrier
	ds_read_b128 v[106:109], v134
	ds_read_b128 v[114:117], v134 offset:2048
	ds_read_b128 v[110:113], v134 offset:1024
	ds_read_b128 v[134:137], v134 offset:3072
	s_add_u32 s10, s16, 0xb0000
	s_addc_u32 s11, s17, 0
	s_mov_b32 m0, s26
	v_lshl_add_u64 v[178:179], s[10:11], 0, v[32:33]
	ds_read_b128 v[138:141], v232 offset:32768
	ds_read_b128 v[154:157], v232 offset:34816
	ds_read_b128 v[162:165], v232 offset:36864
	ds_read_b128 v[170:173], v232 offset:38912
	ds_read_b128 v[150:153], v232 offset:33792
	ds_read_b128 v[158:161], v232 offset:35840
	ds_read_b128 v[166:169], v232 offset:37888
	ds_read_b128 v[174:177], v232 offset:39936
	global_load_lds_dwordx4 v[178:179], off
	v_lshl_add_u64 v[178:179], s[10:11], 0, v[182:183]
	s_mov_b32 m0, s27
	s_nop 0
	global_load_lds_dwordx4 v[178:179], off
	s_waitcnt lgkmcnt(8)
	s_waitcnt vmcnt(10)
	s_barrier
	s_waitcnt lgkmcnt(7)
	s_setprio 1
	v_mfma_f32_16x16x32_f16 v[146:149], v[106:109], v[138:141], v[146:149]
	v_mfma_f32_16x16x32_f16 v[142:145], v[114:117], v[138:141], v[142:145]
	s_waitcnt lgkmcnt(6)
	v_mfma_f32_16x16x32_f16 v[130:133], v[106:109], v[154:157], v[130:133]
	v_mfma_f32_16x16x32_f16 v[122:125], v[114:117], v[154:157], v[122:125]
	s_waitcnt lgkmcnt(5)
	v_mfma_f32_16x16x32_f16 v[94:97], v[106:109], v[162:165], v[94:97]
	v_mfma_f32_16x16x32_f16 v[90:93], v[114:117], v[162:165], v[90:93]
	s_waitcnt lgkmcnt(4)
	v_mfma_f32_16x16x32_f16 v[78:81], v[106:109], v[170:173], v[78:81]
	v_mfma_f32_16x16x32_f16 v[74:77], v[114:117], v[170:173], v[74:77]
	s_waitcnt lgkmcnt(3)
	v_mfma_f32_16x16x32_f16 v[146:149], v[110:113], v[150:153], v[146:149]
	v_mfma_f32_16x16x32_f16 v[142:145], v[134:137], v[150:153], v[142:145]
	s_waitcnt lgkmcnt(2)
	v_mfma_f32_16x16x32_f16 v[130:133], v[110:113], v[158:161], v[130:133]
	v_mfma_f32_16x16x32_f16 v[122:125], v[134:137], v[158:161], v[122:125]
	s_waitcnt lgkmcnt(1)
	v_mfma_f32_16x16x32_f16 v[94:97], v[110:113], v[166:169], v[94:97]
	v_mfma_f32_16x16x32_f16 v[90:93], v[134:137], v[166:169], v[90:93]
	s_waitcnt lgkmcnt(0)
	v_mfma_f32_16x16x32_f16 v[78:81], v[110:113], v[174:177], v[78:81]
	v_mfma_f32_16x16x32_f16 v[74:77], v[134:137], v[174:177], v[74:77]
	s_setprio 0
	s_barrier
	s_add_i32 s16, 0, 0x1c000
	s_add_i32 s10, s47, s23
	v_add_u32_e32 v196, s16, v230
	v_lshl_add_u64 v[200:201], v[200:201], 0, s[84:85]
	s_mov_b32 m0, s10
	ds_read_b128 v[178:181], v196
	ds_read_b128 v[192:195], v196 offset:2048
	ds_read_b128 v[188:191], v196 offset:1024
	ds_read_b128 v[196:199], v196 offset:3072
	global_load_lds_dwordx4 v[200:201], off
	v_lshl_add_u64 v[200:201], v[202:203], 0, s[84:85]
	s_add_i32 m0, s10, 0x2000
	s_nop 0
	global_load_lds_dwordx4 v[200:201], off
	s_waitcnt vmcnt(10)
	s_barrier
	s_waitcnt lgkmcnt(2)
	s_setprio 1
	v_mfma_f32_16x16x32_f16 v[126:129], v[178:181], v[138:141], v[126:129]
	v_mfma_f32_16x16x32_f16 v[118:121], v[192:195], v[138:141], v[118:121]
	v_mfma_f32_16x16x32_f16 v[102:105], v[178:181], v[154:157], v[102:105]
	v_mfma_f32_16x16x32_f16 v[98:101], v[192:195], v[154:157], v[98:101]
	v_mfma_f32_16x16x32_f16 v[86:89], v[178:181], v[162:165], v[86:89]
	v_mfma_f32_16x16x32_f16 v[82:85], v[192:195], v[162:165], v[82:85]
	v_mfma_f32_16x16x32_f16 v[70:73], v[178:181], v[170:173], v[70:73]
	v_mfma_f32_16x16x32_f16 v[66:69], v[192:195], v[170:173], v[66:69]
	s_waitcnt lgkmcnt(0)
	v_mfma_f32_16x16x32_f16 v[126:129], v[188:191], v[150:153], v[126:129]
	v_mfma_f32_16x16x32_f16 v[118:121], v[196:199], v[150:153], v[118:121]
	v_mfma_f32_16x16x32_f16 v[102:105], v[188:191], v[158:161], v[102:105]
	v_mfma_f32_16x16x32_f16 v[98:101], v[196:199], v[158:161], v[98:101]
	v_mfma_f32_16x16x32_f16 v[86:89], v[188:191], v[166:169], v[86:89]
	v_mfma_f32_16x16x32_f16 v[82:85], v[196:199], v[166:169], v[82:85]
	v_mfma_f32_16x16x32_f16 v[70:73], v[188:191], v[174:177], v[70:73]
	v_mfma_f32_16x16x32_f16 v[66:69], v[196:199], v[174:177], v[66:69]
	s_setprio 0
	s_mov_b32 m0, s29
	v_lshl_add_u64 v[200:201], v[204:205], 0, s[84:85]
	s_barrier
	ds_read_b128 v[138:141], v232 offset:49152
	ds_read_b128 v[154:157], v232 offset:51200
	ds_read_b128 v[162:165], v232 offset:53248
	ds_read_b128 v[170:173], v232 offset:55296
	ds_read_b128 v[150:153], v232 offset:50176
	ds_read_b128 v[158:161], v232 offset:52224
	ds_read_b128 v[166:169], v232 offset:54272
	ds_read_b128 v[174:177], v232 offset:56320
	global_load_lds_dwordx4 v[200:201], off
	v_lshl_add_u64 v[200:201], v[206:207], 0, s[84:85]
	s_mov_b32 m0, s30
	s_nop 0
	global_load_lds_dwordx4 v[200:201], off
	s_barrier
	s_waitcnt lgkmcnt(7)
	s_setprio 1
	v_mfma_f32_16x16x32_f16 v[62:65], v[106:109], v[138:141], v[62:65]
	v_mfma_f32_16x16x32_f16 v[58:61], v[114:117], v[138:141], v[58:61]
	s_waitcnt lgkmcnt(6)
	v_mfma_f32_16x16x32_f16 v[46:49], v[106:109], v[154:157], v[46:49]
	v_mfma_f32_16x16x32_f16 v[42:45], v[114:117], v[154:157], v[42:45]
	s_waitcnt lgkmcnt(5)
	v_mfma_f32_16x16x32_f16 v[28:31], v[106:109], v[162:165], v[28:31]
	v_mfma_f32_16x16x32_f16 v[24:27], v[114:117], v[162:165], v[24:27]
	s_waitcnt lgkmcnt(4)
	v_mfma_f32_16x16x32_f16 v[12:15], v[106:109], v[170:173], v[12:15]
	v_mfma_f32_16x16x32_f16 v[8:11], v[114:117], v[170:173], v[8:11]
	s_waitcnt lgkmcnt(3)
	v_mfma_f32_16x16x32_f16 v[62:65], v[110:113], v[150:153], v[62:65]
	v_mfma_f32_16x16x32_f16 v[58:61], v[134:137], v[150:153], v[58:61]
	s_waitcnt lgkmcnt(2)
	v_mfma_f32_16x16x32_f16 v[46:49], v[110:113], v[158:161], v[46:49]
	v_mfma_f32_16x16x32_f16 v[42:45], v[134:137], v[158:161], v[42:45]
	s_waitcnt lgkmcnt(1)
	v_mfma_f32_16x16x32_f16 v[28:31], v[110:113], v[166:169], v[28:31]
	v_mfma_f32_16x16x32_f16 v[24:27], v[134:137], v[166:169], v[24:27]
	s_waitcnt lgkmcnt(0)
	v_mfma_f32_16x16x32_f16 v[12:15], v[110:113], v[174:177], v[12:15]
	v_mfma_f32_16x16x32_f16 v[8:11], v[134:137], v[174:177], v[8:11]
	s_setprio 0
	s_barrier
	s_add_u32 s10, s14, 0xb0080
	s_addc_u32 s11, s15, 0
	s_add_i32 s14, s16, s23
	v_lshl_add_u64 v[106:107], s[10:11], 0, v[32:33]
	s_mov_b32 m0, s14
	s_nop 0
	global_load_lds_dwordx4 v[106:107], off
	v_lshl_add_u64 v[106:107], s[10:11], 0, v[182:183]
	s_add_i32 m0, s14, 0x2000
	s_nop 0
	global_load_lds_dwordx4 v[106:107], off
	s_waitcnt vmcnt(10)
	s_barrier
	s_setprio 1
	v_mfma_f32_16x16x32_f16 v[54:57], v[178:181], v[138:141], v[54:57]
	v_mfma_f32_16x16x32_f16 v[50:53], v[192:195], v[138:141], v[50:53]
	v_mfma_f32_16x16x32_f16 v[38:41], v[178:181], v[154:157], v[38:41]
	v_mfma_f32_16x16x32_f16 v[34:37], v[192:195], v[154:157], v[34:37]
	v_mfma_f32_16x16x32_f16 v[20:23], v[178:181], v[162:165], v[20:23]
	v_mfma_f32_16x16x32_f16 v[16:19], v[192:195], v[162:165], v[16:19]
	v_mfma_f32_16x16x32_f16 v[4:7], v[178:181], v[170:173], v[4:7]
	v_mfma_f32_16x16x32_f16 v[0:3], v[192:195], v[170:173], v[0:3]
	v_mfma_f32_16x16x32_f16 v[54:57], v[188:191], v[150:153], v[54:57]
	v_mfma_f32_16x16x32_f16 v[50:53], v[196:199], v[150:153], v[50:53]
	v_mfma_f32_16x16x32_f16 v[38:41], v[188:191], v[158:161], v[38:41]
	v_mfma_f32_16x16x32_f16 v[34:37], v[196:199], v[158:161], v[34:37]
	v_mfma_f32_16x16x32_f16 v[20:23], v[188:191], v[166:169], v[20:23]
	v_mfma_f32_16x16x32_f16 v[16:19], v[196:199], v[166:169], v[16:19]
	v_mfma_f32_16x16x32_f16 v[4:7], v[188:191], v[174:177], v[4:7]
	v_mfma_f32_16x16x32_f16 v[0:3], v[196:199], v[174:177], v[0:3]
	s_setprio 0
	s_add_u32 s44, s44, 0x100
	s_addc_u32 s45, s45, 0
	s_cmp_ge_u32 s46, s42
	s_mov_b64 s[10:11], s[12:13]
	s_mov_b32 s14, s46
	s_barrier
	s_cbranch_scc0 .LBB0_1365
	s_cmp_eq_u32 s40, 0
	s_cselect_b32 s6, 0x9000, 0
	v_lshl_or_b32 v106, s41, 8, v231
	s_add_u32 s6, s31, s6
	s_addc_u32 s7, s34, 0
	v_ashrrev_i32_e32 v107, 31, v106
	v_lshl_add_u64 v[116:117], v[106:107], 2, s[6:7]
	global_load_dwordx4 v[108:111], v[116:117], off offset:16
	global_load_dwordx4 v[112:115], v[116:117], off
	s_cmp_eq_u32 s39, 0
	s_waitcnt vmcnt(0)
	v_pk_mul_f32 v[194:195], v[110:111], 0.5 op_sel_hi:[1,0]
	v_pk_mul_f32 v[198:199], v[114:115], 0.5 op_sel_hi:[1,0]
	v_pk_mul_f32 v[202:203], v[112:113], 0.5 op_sel_hi:[1,0]
	v_pk_mul_f32 v[200:201], v[108:109], 0.5 op_sel_hi:[1,0]
	global_load_dwordx4 v[108:111], v[116:117], off offset:528
	global_load_dwordx4 v[112:115], v[116:117], off offset:512
	s_waitcnt vmcnt(0)
	v_pk_mul_f32 v[188:189], v[110:111], 0.5 op_sel_hi:[1,0]
	v_pk_mul_f32 v[196:197], v[112:113], 0.5 op_sel_hi:[1,0]
	v_lshl_add_u32 v112, s40, 8, v229
	v_pk_mul_f32 v[190:191], v[114:115], 0.5 op_sel_hi:[1,0]
	v_pk_mul_f32 v[192:193], v[108:109], 0.5 op_sel_hi:[1,0]
	v_or_b32_e32 v114, 16, v112
	v_or_b32_e32 v110, 32, v112
	v_or_b32_e32 v108, 48, v112
	v_ashrrev_i32_e32 v113, 31, v112
	v_ashrrev_i32_e32 v115, 31, v114
	v_ashrrev_i32_e32 v111, 31, v110
	v_ashrrev_i32_e32 v109, 31, v108
	s_cbranch_scc1 .LBB0_1368
	s_add_i32 s96, s39, -1
	s_lshl_b64 s[6:7], s[96:97], 20
	v_readlane_b32 s8, v252, 11
	v_readlane_b32 s9, v252, 12
	s_add_u32 s6, s8, s6
	s_addc_u32 s7, s9, s7
	v_lshlrev_b64 v[138:139], 2, v[106:107]
	v_lshrrev_b32_e32 v150, 5, v220
	v_mul_u32_u24_e32 v150, 48, v150
	s_nop 0
	v_sub_co_u32_e32 v138, vcc, v138, v150
	s_nop 1
	v_subbrev_co_u32_e32 v139, vcc, 0, v139, vcc
	v_lshl_add_u64 v[138:139], s[6:7], 0, v[138:139]
	s_mov_b64 s[6:7], 0x80000
	v_lshlrev_b64 v[204:205], 12, v[112:113]
	v_lshl_add_u64 v[204:205], v[204:205], 0, v[138:139]
	v_lshl_add_u64 v[212:213], v[204:205], 0, s[6:7]
	v_lshlrev_b64 v[206:207], 12, v[114:115]
	v_lshl_add_u64 v[206:207], v[206:207], 0, v[138:139]
	v_lshl_add_u64 v[214:215], v[206:207], 0, s[6:7]
	v_lshlrev_b64 v[208:209], 12, v[110:111]
	v_lshl_add_u64 v[208:209], v[208:209], 0, v[138:139]
	v_lshl_add_u64 v[216:217], v[208:209], 0, s[6:7]
	v_lshlrev_b64 v[210:211], 12, v[108:109]
	v_lshl_add_u64 v[210:211], v[210:211], 0, v[138:139]
	v_lshl_add_u64 v[218:219], v[210:211], 0, s[6:7]
	s_waitcnt vmcnt(0)
	v_pk_mul_f32 v[152:153], v[146:147], v[202:203]
	v_pk_mul_f32 v[154:155], v[148:149], v[198:199]
	v_pk_mul_f32 v[156:157], v[142:143], v[200:201]
	v_pk_mul_f32 v[158:159], v[144:145], v[194:195]
	s_nop 1
	v_permlane32_swap_b32_e32 v152, v156
	v_permlane32_swap_b32_e32 v153, v157
	v_permlane32_swap_b32_e32 v154, v158
	v_permlane32_swap_b32_e32 v155, v159
	s_nop 0
	global_store_dwordx4 v[204:205], v[152:155], off
	global_store_dwordx4 v[204:205], v[156:159], off offset:64
	v_pk_mul_f32 v[160:161], v[126:127], v[196:197]
	v_pk_mul_f32 v[162:163], v[128:129], v[190:191]
	v_pk_mul_f32 v[164:165], v[118:119], v[192:193]
	v_pk_mul_f32 v[166:167], v[120:121], v[188:189]
	s_nop 1
	v_permlane32_swap_b32_e32 v160, v164
	v_permlane32_swap_b32_e32 v161, v165
	v_permlane32_swap_b32_e32 v162, v166
	v_permlane32_swap_b32_e32 v163, v167
	s_nop 0
	global_store_dwordx4 v[204:205], v[160:163], off offset:512
	global_store_dwordx4 v[204:205], v[164:167], off offset:576
	v_pk_mul_f32 v[168:169], v[130:131], v[202:203]
	v_pk_mul_f32 v[170:171], v[132:133], v[198:199]
	v_pk_mul_f32 v[172:173], v[122:123], v[200:201]
	v_pk_mul_f32 v[174:175], v[124:125], v[194:195]
	s_nop 1
	v_permlane32_swap_b32_e32 v168, v172
	v_permlane32_swap_b32_e32 v169, v173
	v_permlane32_swap_b32_e32 v170, v174
	v_permlane32_swap_b32_e32 v171, v175
	s_nop 0
	global_store_dwordx4 v[206:207], v[168:171], off
	global_store_dwordx4 v[206:207], v[172:175], off offset:64
	v_pk_mul_f32 v[176:177], v[102:103], v[196:197]
	v_pk_mul_f32 v[178:179], v[104:105], v[190:191]
	v_pk_mul_f32 v[180:181], v[98:99], v[192:193]
	v_pk_mul_f32 v[182:183], v[100:101], v[188:189]
	s_nop 1
	v_permlane32_swap_b32_e32 v176, v180
	v_permlane32_swap_b32_e32 v177, v181
	v_permlane32_swap_b32_e32 v178, v182
	v_permlane32_swap_b32_e32 v179, v183
	s_nop 0
	global_store_dwordx4 v[206:207], v[176:179], off offset:512
	global_store_dwordx4 v[206:207], v[180:183], off offset:576
	v_pk_mul_f32 v[152:153], v[94:95], v[202:203]
	v_pk_mul_f32 v[154:155], v[96:97], v[198:199]
	v_pk_mul_f32 v[156:157], v[90:91], v[200:201]
	v_pk_mul_f32 v[158:159], v[92:93], v[194:195]
	s_nop 1
	v_permlane32_swap_b32_e32 v152, v156
	v_permlane32_swap_b32_e32 v153, v157
	v_permlane32_swap_b32_e32 v154, v158
	v_permlane32_swap_b32_e32 v155, v159
	s_nop 0
	global_store_dwordx4 v[208:209], v[152:155], off
	global_store_dwordx4 v[208:209], v[156:159], off offset:64
	v_pk_mul_f32 v[160:161], v[86:87], v[196:197]
	v_pk_mul_f32 v[162:163], v[88:89], v[190:191]
	v_pk_mul_f32 v[164:165], v[82:83], v[192:193]
	v_pk_mul_f32 v[166:167], v[84:85], v[188:189]
	s_nop 1
	v_permlane32_swap_b32_e32 v160, v164
	v_permlane32_swap_b32_e32 v161, v165
	v_permlane32_swap_b32_e32 v162, v166
	v_permlane32_swap_b32_e32 v163, v167
	s_nop 0
	global_store_dwordx4 v[208:209], v[160:163], off offset:512
	global_store_dwordx4 v[208:209], v[164:167], off offset:576
	v_pk_mul_f32 v[168:169], v[78:79], v[202:203]
	v_pk_mul_f32 v[170:171], v[80:81], v[198:199]
	v_pk_mul_f32 v[172:173], v[74:75], v[200:201]
	v_pk_mul_f32 v[174:175], v[76:77], v[194:195]
	s_nop 1
	v_permlane32_swap_b32_e32 v168, v172
	v_permlane32_swap_b32_e32 v169, v173
	v_permlane32_swap_b32_e32 v170, v174
	v_permlane32_swap_b32_e32 v171, v175
	s_nop 0
	global_store_dwordx4 v[210:211], v[168:171], off
	global_store_dwordx4 v[210:211], v[172:175], off offset:64
	v_pk_mul_f32 v[176:177], v[70:71], v[196:197]
	v_pk_mul_f32 v[178:179], v[72:73], v[190:191]
	v_pk_mul_f32 v[180:181], v[66:67], v[192:193]
	v_pk_mul_f32 v[182:183], v[68:69], v[188:189]
	s_nop 1
	v_permlane32_swap_b32_e32 v176, v180
	v_permlane32_swap_b32_e32 v177, v181
	v_permlane32_swap_b32_e32 v178, v182
	v_permlane32_swap_b32_e32 v179, v183
	s_nop 0
	global_store_dwordx4 v[210:211], v[176:179], off offset:512
	global_store_dwordx4 v[210:211], v[180:183], off offset:576
	v_pk_mul_f32 v[152:153], v[62:63], v[202:203]
	v_pk_mul_f32 v[154:155], v[64:65], v[198:199]
	v_pk_mul_f32 v[156:157], v[58:59], v[200:201]
	v_pk_mul_f32 v[158:159], v[60:61], v[194:195]
	s_nop 1
	v_permlane32_swap_b32_e32 v152, v156
	v_permlane32_swap_b32_e32 v153, v157
	v_permlane32_swap_b32_e32 v154, v158
	v_permlane32_swap_b32_e32 v155, v159
	s_nop 0
	global_store_dwordx4 v[212:213], v[152:155], off
	global_store_dwordx4 v[212:213], v[156:159], off offset:64
	v_pk_mul_f32 v[160:161], v[54:55], v[196:197]
	v_pk_mul_f32 v[162:163], v[56:57], v[190:191]
	v_pk_mul_f32 v[164:165], v[50:51], v[192:193]
	v_pk_mul_f32 v[166:167], v[52:53], v[188:189]
	s_nop 1
	v_permlane32_swap_b32_e32 v160, v164
	v_permlane32_swap_b32_e32 v161, v165
	v_permlane32_swap_b32_e32 v162, v166
	v_permlane32_swap_b32_e32 v163, v167
	s_nop 0
	global_store_dwordx4 v[212:213], v[160:163], off offset:512
	global_store_dwordx4 v[212:213], v[164:167], off offset:576
	v_pk_mul_f32 v[168:169], v[46:47], v[202:203]
	v_pk_mul_f32 v[170:171], v[48:49], v[198:199]
	v_pk_mul_f32 v[172:173], v[42:43], v[200:201]
	v_pk_mul_f32 v[174:175], v[44:45], v[194:195]
	s_nop 1
	v_permlane32_swap_b32_e32 v168, v172
	v_permlane32_swap_b32_e32 v169, v173
	v_permlane32_swap_b32_e32 v170, v174
	v_permlane32_swap_b32_e32 v171, v175
	s_nop 0
	global_store_dwordx4 v[214:215], v[168:171], off
	global_store_dwordx4 v[214:215], v[172:175], off offset:64
	v_pk_mul_f32 v[176:177], v[38:39], v[196:197]
	v_pk_mul_f32 v[178:179], v[40:41], v[190:191]
	v_pk_mul_f32 v[180:181], v[34:35], v[192:193]
	v_pk_mul_f32 v[182:183], v[36:37], v[188:189]
	s_nop 1
	v_permlane32_swap_b32_e32 v176, v180
	v_permlane32_swap_b32_e32 v177, v181
	v_permlane32_swap_b32_e32 v178, v182
	v_permlane32_swap_b32_e32 v179, v183
	s_nop 0
	global_store_dwordx4 v[214:215], v[176:179], off offset:512
	global_store_dwordx4 v[214:215], v[180:183], off offset:576
	v_pk_mul_f32 v[152:153], v[28:29], v[202:203]
	v_pk_mul_f32 v[154:155], v[30:31], v[198:199]
	v_pk_mul_f32 v[156:157], v[24:25], v[200:201]
	v_pk_mul_f32 v[158:159], v[26:27], v[194:195]
	s_nop 1
	v_permlane32_swap_b32_e32 v152, v156
	v_permlane32_swap_b32_e32 v153, v157
	v_permlane32_swap_b32_e32 v154, v158
	v_permlane32_swap_b32_e32 v155, v159
	s_nop 0
	global_store_dwordx4 v[216:217], v[152:155], off
	global_store_dwordx4 v[216:217], v[156:159], off offset:64
	v_pk_mul_f32 v[160:161], v[20:21], v[196:197]
	v_pk_mul_f32 v[162:163], v[22:23], v[190:191]
	v_pk_mul_f32 v[164:165], v[16:17], v[192:193]
	v_pk_mul_f32 v[166:167], v[18:19], v[188:189]
	s_nop 1
	v_permlane32_swap_b32_e32 v160, v164
	v_permlane32_swap_b32_e32 v161, v165
	v_permlane32_swap_b32_e32 v162, v166
	v_permlane32_swap_b32_e32 v163, v167
	s_nop 0
	global_store_dwordx4 v[216:217], v[160:163], off offset:512
	global_store_dwordx4 v[216:217], v[164:167], off offset:576
	v_pk_mul_f32 v[168:169], v[12:13], v[202:203]
	v_pk_mul_f32 v[170:171], v[14:15], v[198:199]
	v_pk_mul_f32 v[172:173], v[8:9], v[200:201]
	v_pk_mul_f32 v[174:175], v[10:11], v[194:195]
	s_nop 1
	v_permlane32_swap_b32_e32 v168, v172
	v_permlane32_swap_b32_e32 v169, v173
	v_permlane32_swap_b32_e32 v170, v174
	v_permlane32_swap_b32_e32 v171, v175
	s_nop 0
	global_store_dwordx4 v[218:219], v[168:171], off
	global_store_dwordx4 v[218:219], v[172:175], off offset:64
	v_pk_mul_f32 v[176:177], v[4:5], v[196:197]
	v_pk_mul_f32 v[178:179], v[6:7], v[190:191]
	v_pk_mul_f32 v[180:181], v[0:1], v[192:193]
	v_pk_mul_f32 v[182:183], v[2:3], v[188:189]
	s_nop 1
	v_permlane32_swap_b32_e32 v176, v180
	v_permlane32_swap_b32_e32 v177, v181
	v_permlane32_swap_b32_e32 v178, v182
	v_permlane32_swap_b32_e32 v179, v183
	s_nop 0
	global_store_dwordx4 v[218:219], v[176:179], off offset:512
	global_store_dwordx4 v[218:219], v[180:183], off offset:576
	s_cbranch_execnz .LBB0_1352
	s_branch .LBB0_1351
